# v64: lever 7 instruction selection - packed f32 ops (v_pk_fma/mul/add_f32) in the GEMM epilogues and fixup replaced by pairs of plain f32 ops
# baseline (speedup 1.0000x reference)
; __device__ __forceinline__ u32x2 pk4(f32x4 v) { u32x2 r; r.x = pk2(v.x, v.y); r.y = pk2(v.z, v.w); return r; }
; __device__ __forceinline__ float rcp_nr(float d) { const float r = __builtin_amdgcn_rcpf(d); return fmaf(r, fmaf(-d, r, 1.f), r); }
; __device__ __forceinline__ float sigmoidf_(float x) { return rcp_nr(1.f + __expf(fminf(-x, 80.f))); }
; template <int EPI>
; __device__ __forceinline__ void epilogue(const Params& p, f32x4 (&acc)[2][2][4][2], const int pm, const int pn, const int wr, const int wc, const int fr, const int fq) {
;     ...
;           } else if (col0 >= 1280) {
;             v0.x = sigmoidf_(v0.x); v0.y = sigmoidf_(v0.y); v0.z = sigmoidf_(v0.z); v0.w = sigmoidf_(v0.w);
;             v1.x = sigmoidf_(v1.x); v1.y = sigmoidf_(v1.y); v1.z = sigmoidf_(v1.z); v1.w = sigmoidf_(v1.w);
;             const u32x2 lo = pk4(v0), hi = pk4(v1);
;             *(u32x4*)(P + (size_t)row * PW + col - 256) = u32x4{lo.x, lo.y, hi.x, hi.y};
.LBB0_159:
	s_andn2_b64 vcc, exec, s[4:5]
	s_cbranch_vccnz .LBB0_161
	v_max_f32_e64 v130, -v126, -v126
	v_max_f32_e64 v131, -v127, -v127
	v_min_f32_e32 v130, 0x42a00000, v130
	v_min_f32_e32 v131, 0x42a00000, v131
	v_mul_f32_e32 v130, 0x3fb8aa3b, v130
	v_mul_f32_e32 v131, 0x3fb8aa3b, v131
	v_exp_f32_e32 v130, v130
	v_exp_f32_e32 v131, v131
	v_max_f32_e64 v165, -v122, -v122
	v_min_f32_e32 v165, 0x42a00000, v165
	v_mul_f32_e32 v165, 0x3fb8aa3b, v165
	v_add_f32_e64 v130, v130, 1.0
	v_add_f32_e64 v131, v131, 1.0
	s_nop 0
	v_rcp_f32_e32 v132, v130
	v_rcp_f32_e32 v133, v131
	s_nop 0
	v_fma_f32 v130, -v130, v132, 1.0
	v_fma_f32 v131, -v131, v133, 1.0
	s_nop 0
	v_fma_f32 v130, v132, v130, v132
	v_fma_f32 v131, v133, v131, v133
	v_max_f32_e64 v132, -v128, -v128
	v_max_f32_e64 v133, -v129, -v129
	v_min_f32_e32 v132, 0x42a00000, v132
	v_min_f32_e32 v133, 0x42a00000, v133
	v_mul_f32_e32 v132, 0x3fb8aa3b, v132
	v_mul_f32_e32 v133, 0x3fb8aa3b, v133
	v_exp_f32_e32 v132, v132
	v_exp_f32_e32 v133, v133
	v_cvt_pk_bf16_f32 v130, v130, v131
	v_add_f32_e64 v132, v132, 1.0
	v_add_f32_e64 v133, v133, 1.0
	s_nop 0
	v_rcp_f32_e32 v188, v132
	v_rcp_f32_e32 v189, v133
	s_nop 0
	v_fma_f32 v132, -v132, v188, 1.0
	v_fma_f32 v133, -v133, v189, 1.0
	s_nop 0
	v_fma_f32 v132, v188, v132, v188
	v_fma_f32 v133, v189, v133, v189
	v_exp_f32_e32 v188, v165
	v_max_f32_e64 v165, -v123, -v123
	v_min_f32_e32 v165, 0x42a00000, v165
	v_mul_f32_e32 v165, 0x3fb8aa3b, v165
	v_exp_f32_e32 v189, v165
	v_max_f32_e64 v165, -v124, -v124
	v_min_f32_e32 v165, 0x42a00000, v165
	v_mul_f32_e32 v165, 0x3fb8aa3b, v165
	v_add_f32_e64 v188, v188, 1.0
	v_add_f32_e64 v189, v189, 1.0
	v_cvt_pk_bf16_f32 v131, v132, v133
	v_rcp_f32_e32 v190, v188
	v_rcp_f32_e32 v191, v189
	s_nop 0
	v_fma_f32 v188, -v188, v190, 1.0
	v_fma_f32 v189, -v189, v191, 1.0
	s_nop 0
	v_fma_f32 v188, v190, v188, v190
	v_fma_f32 v189, v191, v189, v191
	v_exp_f32_e32 v190, v165
	v_max_f32_e64 v165, -v125, -v125
	v_min_f32_e32 v165, 0x42a00000, v165
	v_mul_f32_e32 v165, 0x3fb8aa3b, v165
	v_exp_f32_e32 v191, v165
	v_cvt_pk_bf16_f32 v132, v188, v189
	v_mad_i64_i32 v[188:189], s[4:5], v164, s62, v[166:167]
	v_add_f32_e64 v190, v190, 1.0
	v_add_f32_e64 v191, v191, 1.0
	s_nop 0
	v_rcp_f32_e32 v192, v190
	v_rcp_f32_e32 v193, v191
	s_nop 0
	v_fma_f32 v190, -v190, v192, 1.0
	v_fma_f32 v191, -v191, v193, 1.0
	s_nop 0
	v_fma_f32 v190, v192, v190, v192
	v_fma_f32 v191, v193, v191, v193
	s_nop 0
	v_cvt_pk_bf16_f32 v133, v190, v191
	global_store_dwordx4 v[188:189], v[130:133], off offset:-512

; __device__ __forceinline__ u32x2 pk4(f32x4 v) { u32x2 r; r.x = pk2(v.x, v.y); r.y = pk2(v.z, v.w); return r; }
; __device__ __forceinline__ float rcp_nr(float d) { const float r = __builtin_amdgcn_rcpf(d); return fmaf(r, fmaf(-d, r, 1.f), r); }
; __device__ __forceinline__ float sigmoidf_(float x) { return rcp_nr(1.f + __expf(fminf(-x, 80.f))); }
; template <int EPI>
; __device__ __forceinline__ void epilogue(const Params& p, f32x4 (&acc)[2][2][4][2], const int pm, const int pn, const int wr, const int wc, const int fr, const int fq) {
;     ...
;           } else if (col0 >= 1280) {
;             v0.x = sigmoidf_(v0.x); v0.y = sigmoidf_(v0.y); v0.z = sigmoidf_(v0.z); v0.w = sigmoidf_(v0.w);
;             v1.x = sigmoidf_(v1.x); v1.y = sigmoidf_(v1.y); v1.z = sigmoidf_(v1.z); v1.w = sigmoidf_(v1.w);
;             const u32x2 lo = pk4(v0), hi = pk4(v1);
;             *(u32x4*)(P + (size_t)row * PW + col - 256) = u32x4{lo.x, lo.y, hi.x, hi.y};
.LBB0_183:
	s_andn2_b64 vcc, exec, s[28:29]
	s_cbranch_vccnz .LBB0_185
	v_max_f32_e64 v122, -v118, -v118
	v_max_f32_e64 v123, -v119, -v119
	v_min_f32_e32 v122, 0x42a00000, v122
	v_min_f32_e32 v123, 0x42a00000, v123
	v_mul_f32_e32 v122, 0x3fb8aa3b, v122
	v_mul_f32_e32 v123, 0x3fb8aa3b, v123
	v_exp_f32_e32 v122, v122
	v_exp_f32_e32 v123, v123
	v_max_f32_e64 v127, -v114, -v114
	v_min_f32_e32 v127, 0x42a00000, v127
	v_mul_f32_e32 v127, 0x3fb8aa3b, v127
	v_add_f32_e64 v122, v122, 1.0
	v_add_f32_e64 v123, v123, 1.0
	s_nop 0
	v_rcp_f32_e32 v124, v122
	v_rcp_f32_e32 v125, v123
	s_nop 0
	v_fma_f32 v122, -v122, v124, 1.0
	v_fma_f32 v123, -v123, v125, 1.0
	s_nop 0
	v_fma_f32 v122, v124, v122, v124
	v_fma_f32 v123, v125, v123, v125
	v_max_f32_e64 v124, -v120, -v120
	v_max_f32_e64 v125, -v121, -v121
	v_min_f32_e32 v124, 0x42a00000, v124
	v_min_f32_e32 v125, 0x42a00000, v125
	v_mul_f32_e32 v124, 0x3fb8aa3b, v124
	v_mul_f32_e32 v125, 0x3fb8aa3b, v125
	v_exp_f32_e32 v124, v124
	v_exp_f32_e32 v125, v125
	v_cvt_pk_bf16_f32 v122, v122, v123
	v_add_f32_e64 v124, v124, 1.0
	v_add_f32_e64 v125, v125, 1.0
	s_nop 0
	v_rcp_f32_e32 v128, v124
	v_rcp_f32_e32 v129, v125
	s_nop 0
	v_fma_f32 v124, -v124, v128, 1.0
	v_fma_f32 v125, -v125, v129, 1.0
	s_nop 0
	v_fma_f32 v124, v128, v124, v128
	v_fma_f32 v125, v129, v125, v129
	v_exp_f32_e32 v128, v127
	v_max_f32_e64 v127, -v115, -v115
	v_min_f32_e32 v127, 0x42a00000, v127
	v_mul_f32_e32 v127, 0x3fb8aa3b, v127
	v_exp_f32_e32 v129, v127
	v_max_f32_e64 v127, -v116, -v116
	v_min_f32_e32 v127, 0x42a00000, v127
	v_mul_f32_e32 v127, 0x3fb8aa3b, v127
	v_add_f32_e64 v128, v128, 1.0
	v_add_f32_e64 v129, v129, 1.0
	v_cvt_pk_bf16_f32 v123, v124, v125
	v_rcp_f32_e32 v132, v128
	v_rcp_f32_e32 v133, v129
	s_nop 0
	v_fma_f32 v128, -v128, v132, 1.0
	v_fma_f32 v129, -v129, v133, 1.0
	s_nop 0
	v_fma_f32 v128, v132, v128, v132
	v_fma_f32 v129, v133, v129, v133
	v_exp_f32_e32 v132, v127
	v_max_f32_e64 v127, -v117, -v117
	v_min_f32_e32 v127, 0x42a00000, v127
	v_mul_f32_e32 v127, 0x3fb8aa3b, v127
	v_exp_f32_e32 v133, v127
	v_cvt_pk_bf16_f32 v124, v128, v129
	v_mad_i64_i32 v[128:129], s[28:29], v126, s62, v[166:167]
	v_add_f32_e64 v132, v132, 1.0
	v_add_f32_e64 v133, v133, 1.0
	s_nop 0
	v_rcp_f32_e32 v176, v132
	v_rcp_f32_e32 v177, v133
	s_nop 0
	v_fma_f32 v132, -v132, v176, 1.0
	v_fma_f32 v133, -v133, v177, 1.0
	s_nop 0
	v_fma_f32 v132, v176, v132, v176
	v_fma_f32 v133, v177, v133, v177
	s_nop 0
	v_cvt_pk_bf16_f32 v125, v132, v133
	global_store_dwordx4 v[128:129], v[122:125], off offset:-512

; __device__ __forceinline__ u32x2 pk4(f32x4 v) { u32x2 r; r.x = pk2(v.x, v.y); r.y = pk2(v.z, v.w); return r; }
; __device__ __forceinline__ float rcp_nr(float d) { const float r = __builtin_amdgcn_rcpf(d); return fmaf(r, fmaf(-d, r, 1.f), r); }
; __device__ __forceinline__ float sigmoidf_(float x) { return rcp_nr(1.f + __expf(fminf(-x, 80.f))); }
; template <int EPI>
; __device__ __forceinline__ void epilogue(const Params& p, f32x4 (&acc)[2][2][4][2], const int pm, const int pn, const int wr, const int wc, const int fr, const int fq) {
;     ...
;           } else if (col0 >= 1280) {
;             v0.x = sigmoidf_(v0.x); v0.y = sigmoidf_(v0.y); v0.z = sigmoidf_(v0.z); v0.w = sigmoidf_(v0.w);
;             v1.x = sigmoidf_(v1.x); v1.y = sigmoidf_(v1.y); v1.z = sigmoidf_(v1.z); v1.w = sigmoidf_(v1.w);
;             const u32x2 lo = pk4(v0), hi = pk4(v1);
;             *(u32x4*)(P + (size_t)row * PW + col - 256) = u32x4{lo.x, lo.y, hi.x, hi.y};
.LBB0_205:
	s_andn2_b64 vcc, exec, s[28:29]
	s_cbranch_vccnz .LBB0_207
	v_max_f32_e64 v114, -v110, -v110
	v_max_f32_e64 v115, -v111, -v111
	v_min_f32_e32 v114, 0x42a00000, v114
	v_min_f32_e32 v115, 0x42a00000, v115
	v_mul_f32_e32 v114, 0x3fb8aa3b, v114
	v_mul_f32_e32 v115, 0x3fb8aa3b, v115
	v_exp_f32_e32 v114, v114
	v_exp_f32_e32 v115, v115
	v_max_f32_e64 v119, -v106, -v106
	v_min_f32_e32 v119, 0x42a00000, v119
	v_mul_f32_e32 v119, 0x3fb8aa3b, v119
	v_add_f32_e64 v114, v114, 1.0
	v_add_f32_e64 v115, v115, 1.0
	s_nop 0
	v_rcp_f32_e32 v116, v114
	v_rcp_f32_e32 v117, v115
	s_nop 0
	v_fma_f32 v114, -v114, v116, 1.0
	v_fma_f32 v115, -v115, v117, 1.0
	s_nop 0
	v_fma_f32 v114, v116, v114, v116
	v_fma_f32 v115, v117, v115, v117
	v_max_f32_e64 v116, -v112, -v112
	v_max_f32_e64 v117, -v113, -v113
	v_min_f32_e32 v116, 0x42a00000, v116
	v_min_f32_e32 v117, 0x42a00000, v117
	v_mul_f32_e32 v116, 0x3fb8aa3b, v116
	v_mul_f32_e32 v117, 0x3fb8aa3b, v117
	v_exp_f32_e32 v116, v116
	v_exp_f32_e32 v117, v117
	v_cvt_pk_bf16_f32 v114, v114, v115
	v_add_f32_e64 v116, v116, 1.0
	v_add_f32_e64 v117, v117, 1.0
	s_nop 0
	v_rcp_f32_e32 v120, v116
	v_rcp_f32_e32 v121, v117
	s_nop 0
	v_fma_f32 v116, -v116, v120, 1.0
	v_fma_f32 v117, -v117, v121, 1.0
	s_nop 0
	v_fma_f32 v116, v120, v116, v120
	v_fma_f32 v117, v121, v117, v121
	v_exp_f32_e32 v120, v119
	v_max_f32_e64 v119, -v107, -v107
	v_min_f32_e32 v119, 0x42a00000, v119
	v_mul_f32_e32 v119, 0x3fb8aa3b, v119
	v_exp_f32_e32 v121, v119
	v_max_f32_e64 v119, -v108, -v108
	v_min_f32_e32 v119, 0x42a00000, v119
	v_mul_f32_e32 v119, 0x3fb8aa3b, v119
	v_add_f32_e64 v120, v120, 1.0
	v_add_f32_e64 v121, v121, 1.0
	v_cvt_pk_bf16_f32 v115, v116, v117
	v_rcp_f32_e32 v122, v120
	v_rcp_f32_e32 v123, v121
	s_nop 0
	v_fma_f32 v120, -v120, v122, 1.0
	v_fma_f32 v121, -v121, v123, 1.0
	s_nop 0
	v_fma_f32 v120, v122, v120, v122
	v_fma_f32 v121, v123, v121, v123
	v_exp_f32_e32 v122, v119
	v_max_f32_e64 v119, -v109, -v109
	v_min_f32_e32 v119, 0x42a00000, v119
	v_mul_f32_e32 v119, 0x3fb8aa3b, v119
	v_exp_f32_e32 v123, v119
	v_cvt_pk_bf16_f32 v116, v120, v121
	v_mad_i64_i32 v[120:121], s[28:29], v118, s62, v[166:167]
	v_add_f32_e64 v122, v122, 1.0
	v_add_f32_e64 v123, v123, 1.0
	s_nop 0
	v_rcp_f32_e32 v124, v122
	v_rcp_f32_e32 v125, v123
	s_nop 0
	v_fma_f32 v122, -v122, v124, 1.0
	v_fma_f32 v123, -v123, v125, 1.0
	s_nop 0
	v_fma_f32 v122, v124, v122, v124
	v_fma_f32 v123, v125, v123, v125
	s_nop 0
	v_cvt_pk_bf16_f32 v117, v122, v123
	global_store_dwordx4 v[120:121], v[114:117], off offset:-512

; __device__ __forceinline__ u32x2 pk4(f32x4 v) { u32x2 r; r.x = pk2(v.x, v.y); r.y = pk2(v.z, v.w); return r; }
; __device__ __forceinline__ float rcp_nr(float d) { const float r = __builtin_amdgcn_rcpf(d); return fmaf(r, fmaf(-d, r, 1.f), r); }
; __device__ __forceinline__ float sigmoidf_(float x) { return rcp_nr(1.f + __expf(fminf(-x, 80.f))); }
; template <int EPI>
; __device__ __forceinline__ void epilogue(const Params& p, f32x4 (&acc)[2][2][4][2], const int pm, const int pn, const int wr, const int wc, const int fr, const int fq) {
;     ...
;           } else if (col0 >= 1280) {
;             v0.x = sigmoidf_(v0.x); v0.y = sigmoidf_(v0.y); v0.z = sigmoidf_(v0.z); v0.w = sigmoidf_(v0.w);
;             v1.x = sigmoidf_(v1.x); v1.y = sigmoidf_(v1.y); v1.z = sigmoidf_(v1.z); v1.w = sigmoidf_(v1.w);
;             const u32x2 lo = pk4(v0), hi = pk4(v1);
;             *(u32x4*)(P + (size_t)row * PW + col - 256) = u32x4{lo.x, lo.y, hi.x, hi.y};
.LBB0_227:
	s_andn2_b64 vcc, exec, s[28:29]
	s_cbranch_vccnz .LBB0_229
	v_max_f32_e64 v106, -v102, -v102
	v_max_f32_e64 v107, -v103, -v103
	v_min_f32_e32 v106, 0x42a00000, v106
	v_min_f32_e32 v107, 0x42a00000, v107
	v_mul_f32_e32 v106, 0x3fb8aa3b, v106
	v_mul_f32_e32 v107, 0x3fb8aa3b, v107
	v_exp_f32_e32 v106, v106
	v_exp_f32_e32 v107, v107
	v_max_f32_e64 v111, -v98, -v98
	v_min_f32_e32 v111, 0x42a00000, v111
	v_mul_f32_e32 v111, 0x3fb8aa3b, v111
	v_add_f32_e64 v106, v106, 1.0
	v_add_f32_e64 v107, v107, 1.0
	s_nop 0
	v_rcp_f32_e32 v108, v106
	v_rcp_f32_e32 v109, v107
	s_nop 0
	v_fma_f32 v106, -v106, v108, 1.0
	v_fma_f32 v107, -v107, v109, 1.0
	s_nop 0
	v_fma_f32 v106, v108, v106, v108
	v_fma_f32 v107, v109, v107, v109
	v_max_f32_e64 v108, -v104, -v104
	v_max_f32_e64 v109, -v105, -v105
	v_min_f32_e32 v108, 0x42a00000, v108
	v_min_f32_e32 v109, 0x42a00000, v109
	v_mul_f32_e32 v108, 0x3fb8aa3b, v108
	v_mul_f32_e32 v109, 0x3fb8aa3b, v109
	v_exp_f32_e32 v108, v108
	v_exp_f32_e32 v109, v109
	v_cvt_pk_bf16_f32 v106, v106, v107
	v_add_f32_e64 v108, v108, 1.0
	v_add_f32_e64 v109, v109, 1.0
	s_nop 0
	v_rcp_f32_e32 v112, v108
	v_rcp_f32_e32 v113, v109
	s_nop 0
	v_fma_f32 v108, -v108, v112, 1.0
	v_fma_f32 v109, -v109, v113, 1.0
	s_nop 0
	v_fma_f32 v108, v112, v108, v112
	v_fma_f32 v109, v113, v109, v113
	v_exp_f32_e32 v112, v111
	v_max_f32_e64 v111, -v99, -v99
	v_min_f32_e32 v111, 0x42a00000, v111
	v_mul_f32_e32 v111, 0x3fb8aa3b, v111
	v_exp_f32_e32 v113, v111
	v_max_f32_e64 v111, -v100, -v100
	v_min_f32_e32 v111, 0x42a00000, v111
	v_mul_f32_e32 v111, 0x3fb8aa3b, v111
	v_add_f32_e64 v112, v112, 1.0
	v_add_f32_e64 v113, v113, 1.0
	v_cvt_pk_bf16_f32 v107, v108, v109
	v_rcp_f32_e32 v114, v112
	v_rcp_f32_e32 v115, v113
	s_nop 0
	v_fma_f32 v112, -v112, v114, 1.0
	v_fma_f32 v113, -v113, v115, 1.0
	s_nop 0
	v_fma_f32 v112, v114, v112, v114
	v_fma_f32 v113, v115, v113, v115
	v_exp_f32_e32 v114, v111
	v_max_f32_e64 v111, -v101, -v101
	v_min_f32_e32 v111, 0x42a00000, v111
	v_mul_f32_e32 v111, 0x3fb8aa3b, v111
	v_exp_f32_e32 v115, v111
	v_cvt_pk_bf16_f32 v108, v112, v113
	v_mad_i64_i32 v[112:113], s[28:29], v110, s62, v[166:167]
	v_add_f32_e64 v114, v114, 1.0
	v_add_f32_e64 v115, v115, 1.0
	s_nop 0
	v_rcp_f32_e32 v116, v114
	v_rcp_f32_e32 v117, v115
	s_nop 0
	v_fma_f32 v114, -v114, v116, 1.0
	v_fma_f32 v115, -v115, v117, 1.0
	s_nop 0
	v_fma_f32 v114, v116, v114, v116
	v_fma_f32 v115, v117, v115, v117
	s_nop 0
	v_cvt_pk_bf16_f32 v109, v114, v115
	global_store_dwordx4 v[112:113], v[106:109], off offset:-512

; __device__ __forceinline__ u32x2 pk4(f32x4 v) { u32x2 r; r.x = pk2(v.x, v.y); r.y = pk2(v.z, v.w); return r; }
; __device__ __forceinline__ float rcp_nr(float d) { const float r = __builtin_amdgcn_rcpf(d); return fmaf(r, fmaf(-d, r, 1.f), r); }
; __device__ __forceinline__ float sigmoidf_(float x) { return rcp_nr(1.f + __expf(fminf(-x, 80.f))); }
; template <int EPI>
; __device__ __forceinline__ void epilogue(const Params& p, f32x4 (&acc)[2][2][4][2], const int pm, const int pn, const int wr, const int wc, const int fr, const int fq) {
;     ...
;           } else if (col0 >= 1280) {
;             v0.x = sigmoidf_(v0.x); v0.y = sigmoidf_(v0.y); v0.z = sigmoidf_(v0.z); v0.w = sigmoidf_(v0.w);
;             v1.x = sigmoidf_(v1.x); v1.y = sigmoidf_(v1.y); v1.z = sigmoidf_(v1.z); v1.w = sigmoidf_(v1.w);
;             const u32x2 lo = pk4(v0), hi = pk4(v1);
;             *(u32x4*)(P + (size_t)row * PW + col - 256) = u32x4{lo.x, lo.y, hi.x, hi.y};
.LBB0_255:
	s_andn2_b64 vcc, exec, s[36:37]
	s_cbranch_vccnz .LBB0_257
	v_max_f32_e64 v98, -v94, -v94
	v_max_f32_e64 v99, -v95, -v95
	v_min_f32_e32 v98, 0x42a00000, v98
	v_min_f32_e32 v99, 0x42a00000, v99
	v_mul_f32_e32 v98, 0x3fb8aa3b, v98
	v_mul_f32_e32 v99, 0x3fb8aa3b, v99
	v_exp_f32_e32 v98, v98
	v_exp_f32_e32 v99, v99
	v_max_f32_e64 v103, -v90, -v90
	v_min_f32_e32 v103, 0x42a00000, v103
	v_mul_f32_e32 v103, 0x3fb8aa3b, v103
	v_add_f32_e64 v98, v98, 1.0
	v_add_f32_e64 v99, v99, 1.0
	s_nop 0
	v_rcp_f32_e32 v100, v98
	v_rcp_f32_e32 v101, v99
	s_nop 0
	v_fma_f32 v98, -v98, v100, 1.0
	v_fma_f32 v99, -v99, v101, 1.0
	s_nop 0
	v_fma_f32 v98, v100, v98, v100
	v_fma_f32 v99, v101, v99, v101
	v_max_f32_e64 v100, -v96, -v96
	v_max_f32_e64 v101, -v97, -v97
	v_min_f32_e32 v100, 0x42a00000, v100
	v_min_f32_e32 v101, 0x42a00000, v101
	v_mul_f32_e32 v100, 0x3fb8aa3b, v100
	v_mul_f32_e32 v101, 0x3fb8aa3b, v101
	v_exp_f32_e32 v100, v100
	v_exp_f32_e32 v101, v101
	v_cvt_pk_bf16_f32 v98, v98, v99
	v_add_f32_e64 v100, v100, 1.0
	v_add_f32_e64 v101, v101, 1.0
	s_nop 0
	v_rcp_f32_e32 v106, v100
	v_rcp_f32_e32 v107, v101
	s_nop 0
	v_fma_f32 v100, -v100, v106, 1.0
	v_fma_f32 v101, -v101, v107, 1.0
	s_nop 0
	v_fma_f32 v100, v106, v100, v106
	v_fma_f32 v101, v107, v101, v107
	v_exp_f32_e32 v106, v103
	v_max_f32_e64 v103, -v91, -v91
	v_min_f32_e32 v103, 0x42a00000, v103
	v_mul_f32_e32 v103, 0x3fb8aa3b, v103
	v_exp_f32_e32 v107, v103
	v_max_f32_e64 v103, -v92, -v92
	v_min_f32_e32 v103, 0x42a00000, v103
	v_mul_f32_e32 v103, 0x3fb8aa3b, v103
	v_add_f32_e64 v106, v106, 1.0
	v_add_f32_e64 v107, v107, 1.0
	v_cvt_pk_bf16_f32 v99, v100, v101
	v_rcp_f32_e32 v108, v106
	v_rcp_f32_e32 v109, v107
	s_nop 0
	v_fma_f32 v106, -v106, v108, 1.0
	v_fma_f32 v107, -v107, v109, 1.0
	s_nop 0
	v_fma_f32 v106, v108, v106, v108
	v_fma_f32 v107, v109, v107, v109
	v_exp_f32_e32 v108, v103
	v_max_f32_e64 v103, -v93, -v93
	v_min_f32_e32 v103, 0x42a00000, v103
	v_mul_f32_e32 v103, 0x3fb8aa3b, v103
	v_exp_f32_e32 v109, v103
	v_cvt_pk_bf16_f32 v100, v106, v107
	v_mad_i64_i32 v[106:107], s[36:37], v102, s62, v[166:167]
	v_add_f32_e64 v108, v108, 1.0
	v_add_f32_e64 v109, v109, 1.0
	s_nop 0
	v_rcp_f32_e32 v112, v108
	v_rcp_f32_e32 v113, v109
	s_nop 0
	v_fma_f32 v108, -v108, v112, 1.0
	v_fma_f32 v109, -v109, v113, 1.0
	s_nop 0
	v_fma_f32 v108, v112, v108, v112
	v_fma_f32 v109, v113, v109, v113
	s_nop 0
	v_cvt_pk_bf16_f32 v101, v108, v109
	global_store_dwordx4 v[106:107], v[98:101], off offset:-512

; __device__ __forceinline__ u32x2 pk4(f32x4 v) { u32x2 r; r.x = pk2(v.x, v.y); r.y = pk2(v.z, v.w); return r; }
; __device__ __forceinline__ float rcp_nr(float d) { const float r = __builtin_amdgcn_rcpf(d); return fmaf(r, fmaf(-d, r, 1.f), r); }
; __device__ __forceinline__ float sigmoidf_(float x) { return rcp_nr(1.f + __expf(fminf(-x, 80.f))); }
; template <int EPI>
; __device__ __forceinline__ void epilogue(const Params& p, f32x4 (&acc)[2][2][4][2], const int pm, const int pn, const int wr, const int wc, const int fr, const int fq) {
;     ...
;           } else if (col0 >= 1280) {
;             v0.x = sigmoidf_(v0.x); v0.y = sigmoidf_(v0.y); v0.z = sigmoidf_(v0.z); v0.w = sigmoidf_(v0.w);
;             v1.x = sigmoidf_(v1.x); v1.y = sigmoidf_(v1.y); v1.z = sigmoidf_(v1.z); v1.w = sigmoidf_(v1.w);
;             const u32x2 lo = pk4(v0), hi = pk4(v1);
;             *(u32x4*)(P + (size_t)row * PW + col - 256) = u32x4{lo.x, lo.y, hi.x, hi.y};
.LBB0_277:
	s_andn2_b64 vcc, exec, s[36:37]
	s_cbranch_vccnz .LBB0_279
	v_max_f32_e64 v90, -v86, -v86
	v_max_f32_e64 v91, -v87, -v87
	v_min_f32_e32 v90, 0x42a00000, v90
	v_min_f32_e32 v91, 0x42a00000, v91
	v_mul_f32_e32 v90, 0x3fb8aa3b, v90
	v_mul_f32_e32 v91, 0x3fb8aa3b, v91
	v_exp_f32_e32 v90, v90
	v_exp_f32_e32 v91, v91
	v_max_f32_e64 v95, -v82, -v82
	v_min_f32_e32 v95, 0x42a00000, v95
	v_mul_f32_e32 v95, 0x3fb8aa3b, v95
	v_add_f32_e64 v90, v90, 1.0
	v_add_f32_e64 v91, v91, 1.0
	s_nop 0
	v_rcp_f32_e32 v92, v90
	v_rcp_f32_e32 v93, v91
	s_nop 0
	v_fma_f32 v90, -v90, v92, 1.0
	v_fma_f32 v91, -v91, v93, 1.0
	s_nop 0
	v_fma_f32 v90, v92, v90, v92
	v_fma_f32 v91, v93, v91, v93
	v_max_f32_e64 v92, -v88, -v88
	v_max_f32_e64 v93, -v89, -v89
	v_min_f32_e32 v92, 0x42a00000, v92
	v_min_f32_e32 v93, 0x42a00000, v93
	v_mul_f32_e32 v92, 0x3fb8aa3b, v92
	v_mul_f32_e32 v93, 0x3fb8aa3b, v93
	v_exp_f32_e32 v92, v92
	v_exp_f32_e32 v93, v93
	v_cvt_pk_bf16_f32 v90, v90, v91
	v_add_f32_e64 v92, v92, 1.0
	v_add_f32_e64 v93, v93, 1.0
	s_nop 0
	v_rcp_f32_e32 v96, v92
	v_rcp_f32_e32 v97, v93
	s_nop 0
	v_fma_f32 v92, -v92, v96, 1.0
	v_fma_f32 v93, -v93, v97, 1.0
	s_nop 0
	v_fma_f32 v92, v96, v92, v96
	v_fma_f32 v93, v97, v93, v97
	v_exp_f32_e32 v96, v95
	v_max_f32_e64 v95, -v83, -v83
	v_min_f32_e32 v95, 0x42a00000, v95
	v_mul_f32_e32 v95, 0x3fb8aa3b, v95
	v_exp_f32_e32 v97, v95
	v_max_f32_e64 v95, -v84, -v84
	v_min_f32_e32 v95, 0x42a00000, v95
	v_mul_f32_e32 v95, 0x3fb8aa3b, v95
	v_add_f32_e64 v96, v96, 1.0
	v_add_f32_e64 v97, v97, 1.0
	v_cvt_pk_bf16_f32 v91, v92, v93
	v_rcp_f32_e32 v98, v96
	v_rcp_f32_e32 v99, v97
	s_nop 0
	v_fma_f32 v96, -v96, v98, 1.0
	v_fma_f32 v97, -v97, v99, 1.0
	s_nop 0
	v_fma_f32 v96, v98, v96, v98
	v_fma_f32 v97, v99, v97, v99
	v_exp_f32_e32 v98, v95
	v_max_f32_e64 v95, -v85, -v85
	v_min_f32_e32 v95, 0x42a00000, v95
	v_mul_f32_e32 v95, 0x3fb8aa3b, v95
	v_exp_f32_e32 v99, v95
	v_cvt_pk_bf16_f32 v92, v96, v97
	v_mad_i64_i32 v[96:97], s[36:37], v94, s62, v[166:167]
	v_add_f32_e64 v98, v98, 1.0
	v_add_f32_e64 v99, v99, 1.0
	s_nop 0
	v_rcp_f32_e32 v100, v98
	v_rcp_f32_e32 v101, v99
	s_nop 0
	v_fma_f32 v98, -v98, v100, 1.0
	v_fma_f32 v99, -v99, v101, 1.0
	s_nop 0
	v_fma_f32 v98, v100, v98, v100
	v_fma_f32 v99, v101, v99, v101
	s_nop 0
	v_cvt_pk_bf16_f32 v93, v98, v99
	global_store_dwordx4 v[96:97], v[90:93], off offset:-512

; __device__ __forceinline__ u32x2 pk4(f32x4 v) { u32x2 r; r.x = pk2(v.x, v.y); r.y = pk2(v.z, v.w); return r; }
; __device__ __forceinline__ float rcp_nr(float d) { const float r = __builtin_amdgcn_rcpf(d); return fmaf(r, fmaf(-d, r, 1.f), r); }
; __device__ __forceinline__ float sigmoidf_(float x) { return rcp_nr(1.f + __expf(fminf(-x, 80.f))); }
; template <int EPI>
; __device__ __forceinline__ void epilogue(const Params& p, f32x4 (&acc)[2][2][4][2], const int pm, const int pn, const int wr, const int wc, const int fr, const int fq) {
;     ...
;           } else if (col0 >= 1280) {
;             v0.x = sigmoidf_(v0.x); v0.y = sigmoidf_(v0.y); v0.z = sigmoidf_(v0.z); v0.w = sigmoidf_(v0.w);
;             v1.x = sigmoidf_(v1.x); v1.y = sigmoidf_(v1.y); v1.z = sigmoidf_(v1.z); v1.w = sigmoidf_(v1.w);
;             const u32x2 lo = pk4(v0), hi = pk4(v1);
;             *(u32x4*)(P + (size_t)row * PW + col - 256) = u32x4{lo.x, lo.y, hi.x, hi.y};
.LBB0_299:
	s_andn2_b64 vcc, exec, s[36:37]
	s_cbranch_vccnz .LBB0_301
	v_max_f32_e64 v82, -v78, -v78
	v_max_f32_e64 v83, -v79, -v79
	v_min_f32_e32 v82, 0x42a00000, v82
	v_min_f32_e32 v83, 0x42a00000, v83
	v_mul_f32_e32 v82, 0x3fb8aa3b, v82
	v_mul_f32_e32 v83, 0x3fb8aa3b, v83
	v_exp_f32_e32 v82, v82
	v_exp_f32_e32 v83, v83
	v_max_f32_e64 v87, -v74, -v74
	v_min_f32_e32 v87, 0x42a00000, v87
	v_mul_f32_e32 v87, 0x3fb8aa3b, v87
	v_add_f32_e64 v82, v82, 1.0
	v_add_f32_e64 v83, v83, 1.0
	s_nop 0
	v_rcp_f32_e32 v84, v82
	v_rcp_f32_e32 v85, v83
	s_nop 0
	v_fma_f32 v82, -v82, v84, 1.0
	v_fma_f32 v83, -v83, v85, 1.0
	s_nop 0
	v_fma_f32 v82, v84, v82, v84
	v_fma_f32 v83, v85, v83, v85
	v_max_f32_e64 v84, -v80, -v80
	v_max_f32_e64 v85, -v81, -v81
	v_min_f32_e32 v84, 0x42a00000, v84
	v_min_f32_e32 v85, 0x42a00000, v85
	v_mul_f32_e32 v84, 0x3fb8aa3b, v84
	v_mul_f32_e32 v85, 0x3fb8aa3b, v85
	v_exp_f32_e32 v84, v84
	v_exp_f32_e32 v85, v85
	v_cvt_pk_bf16_f32 v82, v82, v83
	v_add_f32_e64 v84, v84, 1.0
	v_add_f32_e64 v85, v85, 1.0
	s_nop 0
	v_rcp_f32_e32 v88, v84
	v_rcp_f32_e32 v89, v85
	s_nop 0
	v_fma_f32 v84, -v84, v88, 1.0
	v_fma_f32 v85, -v85, v89, 1.0
	s_nop 0
	v_fma_f32 v84, v88, v84, v88
	v_fma_f32 v85, v89, v85, v89
	v_exp_f32_e32 v88, v87
	v_max_f32_e64 v87, -v75, -v75
	v_min_f32_e32 v87, 0x42a00000, v87
	v_mul_f32_e32 v87, 0x3fb8aa3b, v87
	v_exp_f32_e32 v89, v87
	v_max_f32_e64 v87, -v76, -v76
	v_min_f32_e32 v87, 0x42a00000, v87
	v_mul_f32_e32 v87, 0x3fb8aa3b, v87
	v_add_f32_e64 v88, v88, 1.0
	v_add_f32_e64 v89, v89, 1.0
	v_cvt_pk_bf16_f32 v83, v84, v85
	v_rcp_f32_e32 v90, v88
	v_rcp_f32_e32 v91, v89
	s_nop 0
	v_fma_f32 v88, -v88, v90, 1.0
	v_fma_f32 v89, -v89, v91, 1.0
	s_nop 0
	v_fma_f32 v88, v90, v88, v90
	v_fma_f32 v89, v91, v89, v91
	v_exp_f32_e32 v90, v87
	v_max_f32_e64 v87, -v77, -v77
	v_min_f32_e32 v87, 0x42a00000, v87
	v_mul_f32_e32 v87, 0x3fb8aa3b, v87
	v_exp_f32_e32 v91, v87
	v_cvt_pk_bf16_f32 v84, v88, v89
	v_mad_i64_i32 v[88:89], s[36:37], v86, s62, v[166:167]
	v_add_f32_e64 v90, v90, 1.0
	v_add_f32_e64 v91, v91, 1.0
	s_nop 0
	v_rcp_f32_e32 v92, v90
	v_rcp_f32_e32 v93, v91
	s_nop 0
	v_fma_f32 v90, -v90, v92, 1.0
	v_fma_f32 v91, -v91, v93, 1.0
	s_nop 0
	v_fma_f32 v90, v92, v90, v92
	v_fma_f32 v91, v93, v91, v93
	s_nop 0
	v_cvt_pk_bf16_f32 v85, v90, v91
	global_store_dwordx4 v[88:89], v[82:85], off offset:-512

; __device__ __forceinline__ u32x2 pk4(f32x4 v) { u32x2 r; r.x = pk2(v.x, v.y); r.y = pk2(v.z, v.w); return r; }
; __device__ __forceinline__ float rcp_nr(float d) { const float r = __builtin_amdgcn_rcpf(d); return fmaf(r, fmaf(-d, r, 1.f), r); }
; __device__ __forceinline__ float sigmoidf_(float x) { return rcp_nr(1.f + __expf(fminf(-x, 80.f))); }
; template <int EPI>
; __device__ __forceinline__ void epilogue(const Params& p, f32x4 (&acc)[2][2][4][2], const int pm, const int pn, const int wr, const int wc, const int fr, const int fq) {
;     ...
;           } else if (col0 >= 1280) {
;             v0.x = sigmoidf_(v0.x); v0.y = sigmoidf_(v0.y); v0.z = sigmoidf_(v0.z); v0.w = sigmoidf_(v0.w);
;             v1.x = sigmoidf_(v1.x); v1.y = sigmoidf_(v1.y); v1.z = sigmoidf_(v1.z); v1.w = sigmoidf_(v1.w);
;             const u32x2 lo = pk4(v0), hi = pk4(v1);
;             *(u32x4*)(P + (size_t)row * PW + col - 256) = u32x4{lo.x, lo.y, hi.x, hi.y};
.LBB0_321:
	s_andn2_b64 vcc, exec, s[6:7]
	s_cbranch_vccnz .LBB0_323
	v_max_f32_e64 v74, -v70, -v70
	v_max_f32_e64 v75, -v71, -v71
	v_min_f32_e32 v74, 0x42a00000, v74
	v_min_f32_e32 v75, 0x42a00000, v75
	v_mul_f32_e32 v74, 0x3fb8aa3b, v74
	v_mul_f32_e32 v75, 0x3fb8aa3b, v75
	v_exp_f32_e32 v74, v74
	v_exp_f32_e32 v75, v75
	v_max_f32_e64 v79, -v66, -v66
	v_min_f32_e32 v79, 0x42a00000, v79
	v_mul_f32_e32 v79, 0x3fb8aa3b, v79
	v_add_f32_e64 v74, v74, 1.0
	v_add_f32_e64 v75, v75, 1.0
	s_nop 0
	v_rcp_f32_e32 v76, v74
	v_rcp_f32_e32 v77, v75
	s_nop 0
	v_fma_f32 v74, -v74, v76, 1.0
	v_fma_f32 v75, -v75, v77, 1.0
	s_nop 0
	v_fma_f32 v74, v76, v74, v76
	v_fma_f32 v75, v77, v75, v77
	v_max_f32_e64 v76, -v72, -v72
	v_max_f32_e64 v77, -v73, -v73
	v_min_f32_e32 v76, 0x42a00000, v76
	v_min_f32_e32 v77, 0x42a00000, v77
	v_mul_f32_e32 v76, 0x3fb8aa3b, v76
	v_mul_f32_e32 v77, 0x3fb8aa3b, v77
	v_exp_f32_e32 v76, v76
	v_exp_f32_e32 v77, v77
	v_cvt_pk_bf16_f32 v74, v74, v75
	v_add_f32_e64 v76, v76, 1.0
	v_add_f32_e64 v77, v77, 1.0
	s_nop 0
	v_rcp_f32_e32 v80, v76
	v_rcp_f32_e32 v81, v77
	s_nop 0
	v_fma_f32 v76, -v76, v80, 1.0
	v_fma_f32 v77, -v77, v81, 1.0
	s_nop 0
	v_fma_f32 v76, v80, v76, v80
	v_fma_f32 v77, v81, v77, v81
	v_exp_f32_e32 v80, v79
	v_max_f32_e64 v79, -v67, -v67
	v_min_f32_e32 v79, 0x42a00000, v79
	v_mul_f32_e32 v79, 0x3fb8aa3b, v79
	v_exp_f32_e32 v81, v79
	v_max_f32_e64 v79, -v68, -v68
	v_min_f32_e32 v79, 0x42a00000, v79
	v_mul_f32_e32 v79, 0x3fb8aa3b, v79
	v_add_f32_e64 v80, v80, 1.0
	v_add_f32_e64 v81, v81, 1.0
	v_cvt_pk_bf16_f32 v75, v76, v77
	v_rcp_f32_e32 v82, v80
	v_rcp_f32_e32 v83, v81
	s_nop 0
	v_fma_f32 v80, -v80, v82, 1.0
	v_fma_f32 v81, -v81, v83, 1.0
	s_nop 0
	v_fma_f32 v80, v82, v80, v82
	v_fma_f32 v81, v83, v81, v83
	v_exp_f32_e32 v82, v79
	v_max_f32_e64 v79, -v69, -v69
	v_min_f32_e32 v79, 0x42a00000, v79
	v_mul_f32_e32 v79, 0x3fb8aa3b, v79
	v_exp_f32_e32 v83, v79
	v_cvt_pk_bf16_f32 v76, v80, v81
	v_mad_i64_i32 v[80:81], s[6:7], v78, s62, v[166:167]
	v_add_f32_e64 v82, v82, 1.0
	v_add_f32_e64 v83, v83, 1.0
	s_nop 0
	v_rcp_f32_e32 v84, v82
	v_rcp_f32_e32 v85, v83
	s_nop 0
	v_fma_f32 v82, -v82, v84, 1.0
	v_fma_f32 v83, -v83, v85, 1.0
	s_nop 0
	v_fma_f32 v82, v84, v82, v84
	v_fma_f32 v83, v85, v83, v85
	s_nop 0
	v_cvt_pk_bf16_f32 v77, v82, v83
	global_store_dwordx4 v[80:81], v[74:77], off offset:-512

; __device__ __forceinline__ u32x2 pk4(f32x4 v) { u32x2 r; r.x = pk2(v.x, v.y); r.y = pk2(v.z, v.w); return r; }
; __device__ __forceinline__ float rcp_nr(float d) { const float r = __builtin_amdgcn_rcpf(d); return fmaf(r, fmaf(-d, r, 1.f), r); }
; __device__ __forceinline__ float sigmoidf_(float x) { return rcp_nr(1.f + __expf(fminf(-x, 80.f))); }
; template <int EPI>
; __device__ __forceinline__ void epilogue(const Params& p, f32x4 (&acc)[2][2][4][2], const int pm, const int pn, const int wr, const int wc, const int fr, const int fq) {
;     ...
;           } else if (col0 >= 1280) {
;             v0.x = sigmoidf_(v0.x); v0.y = sigmoidf_(v0.y); v0.z = sigmoidf_(v0.z); v0.w = sigmoidf_(v0.w);
;             v1.x = sigmoidf_(v1.x); v1.y = sigmoidf_(v1.y); v1.z = sigmoidf_(v1.z); v1.w = sigmoidf_(v1.w);
;             const u32x2 lo = pk4(v0), hi = pk4(v1);
;             *(u32x4*)(P + (size_t)row * PW + col - 256) = u32x4{lo.x, lo.y, hi.x, hi.y};
.LBB0_341:
	s_andn2_b64 vcc, exec, s[6:7]
	s_cbranch_vccnz .LBB0_343
	v_max_f32_e64 v70, -v62, -v62
	v_max_f32_e64 v71, -v63, -v63
	v_min_f32_e32 v70, 0x42a00000, v70
	v_min_f32_e32 v71, 0x42a00000, v71
	v_mul_f32_e32 v70, 0x3fb8aa3b, v70
	v_mul_f32_e32 v71, 0x3fb8aa3b, v71
	v_exp_f32_e32 v70, v70
	v_exp_f32_e32 v71, v71
	v_max_f32_e64 v75, -v64, -v64
	v_min_f32_e32 v75, 0x42a00000, v75
	v_mul_f32_e32 v75, 0x3fb8aa3b, v75
	v_add_f32_e64 v70, v70, 1.0
	v_add_f32_e64 v71, v71, 1.0
	s_nop 0
	v_rcp_f32_e32 v76, v70
	v_rcp_f32_e32 v77, v71
	s_nop 0
	v_fma_f32 v70, -v70, v76, 1.0
	v_fma_f32 v71, -v71, v77, 1.0
	s_nop 0
	v_fma_f32 v70, v76, v70, v76
	v_fma_f32 v71, v77, v71, v77
	v_exp_f32_e32 v76, v75
	v_max_f32_e64 v75, -v65, -v65
	v_min_f32_e32 v75, 0x42a00000, v75
	v_mul_f32_e32 v75, 0x3fb8aa3b, v75
	v_exp_f32_e32 v77, v75
	v_max_f32_e64 v75, -v58, -v58
	v_min_f32_e32 v75, 0x42a00000, v75
	v_mul_f32_e32 v75, 0x3fb8aa3b, v75
	v_add_f32_e64 v76, v76, 1.0
	v_add_f32_e64 v77, v77, 1.0
	s_nop 0
	v_rcp_f32_e32 v80, v76
	v_rcp_f32_e32 v81, v77
	s_nop 0
	v_fma_f32 v76, -v76, v80, 1.0
	v_fma_f32 v77, -v77, v81, 1.0
	s_nop 0
	v_fma_f32 v76, v80, v76, v80
	v_fma_f32 v77, v81, v77, v81
	v_exp_f32_e32 v80, v75
	v_max_f32_e64 v75, -v59, -v59
	v_min_f32_e32 v75, 0x42a00000, v75
	v_mul_f32_e32 v75, 0x3fb8aa3b, v75
	v_exp_f32_e32 v81, v75
	v_max_f32_e64 v75, -v60, -v60
	v_min_f32_e32 v75, 0x42a00000, v75
	v_mul_f32_e32 v75, 0x3fb8aa3b, v75
	v_add_f32_e64 v80, v80, 1.0
	v_add_f32_e64 v81, v81, 1.0
	s_nop 0
	v_rcp_f32_e32 v82, v80
	v_rcp_f32_e32 v83, v81
	s_nop 0
	v_fma_f32 v80, -v80, v82, 1.0
	v_fma_f32 v81, -v81, v83, 1.0
	s_nop 0
	v_fma_f32 v82, v82, v80, v82
	v_fma_f32 v83, v83, v81, v83
	v_exp_f32_e32 v80, v75
	v_max_f32_e64 v75, -v61, -v61
	v_min_f32_e32 v75, 0x42a00000, v75
	v_mul_f32_e32 v75, 0x3fb8aa3b, v75
	v_exp_f32_e32 v81, v75
	v_cvt_pk_bf16_f32 v82, v82, v83
	v_add_f32_e64 v80, v80, 1.0
	v_add_f32_e64 v81, v81, 1.0
	s_nop 0
	v_rcp_f32_e32 v84, v80
	v_rcp_f32_e32 v85, v81
	s_nop 0
	v_fma_f32 v80, -v80, v84, 1.0
	v_fma_f32 v81, -v81, v85, 1.0
	s_nop 0
	v_fma_f32 v84, v84, v80, v84
	v_fma_f32 v85, v85, v81, v85
	v_cvt_pk_bf16_f32 v80, v70, v71
	v_cvt_pk_bf16_f32 v81, v76, v77
	v_cvt_pk_bf16_f32 v83, v84, v85
	v_mad_i64_i32 v[70:71], s[6:7], v164, s62, v[66:67]
	global_store_dwordx4 v[70:71], v[80:83], off offset:-256

; __device__ __forceinline__ u32x2 pk4(f32x4 v) { u32x2 r; r.x = pk2(v.x, v.y); r.y = pk2(v.z, v.w); return r; }
; __device__ __forceinline__ float rcp_nr(float d) { const float r = __builtin_amdgcn_rcpf(d); return fmaf(r, fmaf(-d, r, 1.f), r); }
; __device__ __forceinline__ float sigmoidf_(float x) { return rcp_nr(1.f + __expf(fminf(-x, 80.f))); }
; template <int EPI>
; __device__ __forceinline__ void epilogue(const Params& p, f32x4 (&acc)[2][2][4][2], const int pm, const int pn, const int wr, const int wc, const int fr, const int fq) {
;     ...
;           } else if (col0 >= 1280) {
;             v0.x = sigmoidf_(v0.x); v0.y = sigmoidf_(v0.y); v0.z = sigmoidf_(v0.z); v0.w = sigmoidf_(v0.w);
;             v1.x = sigmoidf_(v1.x); v1.y = sigmoidf_(v1.y); v1.z = sigmoidf_(v1.z); v1.w = sigmoidf_(v1.w);
;             const u32x2 lo = pk4(v0), hi = pk4(v1);
;             *(u32x4*)(P + (size_t)row * PW + col - 256) = u32x4{lo.x, lo.y, hi.x, hi.y};
.LBB0_355:
	s_andn2_b64 vcc, exec, s[30:31]
	s_cbranch_vccnz .LBB0_357
	v_max_f32_e64 v58, -v54, -v54
	v_max_f32_e64 v59, -v55, -v55
	v_min_f32_e32 v58, 0x42a00000, v58
	v_min_f32_e32 v59, 0x42a00000, v59
	v_mul_f32_e32 v58, 0x3fb8aa3b, v58
	v_mul_f32_e32 v59, 0x3fb8aa3b, v59
	v_exp_f32_e32 v58, v58
	v_exp_f32_e32 v59, v59
	s_nop 0
	v_add_f32_e64 v58, v58, 1.0
	v_add_f32_e64 v59, v59, 1.0
	s_nop 0
	v_rcp_f32_e32 v60, v58
	v_rcp_f32_e32 v61, v59
	s_nop 0
	v_fma_f32 v58, -v58, v60, 1.0
	v_fma_f32 v59, -v59, v61, 1.0
	s_nop 0
	v_fma_f32 v58, v60, v58, v60
	v_fma_f32 v59, v61, v59, v61
	v_max_f32_e64 v60, -v56, -v56
	v_max_f32_e64 v61, -v57, -v57
	v_min_f32_e32 v60, 0x42a00000, v60
	v_min_f32_e32 v61, 0x42a00000, v61
	v_mul_f32_e32 v60, 0x3fb8aa3b, v60
	v_mul_f32_e32 v61, 0x3fb8aa3b, v61
	v_exp_f32_e32 v60, v60
	v_exp_f32_e32 v61, v61
	v_cvt_pk_bf16_f32 v58, v58, v59
	v_add_f32_e64 v60, v60, 1.0
	v_add_f32_e64 v61, v61, 1.0
	s_nop 0
	v_rcp_f32_e32 v62, v60
	v_rcp_f32_e32 v63, v61
	s_nop 0
	v_fma_f32 v60, -v60, v62, 1.0
	v_fma_f32 v61, -v61, v63, 1.0
	s_nop 0
	v_fma_f32 v60, v62, v60, v62
	v_fma_f32 v61, v63, v61, v63
	v_max_f32_e64 v62, -v50, -v50
	v_max_f32_e64 v63, -v51, -v51
	v_min_f32_e32 v62, 0x42a00000, v62
	v_min_f32_e32 v63, 0x42a00000, v63
	v_mul_f32_e32 v62, 0x3fb8aa3b, v62
	v_mul_f32_e32 v63, 0x3fb8aa3b, v63
	v_exp_f32_e32 v62, v62
	v_exp_f32_e32 v63, v63
	v_cvt_pk_bf16_f32 v59, v60, v61
	v_add_f32_e64 v62, v62, 1.0
	v_add_f32_e64 v63, v63, 1.0
	s_nop 0
	v_rcp_f32_e32 v64, v62
	v_rcp_f32_e32 v65, v63
	s_nop 0
	v_fma_f32 v62, -v62, v64, 1.0
	v_fma_f32 v63, -v63, v65, 1.0
	s_nop 0
	v_fma_f32 v62, v64, v62, v64
	v_fma_f32 v63, v65, v63, v65
	v_max_f32_e64 v64, -v52, -v52
	v_max_f32_e64 v65, -v53, -v53
	v_min_f32_e32 v64, 0x42a00000, v64
	v_min_f32_e32 v65, 0x42a00000, v65
	v_mul_f32_e32 v64, 0x3fb8aa3b, v64
	v_mul_f32_e32 v65, 0x3fb8aa3b, v65
	v_exp_f32_e32 v64, v64
	v_exp_f32_e32 v65, v65
	v_cvt_pk_bf16_f32 v60, v62, v63
	v_mad_i64_i32 v[62:63], s[30:31], v126, s62, v[66:67]
	v_add_f32_e64 v64, v64, 1.0
	v_add_f32_e64 v65, v65, 1.0
	s_nop 0
	v_rcp_f32_e32 v76, v64
	v_rcp_f32_e32 v77, v65
	s_nop 0
	v_fma_f32 v64, -v64, v76, 1.0
	v_fma_f32 v65, -v65, v77, 1.0
	s_nop 0
	v_fma_f32 v64, v76, v64, v76
	v_fma_f32 v65, v77, v65, v77
	s_nop 0
	v_cvt_pk_bf16_f32 v61, v64, v65
	global_store_dwordx4 v[62:63], v[58:61], off offset:-256

; __device__ __forceinline__ u32x2 pk4(f32x4 v) { u32x2 r; r.x = pk2(v.x, v.y); r.y = pk2(v.z, v.w); return r; }
; __device__ __forceinline__ float rcp_nr(float d) { const float r = __builtin_amdgcn_rcpf(d); return fmaf(r, fmaf(-d, r, 1.f), r); }
; __device__ __forceinline__ float sigmoidf_(float x) { return rcp_nr(1.f + __expf(fminf(-x, 80.f))); }
; template <int EPI>
; __device__ __forceinline__ void epilogue(const Params& p, f32x4 (&acc)[2][2][4][2], const int pm, const int pn, const int wr, const int wc, const int fr, const int fq) {
;     ...
;           } else if (col0 >= 1280) {
;             v0.x = sigmoidf_(v0.x); v0.y = sigmoidf_(v0.y); v0.z = sigmoidf_(v0.z); v0.w = sigmoidf_(v0.w);
;             v1.x = sigmoidf_(v1.x); v1.y = sigmoidf_(v1.y); v1.z = sigmoidf_(v1.z); v1.w = sigmoidf_(v1.w);
;             const u32x2 lo = pk4(v0), hi = pk4(v1);
;             *(u32x4*)(P + (size_t)row * PW + col - 256) = u32x4{lo.x, lo.y, hi.x, hi.y};
.LBB0_367:
	s_andn2_b64 vcc, exec, s[30:31]
	s_cbranch_vccnz .LBB0_369
	v_max_f32_e64 v50, -v46, -v46
	v_max_f32_e64 v51, -v47, -v47
	v_min_f32_e32 v50, 0x42a00000, v50
	v_min_f32_e32 v51, 0x42a00000, v51
	v_mul_f32_e32 v50, 0x3fb8aa3b, v50
	v_mul_f32_e32 v51, 0x3fb8aa3b, v51
	v_exp_f32_e32 v50, v50
	v_exp_f32_e32 v51, v51
	s_nop 0
	v_add_f32_e64 v50, v50, 1.0
	v_add_f32_e64 v51, v51, 1.0
	s_nop 0
	v_rcp_f32_e32 v52, v50
	v_rcp_f32_e32 v53, v51
	s_nop 0
	v_fma_f32 v50, -v50, v52, 1.0
	v_fma_f32 v51, -v51, v53, 1.0
	s_nop 0
	v_fma_f32 v50, v52, v50, v52
	v_fma_f32 v51, v53, v51, v53
	v_max_f32_e64 v52, -v48, -v48
	v_max_f32_e64 v53, -v49, -v49
	v_min_f32_e32 v52, 0x42a00000, v52
	v_min_f32_e32 v53, 0x42a00000, v53
	v_mul_f32_e32 v52, 0x3fb8aa3b, v52
	v_mul_f32_e32 v53, 0x3fb8aa3b, v53
	v_exp_f32_e32 v52, v52
	v_exp_f32_e32 v53, v53
	v_cvt_pk_bf16_f32 v50, v50, v51
	v_add_f32_e64 v52, v52, 1.0
	v_add_f32_e64 v53, v53, 1.0
	s_nop 0
	v_rcp_f32_e32 v54, v52
	v_rcp_f32_e32 v55, v53
	s_nop 0
	v_fma_f32 v52, -v52, v54, 1.0
	v_fma_f32 v53, -v53, v55, 1.0
	s_nop 0
	v_fma_f32 v52, v54, v52, v54
	v_fma_f32 v53, v55, v53, v55
	v_max_f32_e64 v54, -v42, -v42
	v_max_f32_e64 v55, -v43, -v43
	v_min_f32_e32 v54, 0x42a00000, v54
	v_min_f32_e32 v55, 0x42a00000, v55
	v_mul_f32_e32 v54, 0x3fb8aa3b, v54
	v_mul_f32_e32 v55, 0x3fb8aa3b, v55
	v_exp_f32_e32 v54, v54
	v_exp_f32_e32 v55, v55
	v_cvt_pk_bf16_f32 v51, v52, v53
	v_add_f32_e64 v54, v54, 1.0
	v_add_f32_e64 v55, v55, 1.0
	s_nop 0
	v_rcp_f32_e32 v56, v54
	v_rcp_f32_e32 v57, v55
	s_nop 0
	v_fma_f32 v54, -v54, v56, 1.0
	v_fma_f32 v55, -v55, v57, 1.0
	s_nop 0
	v_fma_f32 v54, v56, v54, v56
	v_fma_f32 v55, v57, v55, v57
	v_max_f32_e64 v56, -v44, -v44
	v_max_f32_e64 v57, -v45, -v45
	v_min_f32_e32 v56, 0x42a00000, v56
	v_min_f32_e32 v57, 0x42a00000, v57
	v_mul_f32_e32 v56, 0x3fb8aa3b, v56
	v_mul_f32_e32 v57, 0x3fb8aa3b, v57
	v_exp_f32_e32 v56, v56
	v_exp_f32_e32 v57, v57
	v_cvt_pk_bf16_f32 v52, v54, v55
	v_mad_i64_i32 v[54:55], s[30:31], v118, s62, v[66:67]
	v_add_f32_e64 v56, v56, 1.0
	v_add_f32_e64 v57, v57, 1.0
	s_nop 0
	v_rcp_f32_e32 v58, v56
	v_rcp_f32_e32 v59, v57
	s_nop 0
	v_fma_f32 v56, -v56, v58, 1.0
	v_fma_f32 v57, -v57, v59, 1.0
	s_nop 0
	v_fma_f32 v56, v58, v56, v58
	v_fma_f32 v57, v59, v57, v59
	s_nop 0
	v_cvt_pk_bf16_f32 v53, v56, v57
	global_store_dwordx4 v[54:55], v[50:53], off offset:-256

; __device__ __forceinline__ u32x2 pk4(f32x4 v) { u32x2 r; r.x = pk2(v.x, v.y); r.y = pk2(v.z, v.w); return r; }
; __device__ __forceinline__ float rcp_nr(float d) { const float r = __builtin_amdgcn_rcpf(d); return fmaf(r, fmaf(-d, r, 1.f), r); }
; __device__ __forceinline__ float sigmoidf_(float x) { return rcp_nr(1.f + __expf(fminf(-x, 80.f))); }
; template <int EPI>
; __device__ __forceinline__ void epilogue(const Params& p, f32x4 (&acc)[2][2][4][2], const int pm, const int pn, const int wr, const int wc, const int fr, const int fq) {
;     ...
;           } else if (col0 >= 1280) {
;             v0.x = sigmoidf_(v0.x); v0.y = sigmoidf_(v0.y); v0.z = sigmoidf_(v0.z); v0.w = sigmoidf_(v0.w);
;             v1.x = sigmoidf_(v1.x); v1.y = sigmoidf_(v1.y); v1.z = sigmoidf_(v1.z); v1.w = sigmoidf_(v1.w);
;             const u32x2 lo = pk4(v0), hi = pk4(v1);
;             *(u32x4*)(P + (size_t)row * PW + col - 256) = u32x4{lo.x, lo.y, hi.x, hi.y};
.LBB0_379:
	s_andn2_b64 vcc, exec, s[30:31]
	s_cbranch_vccnz .LBB0_381
	v_max_f32_e64 v42, -v38, -v38
	v_max_f32_e64 v43, -v39, -v39
	v_min_f32_e32 v42, 0x42a00000, v42
	v_min_f32_e32 v43, 0x42a00000, v43
	v_mul_f32_e32 v42, 0x3fb8aa3b, v42
	v_mul_f32_e32 v43, 0x3fb8aa3b, v43
	v_exp_f32_e32 v42, v42
	v_exp_f32_e32 v43, v43
	s_nop 0
	v_add_f32_e64 v42, v42, 1.0
	v_add_f32_e64 v43, v43, 1.0
	s_nop 0
	v_rcp_f32_e32 v44, v42
	v_rcp_f32_e32 v45, v43
	s_nop 0
	v_fma_f32 v42, -v42, v44, 1.0
	v_fma_f32 v43, -v43, v45, 1.0
	s_nop 0
	v_fma_f32 v42, v44, v42, v44
	v_fma_f32 v43, v45, v43, v45
	v_max_f32_e64 v44, -v40, -v40
	v_max_f32_e64 v45, -v41, -v41
	v_min_f32_e32 v44, 0x42a00000, v44
	v_min_f32_e32 v45, 0x42a00000, v45
	v_mul_f32_e32 v44, 0x3fb8aa3b, v44
	v_mul_f32_e32 v45, 0x3fb8aa3b, v45
	v_exp_f32_e32 v44, v44
	v_exp_f32_e32 v45, v45
	v_cvt_pk_bf16_f32 v42, v42, v43
	v_add_f32_e64 v44, v44, 1.0
	v_add_f32_e64 v45, v45, 1.0
	s_nop 0
	v_rcp_f32_e32 v46, v44
	v_rcp_f32_e32 v47, v45
	s_nop 0
	v_fma_f32 v44, -v44, v46, 1.0
	v_fma_f32 v45, -v45, v47, 1.0
	s_nop 0
	v_fma_f32 v44, v46, v44, v46
	v_fma_f32 v45, v47, v45, v47
	v_max_f32_e64 v46, -v34, -v34
	v_max_f32_e64 v47, -v35, -v35
	v_min_f32_e32 v46, 0x42a00000, v46
	v_min_f32_e32 v47, 0x42a00000, v47
	v_mul_f32_e32 v46, 0x3fb8aa3b, v46
	v_mul_f32_e32 v47, 0x3fb8aa3b, v47
	v_exp_f32_e32 v46, v46
	v_exp_f32_e32 v47, v47
	v_cvt_pk_bf16_f32 v43, v44, v45
	v_add_f32_e64 v46, v46, 1.0
	v_add_f32_e64 v47, v47, 1.0
	s_nop 0
	v_rcp_f32_e32 v48, v46
	v_rcp_f32_e32 v49, v47
	s_nop 0
	v_fma_f32 v46, -v46, v48, 1.0
	v_fma_f32 v47, -v47, v49, 1.0
	s_nop 0
	v_fma_f32 v46, v48, v46, v48
	v_fma_f32 v47, v49, v47, v49
	v_max_f32_e64 v48, -v36, -v36
	v_max_f32_e64 v49, -v37, -v37
	v_min_f32_e32 v48, 0x42a00000, v48
	v_min_f32_e32 v49, 0x42a00000, v49
	v_mul_f32_e32 v48, 0x3fb8aa3b, v48
	v_mul_f32_e32 v49, 0x3fb8aa3b, v49
	v_exp_f32_e32 v48, v48
	v_exp_f32_e32 v49, v49
	v_cvt_pk_bf16_f32 v44, v46, v47
	v_mad_i64_i32 v[46:47], s[26:27], v110, s62, v[66:67]
	v_add_f32_e64 v48, v48, 1.0
	v_add_f32_e64 v49, v49, 1.0
	s_nop 0
	v_rcp_f32_e32 v50, v48
	v_rcp_f32_e32 v51, v49
	s_nop 0
	v_fma_f32 v48, -v48, v50, 1.0
	v_fma_f32 v49, -v49, v51, 1.0
	s_nop 0
	v_fma_f32 v48, v50, v48, v50
	v_fma_f32 v49, v51, v49, v51
	s_nop 0
	v_cvt_pk_bf16_f32 v45, v48, v49
	global_store_dwordx4 v[46:47], v[42:45], off offset:-256

; __device__ __forceinline__ u32x2 pk4(f32x4 v) { u32x2 r; r.x = pk2(v.x, v.y); r.y = pk2(v.z, v.w); return r; }
; __device__ __forceinline__ float rcp_nr(float d) { const float r = __builtin_amdgcn_rcpf(d); return fmaf(r, fmaf(-d, r, 1.f), r); }
; __device__ __forceinline__ float sigmoidf_(float x) { return rcp_nr(1.f + __expf(fminf(-x, 80.f))); }
; template <int EPI>
; __device__ __forceinline__ void epilogue(const Params& p, f32x4 (&acc)[2][2][4][2], const int pm, const int pn, const int wr, const int wc, const int fr, const int fq) {
;     ...
;           } else if (col0 >= 1280) {
;             v0.x = sigmoidf_(v0.x); v0.y = sigmoidf_(v0.y); v0.z = sigmoidf_(v0.z); v0.w = sigmoidf_(v0.w);
;             v1.x = sigmoidf_(v1.x); v1.y = sigmoidf_(v1.y); v1.z = sigmoidf_(v1.z); v1.w = sigmoidf_(v1.w);
;             const u32x2 lo = pk4(v0), hi = pk4(v1);
;             *(u32x4*)(P + (size_t)row * PW + col - 256) = u32x4{lo.x, lo.y, hi.x, hi.y};
.LBB0_397:
	s_andn2_b64 vcc, exec, s[26:27]
	s_cbranch_vccnz .LBB0_399
	v_max_f32_e64 v36, -v30, -v30
	v_max_f32_e64 v37, -v31, -v31
	v_min_f32_e32 v36, 0x42a00000, v36
	v_min_f32_e32 v37, 0x42a00000, v37
	v_mul_f32_e32 v36, 0x3fb8aa3b, v36
	v_mul_f32_e32 v37, 0x3fb8aa3b, v37
	v_exp_f32_e32 v36, v36
	v_exp_f32_e32 v37, v37
	s_nop 0
	v_add_f32_e64 v36, v36, 1.0
	v_add_f32_e64 v37, v37, 1.0
	s_nop 0
	v_rcp_f32_e32 v38, v36
	v_rcp_f32_e32 v39, v37
	s_nop 0
	v_fma_f32 v36, -v36, v38, 1.0
	v_fma_f32 v37, -v37, v39, 1.0
	s_nop 0
	v_fma_f32 v36, v38, v36, v38
	v_fma_f32 v37, v39, v37, v39
	v_max_f32_e64 v38, -v32, -v32
	v_max_f32_e64 v39, -v33, -v33
	v_min_f32_e32 v38, 0x42a00000, v38
	v_min_f32_e32 v39, 0x42a00000, v39
	v_mul_f32_e32 v38, 0x3fb8aa3b, v38
	v_mul_f32_e32 v39, 0x3fb8aa3b, v39
	v_exp_f32_e32 v38, v38
	v_exp_f32_e32 v39, v39
	v_cvt_pk_bf16_f32 v36, v36, v37
	v_add_f32_e64 v38, v38, 1.0
	v_add_f32_e64 v39, v39, 1.0
	s_nop 0
	v_rcp_f32_e32 v40, v38
	v_rcp_f32_e32 v41, v39
	s_nop 0
	v_fma_f32 v38, -v38, v40, 1.0
	v_fma_f32 v39, -v39, v41, 1.0
	s_nop 0
	v_fma_f32 v38, v40, v38, v40
	v_fma_f32 v39, v41, v39, v41
	v_max_f32_e64 v40, -v26, -v26
	v_max_f32_e64 v41, -v27, -v27
	v_min_f32_e32 v40, 0x42a00000, v40
	v_min_f32_e32 v41, 0x42a00000, v41
	v_mul_f32_e32 v40, 0x3fb8aa3b, v40
	v_mul_f32_e32 v41, 0x3fb8aa3b, v41
	v_exp_f32_e32 v40, v40
	v_exp_f32_e32 v41, v41
	v_cvt_pk_bf16_f32 v37, v38, v39
	v_add_f32_e64 v40, v40, 1.0
	v_add_f32_e64 v41, v41, 1.0
	s_nop 0
	v_rcp_f32_e32 v42, v40
	v_rcp_f32_e32 v43, v41
	s_nop 0
	v_fma_f32 v40, -v40, v42, 1.0
	v_fma_f32 v41, -v41, v43, 1.0
	s_nop 0
	v_fma_f32 v40, v42, v40, v42
	v_fma_f32 v41, v43, v41, v43
	v_max_f32_e64 v42, -v28, -v28
	v_max_f32_e64 v43, -v29, -v29
	v_min_f32_e32 v42, 0x42a00000, v42
	v_min_f32_e32 v43, 0x42a00000, v43
	v_mul_f32_e32 v42, 0x3fb8aa3b, v42
	v_mul_f32_e32 v43, 0x3fb8aa3b, v43
	v_exp_f32_e32 v42, v42
	v_exp_f32_e32 v43, v43
	v_cvt_pk_bf16_f32 v38, v40, v41
	v_mad_i64_i32 v[40:41], s[26:27], v102, s62, v[66:67]
	v_add_f32_e64 v42, v42, 1.0
	v_add_f32_e64 v43, v43, 1.0
	s_nop 0
	v_rcp_f32_e32 v44, v42
	v_rcp_f32_e32 v45, v43
	s_nop 0
	v_fma_f32 v42, -v42, v44, 1.0
	v_fma_f32 v43, -v43, v45, 1.0
	s_nop 0
	v_fma_f32 v42, v44, v42, v44
	v_fma_f32 v43, v45, v43, v45
	s_nop 0
	v_cvt_pk_bf16_f32 v39, v42, v43
	global_store_dwordx4 v[40:41], v[36:39], off offset:-256

; __device__ __forceinline__ u32x2 pk4(f32x4 v) { u32x2 r; r.x = pk2(v.x, v.y); r.y = pk2(v.z, v.w); return r; }
; __device__ __forceinline__ float rcp_nr(float d) { const float r = __builtin_amdgcn_rcpf(d); return fmaf(r, fmaf(-d, r, 1.f), r); }
; __device__ __forceinline__ float sigmoidf_(float x) { return rcp_nr(1.f + __expf(fminf(-x, 80.f))); }
; template <int EPI>
; __device__ __forceinline__ void epilogue(const Params& p, f32x4 (&acc)[2][2][4][2], const int pm, const int pn, const int wr, const int wc, const int fr, const int fq) {
;     ...
;           } else if (col0 >= 1280) {
;             v0.x = sigmoidf_(v0.x); v0.y = sigmoidf_(v0.y); v0.z = sigmoidf_(v0.z); v0.w = sigmoidf_(v0.w);
;             v1.x = sigmoidf_(v1.x); v1.y = sigmoidf_(v1.y); v1.z = sigmoidf_(v1.z); v1.w = sigmoidf_(v1.w);
;             const u32x2 lo = pk4(v0), hi = pk4(v1);
;             *(u32x4*)(P + (size_t)row * PW + col - 256) = u32x4{lo.x, lo.y, hi.x, hi.y};
.LBB0_409:
	s_andn2_b64 vcc, exec, s[26:27]
	s_cbranch_vccnz .LBB0_411
	v_max_f32_e64 v26, -v22, -v22
	v_max_f32_e64 v27, -v23, -v23
	v_min_f32_e32 v26, 0x42a00000, v26
	v_min_f32_e32 v27, 0x42a00000, v27
	v_mul_f32_e32 v26, 0x3fb8aa3b, v26
	v_mul_f32_e32 v27, 0x3fb8aa3b, v27
	v_exp_f32_e32 v26, v26
	v_exp_f32_e32 v27, v27
	s_nop 0
	v_add_f32_e64 v26, v26, 1.0
	v_add_f32_e64 v27, v27, 1.0
	s_nop 0
	v_rcp_f32_e32 v28, v26
	v_rcp_f32_e32 v29, v27
	s_nop 0
	v_fma_f32 v26, -v26, v28, 1.0
	v_fma_f32 v27, -v27, v29, 1.0
	s_nop 0
	v_fma_f32 v26, v28, v26, v28
	v_fma_f32 v27, v29, v27, v29
	v_max_f32_e64 v28, -v24, -v24
	v_max_f32_e64 v29, -v25, -v25
	v_min_f32_e32 v28, 0x42a00000, v28
	v_min_f32_e32 v29, 0x42a00000, v29
	v_mul_f32_e32 v28, 0x3fb8aa3b, v28
	v_mul_f32_e32 v29, 0x3fb8aa3b, v29
	v_exp_f32_e32 v28, v28
	v_exp_f32_e32 v29, v29
	v_cvt_pk_bf16_f32 v26, v26, v27
	v_add_f32_e64 v28, v28, 1.0
	v_add_f32_e64 v29, v29, 1.0
	s_nop 0
	v_rcp_f32_e32 v30, v28
	v_rcp_f32_e32 v31, v29
	s_nop 0
	v_fma_f32 v28, -v28, v30, 1.0
	v_fma_f32 v29, -v29, v31, 1.0
	s_nop 0
	v_fma_f32 v28, v30, v28, v30
	v_fma_f32 v29, v31, v29, v31
	v_max_f32_e64 v30, -v18, -v18
	v_max_f32_e64 v31, -v19, -v19
	v_min_f32_e32 v30, 0x42a00000, v30
	v_min_f32_e32 v31, 0x42a00000, v31
	v_mul_f32_e32 v30, 0x3fb8aa3b, v30
	v_mul_f32_e32 v31, 0x3fb8aa3b, v31
	v_exp_f32_e32 v30, v30
	v_exp_f32_e32 v31, v31
	v_cvt_pk_bf16_f32 v27, v28, v29
	v_add_f32_e64 v30, v30, 1.0
	v_add_f32_e64 v31, v31, 1.0
	s_nop 0
	v_rcp_f32_e32 v32, v30
	v_rcp_f32_e32 v33, v31
	s_nop 0
	v_fma_f32 v30, -v30, v32, 1.0
	v_fma_f32 v31, -v31, v33, 1.0
	s_nop 0
	v_fma_f32 v30, v32, v30, v32
	v_fma_f32 v31, v33, v31, v33
	v_max_f32_e64 v32, -v20, -v20
	v_max_f32_e64 v33, -v21, -v21
	v_min_f32_e32 v32, 0x42a00000, v32
	v_min_f32_e32 v33, 0x42a00000, v33
	v_mul_f32_e32 v32, 0x3fb8aa3b, v32
	v_mul_f32_e32 v33, 0x3fb8aa3b, v33
	v_exp_f32_e32 v32, v32
	v_exp_f32_e32 v33, v33
	v_cvt_pk_bf16_f32 v28, v30, v31
	v_mad_i64_i32 v[30:31], s[26:27], v94, s62, v[66:67]
	v_add_f32_e64 v32, v32, 1.0
	v_add_f32_e64 v33, v33, 1.0
	s_nop 0
	v_rcp_f32_e32 v36, v32
	v_rcp_f32_e32 v37, v33
	s_nop 0
	v_fma_f32 v32, -v32, v36, 1.0
	v_fma_f32 v33, -v33, v37, 1.0
	s_nop 0
	v_fma_f32 v32, v36, v32, v36
	v_fma_f32 v33, v37, v33, v37
	s_nop 0
	v_cvt_pk_bf16_f32 v29, v32, v33
	global_store_dwordx4 v[30:31], v[26:29], off offset:-256

; __device__ __forceinline__ u32x2 pk4(f32x4 v) { u32x2 r; r.x = pk2(v.x, v.y); r.y = pk2(v.z, v.w); return r; }
; __device__ __forceinline__ float rcp_nr(float d) { const float r = __builtin_amdgcn_rcpf(d); return fmaf(r, fmaf(-d, r, 1.f), r); }
; __device__ __forceinline__ float sigmoidf_(float x) { return rcp_nr(1.f + __expf(fminf(-x, 80.f))); }
; template <int EPI>
; __device__ __forceinline__ void epilogue(const Params& p, f32x4 (&acc)[2][2][4][2], const int pm, const int pn, const int wr, const int wc, const int fr, const int fq) {
;     ...
;           } else if (col0 >= 1280) {
;             v0.x = sigmoidf_(v0.x); v0.y = sigmoidf_(v0.y); v0.z = sigmoidf_(v0.z); v0.w = sigmoidf_(v0.w);
;             v1.x = sigmoidf_(v1.x); v1.y = sigmoidf_(v1.y); v1.z = sigmoidf_(v1.z); v1.w = sigmoidf_(v1.w);
;             const u32x2 lo = pk4(v0), hi = pk4(v1);
;             *(u32x4*)(P + (size_t)row * PW + col - 256) = u32x4{lo.x, lo.y, hi.x, hi.y};
.LBB0_421:
	s_andn2_b64 vcc, exec, s[26:27]
	s_cbranch_vccnz .LBB0_423
	v_max_f32_e64 v18, -v14, -v14
	v_max_f32_e64 v19, -v15, -v15
	v_min_f32_e32 v18, 0x42a00000, v18
	v_min_f32_e32 v19, 0x42a00000, v19
	v_mul_f32_e32 v18, 0x3fb8aa3b, v18
	v_mul_f32_e32 v19, 0x3fb8aa3b, v19
	v_exp_f32_e32 v18, v18
	v_exp_f32_e32 v19, v19
	s_nop 0
	v_add_f32_e64 v18, v18, 1.0
	v_add_f32_e64 v19, v19, 1.0
	s_nop 0
	v_rcp_f32_e32 v20, v18
	v_rcp_f32_e32 v21, v19
	s_nop 0
	v_fma_f32 v18, -v18, v20, 1.0
	v_fma_f32 v19, -v19, v21, 1.0
	s_nop 0
	v_fma_f32 v18, v20, v18, v20
	v_fma_f32 v19, v21, v19, v21
	v_max_f32_e64 v20, -v16, -v16
	v_max_f32_e64 v21, -v17, -v17
	v_min_f32_e32 v20, 0x42a00000, v20
	v_min_f32_e32 v21, 0x42a00000, v21
	v_mul_f32_e32 v20, 0x3fb8aa3b, v20
	v_mul_f32_e32 v21, 0x3fb8aa3b, v21
	v_exp_f32_e32 v20, v20
	v_exp_f32_e32 v21, v21
	v_cvt_pk_bf16_f32 v18, v18, v19
	v_add_f32_e64 v20, v20, 1.0
	v_add_f32_e64 v21, v21, 1.0
	s_nop 0
	v_rcp_f32_e32 v22, v20
	v_rcp_f32_e32 v23, v21
	s_nop 0
	v_fma_f32 v20, -v20, v22, 1.0
	v_fma_f32 v21, -v21, v23, 1.0
	s_nop 0
	v_fma_f32 v20, v22, v20, v22
	v_fma_f32 v21, v23, v21, v23
	v_max_f32_e64 v22, -v10, -v10
	v_max_f32_e64 v23, -v11, -v11
	v_min_f32_e32 v22, 0x42a00000, v22
	v_min_f32_e32 v23, 0x42a00000, v23
	v_mul_f32_e32 v22, 0x3fb8aa3b, v22
	v_mul_f32_e32 v23, 0x3fb8aa3b, v23
	v_exp_f32_e32 v22, v22
	v_exp_f32_e32 v23, v23
	v_cvt_pk_bf16_f32 v19, v20, v21
	v_add_f32_e64 v22, v22, 1.0
	v_add_f32_e64 v23, v23, 1.0
	s_nop 0
	v_rcp_f32_e32 v24, v22
	v_rcp_f32_e32 v25, v23
	s_nop 0
	v_fma_f32 v22, -v22, v24, 1.0
	v_fma_f32 v23, -v23, v25, 1.0
	s_nop 0
	v_fma_f32 v22, v24, v22, v24
	v_fma_f32 v23, v25, v23, v25
	v_max_f32_e64 v24, -v12, -v12
	v_max_f32_e64 v25, -v13, -v13
	v_min_f32_e32 v24, 0x42a00000, v24
	v_min_f32_e32 v25, 0x42a00000, v25
	v_mul_f32_e32 v24, 0x3fb8aa3b, v24
	v_mul_f32_e32 v25, 0x3fb8aa3b, v25
	v_exp_f32_e32 v24, v24
	v_exp_f32_e32 v25, v25
	v_cvt_pk_bf16_f32 v20, v22, v23
	v_mad_i64_i32 v[22:23], s[26:27], v86, s62, v[66:67]
	v_add_f32_e64 v24, v24, 1.0
	v_add_f32_e64 v25, v25, 1.0
	s_nop 0
	v_rcp_f32_e32 v26, v24
	v_rcp_f32_e32 v27, v25
	s_nop 0
	v_fma_f32 v24, -v24, v26, 1.0
	v_fma_f32 v25, -v25, v27, 1.0
	s_nop 0
	v_fma_f32 v24, v26, v24, v26
	v_fma_f32 v25, v27, v25, v27
	s_nop 0
	v_cvt_pk_bf16_f32 v21, v24, v25
	global_store_dwordx4 v[22:23], v[18:21], off offset:-256

; __device__ __forceinline__ u32x2 pk4(f32x4 v) { u32x2 r; r.x = pk2(v.x, v.y); r.y = pk2(v.z, v.w); return r; }
; __device__ __forceinline__ float rcp_nr(float d) { const float r = __builtin_amdgcn_rcpf(d); return fmaf(r, fmaf(-d, r, 1.f), r); }
; __device__ __forceinline__ float sigmoidf_(float x) { return rcp_nr(1.f + __expf(fminf(-x, 80.f))); }
; template <int EPI>
; __device__ __forceinline__ void epilogue(const Params& p, f32x4 (&acc)[2][2][4][2], const int pm, const int pn, const int wr, const int wc, const int fr, const int fq) {
;     ...
;           } else if (col0 >= 1280) {
;             v0.x = sigmoidf_(v0.x); v0.y = sigmoidf_(v0.y); v0.z = sigmoidf_(v0.z); v0.w = sigmoidf_(v0.w);
;             v1.x = sigmoidf_(v1.x); v1.y = sigmoidf_(v1.y); v1.z = sigmoidf_(v1.z); v1.w = sigmoidf_(v1.w);
;             const u32x2 lo = pk4(v0), hi = pk4(v1);
;             *(u32x4*)(P + (size_t)row * PW + col - 256) = u32x4{lo.x, lo.y, hi.x, hi.y};
.LBB0_433:
	s_andn2_b64 vcc, exec, s[4:5]
	s_cbranch_vccnz .LBB0_435
	v_max_f32_e64 v10, -v6, -v6
	v_max_f32_e64 v11, -v7, -v7
	v_min_f32_e32 v10, 0x42a00000, v10
	v_min_f32_e32 v11, 0x42a00000, v11
	v_mul_f32_e32 v10, 0x3fb8aa3b, v10
	v_mul_f32_e32 v11, 0x3fb8aa3b, v11
	v_exp_f32_e32 v10, v10
	v_exp_f32_e32 v11, v11
	v_max_f32_e64 v12, -v8, -v8
	v_max_f32_e64 v13, -v9, -v9
	v_min_f32_e32 v12, 0x42a00000, v12
	v_add_f32_e64 v10, v10, 1.0
	v_add_f32_e64 v11, v11, 1.0
	v_min_f32_e32 v13, 0x42a00000, v13
	v_rcp_f32_e32 v14, v10
	v_rcp_f32_e32 v15, v11
	v_max_f32_e64 v18, -v4, -v4
	v_max_f32_e64 v19, -v5, -v5
	v_mul_f32_e32 v12, 0x3fb8aa3b, v12
	v_fma_f32 v10, -v10, v14, 1.0
	v_fma_f32 v11, -v11, v15, 1.0
	v_mul_f32_e32 v13, 0x3fb8aa3b, v13
	v_fma_f32 v10, v14, v10, v14
	v_fma_f32 v11, v15, v11, v15
	v_max_f32_e64 v14, -v2, -v2
	v_max_f32_e64 v15, -v3, -v3
	v_min_f32_e32 v14, 0x42a00000, v14
	v_min_f32_e32 v15, 0x42a00000, v15
	v_min_f32_e32 v18, 0x42a00000, v18
	v_min_f32_e32 v19, 0x42a00000, v19
	v_exp_f32_e32 v12, v12
	v_exp_f32_e32 v13, v13
	v_mul_f32_e32 v14, 0x3fb8aa3b, v14
	v_mul_f32_e32 v15, 0x3fb8aa3b, v15
	v_mul_f32_e32 v18, 0x3fb8aa3b, v18
	v_mul_f32_e32 v19, 0x3fb8aa3b, v19
	v_exp_f32_e32 v14, v14
	v_exp_f32_e32 v15, v15
	v_exp_f32_e32 v18, v18
	v_exp_f32_e32 v19, v19
	v_add_f32_e64 v12, v12, 1.0
	v_add_f32_e64 v13, v13, 1.0
	v_add_f32_e64 v14, v14, 1.0
	v_add_f32_e64 v15, v15, 1.0
	v_rcp_f32_e32 v16, v12
	v_rcp_f32_e32 v17, v13
	v_add_f32_e64 v18, v18, 1.0
	v_add_f32_e64 v19, v19, 1.0
	v_rcp_f32_e32 v20, v14
	v_rcp_f32_e32 v21, v15
	v_rcp_f32_e32 v22, v18
	v_rcp_f32_e32 v23, v19
	v_fma_f32 v12, -v12, v16, 1.0
	v_fma_f32 v13, -v13, v17, 1.0
	v_fma_f32 v14, -v14, v20, 1.0
	v_fma_f32 v15, -v15, v21, 1.0
	v_fma_f32 v12, v16, v12, v16
	v_fma_f32 v13, v17, v13, v17
	v_fma_f32 v16, -v18, v22, 1.0
	v_fma_f32 v17, -v19, v23, 1.0
	v_fma_f32 v14, v20, v14, v20
	v_fma_f32 v15, v21, v15, v21
	v_fma_f32 v16, v22, v16, v22
	v_fma_f32 v17, v23, v17, v23
	v_cvt_pk_bf16_f32 v10, v10, v11
	v_cvt_pk_bf16_f32 v11, v12, v13
	v_cvt_pk_bf16_f32 v12, v14, v15
	v_cvt_pk_bf16_f32 v13, v16, v17
	v_mad_i64_i32 v[14:15], s[4:5], v78, s62, v[66:67]
	global_store_dwordx4 v[14:15], v[10:13], off offset:-256

; __device__ __forceinline__ u32x2 pk4(f32x4 v) { u32x2 r; r.x = pk2(v.x, v.y); r.y = pk2(v.z, v.w); return r; }
; __device__ __forceinline__ f32x4 unpk4(u32x2 w) { f32x4 r; r.x = bflo(w.x); r.y = bfhi(w.x); r.z = bflo(w.y); r.w = bfhi(w.y); return r; }
; __device__ __forceinline__ float rcp_nr(float d) { const float r = __builtin_amdgcn_rcpf(d); return fmaf(r, fmaf(-d, r, 1.f), r); }
; __device__ __forceinline__ float sigmoidf_(float x) { return rcp_nr(1.f + __expf(fminf(-x, 80.f))); }
; template <int EPI>
; __device__ __forceinline__ void epilogue(const Params& p, f32x4 (&acc)[2][2][4][2], const int pm, const int pn, const int wr, const int wc, const int fr, const int fq) {
;     ...
;       for (int m = 0; m < 4; ++m) {
;         const int row = pm * 256 + ai * 128 + wr * 64 + m * 16 + fr;
;         const int j0 = pn * 128 + wc * 32 + fq * 8;
;         const u32x4 gw4 = *(const u32x4*)(P + (size_t)row * PW + 1024 + j0);
;         u32x2 o[2];
; #pragma unroll
;         for (int bj = 0; bj < 2; ++bj) {
;           const f32x4 ya = acc[ai][bj][m][0], yb = acc[ai][bj][m][1];
;           const f32x4 gs = unpk4(bj == 0 ? u32x2{gw4.x, gw4.y} : u32x2{gw4.z, gw4.w});
;           f32x4 sv;
;           sv.x = gs.x * ya.x * sigmoidf_(yb.x); sv.y = gs.y * ya.y * sigmoidf_(yb.y);
;           sv.z = gs.z * ya.z * sigmoidf_(yb.z); sv.w = gs.w * ya.w * sigmoidf_(yb.w);
;           o[bj] = pk4(sv);
;         }
;         *(u32x4*)(Mg + (size_t)row * DM + j0) = u32x4{o[0].x, o[0].y, o[1].x, o[1].y};
.LBB0_662:
	v_readlane_b32 s28, v244, 0
	v_lshl_or_b32 v142, s6, 7, v157
	v_readlane_b32 s30, v244, 2
	v_readlane_b32 s31, v244, 3
	v_lshl_add_u32 v144, s4, 8, v150
	v_ashrrev_i32_e32 v143, 31, v142
	v_mov_b64_e32 v[146:147], s[30:31]
	v_lshlrev_b64 v[142:143], 1, v[142:143]
	v_mad_i64_i32 v[148:149], s[26:27], v144, s50, v[146:147]
	v_lshl_add_u64 v[148:149], v[148:149], 0, v[142:143]
	global_load_dwordx4 v[162:165], v[148:149], off offset:2048
	v_or_b32_e32 v170, 16, v144
	v_mad_i64_i32 v[148:149], s[26:27], v170, s50, v[146:147]
	v_lshl_add_u64 v[148:149], v[148:149], 0, v[142:143]
	global_load_dwordx4 v[166:169], v[148:149], off offset:2048
	v_max_f32_e64 v134, -v122, -v122
	v_max_f32_e64 v161, -v123, -v123
	v_max_f32_e64 v171, -v124, -v124
	v_max_f32_e64 v172, -v125, -v125
	v_max_f32_e64 v173, -v102, -v102
	v_max_f32_e64 v174, -v103, -v103
	v_max_f32_e64 v175, -v104, -v104
	v_min_f32_e32 v134, 0x42a00000, v134
	v_min_f32_e32 v149, 0x42a00000, v161
	v_max_f32_e64 v148, -v105, -v105
	v_min_f32_e32 v161, 0x42a00000, v171
	v_min_f32_e32 v171, 0x42a00000, v172
	v_min_f32_e32 v172, 0x42a00000, v173
	v_min_f32_e32 v173, 0x42a00000, v174
	v_min_f32_e32 v174, 0x42a00000, v175
	v_mul_f32_e32 v134, 0x3fb8aa3b, v134
	v_mul_f32_e32 v175, 0x3fb8aa3b, v149
	v_min_f32_e32 v148, 0x42a00000, v148
	v_mul_f32_e32 v161, 0x3fb8aa3b, v161
	v_mul_f32_e32 v171, 0x3fb8aa3b, v171
	v_mul_f32_e32 v176, 0x3fb8aa3b, v172
	v_mul_f32_e32 v177, 0x3fb8aa3b, v173
	v_exp_f32_e32 v172, v134
	v_exp_f32_e32 v173, v175
	v_mul_f32_e32 v178, 0x3fb8aa3b, v174
	v_mul_f32_e32 v179, 0x3fb8aa3b, v148
	v_exp_f32_e32 v174, v161
	v_exp_f32_e32 v175, v171
	v_exp_f32_e32 v176, v176
	v_exp_f32_e32 v177, v177
	v_exp_f32_e32 v178, v178
	v_exp_f32_e32 v179, v179
	v_add_f32_e64 v172, v172, 1.0
	v_add_f32_e64 v173, v173, 1.0
	v_add_f32_e64 v174, v174, 1.0
	v_add_f32_e64 v175, v175, 1.0
	v_rcp_f32_e32 v180, v172
	v_rcp_f32_e32 v181, v173
	v_add_f32_e64 v176, v176, 1.0
	v_add_f32_e64 v177, v177, 1.0
	v_add_f32_e64 v178, v178, 1.0
	v_add_f32_e64 v179, v179, 1.0
	v_rcp_f32_e32 v188, v174
	v_rcp_f32_e32 v189, v175
	v_rcp_f32_e32 v190, v176
	v_rcp_f32_e32 v191, v177
	v_rcp_f32_e32 v192, v178
	v_rcp_f32_e32 v193, v179
	v_fma_f32 v172, -v172, v180, 1.0
	v_fma_f32 v173, -v173, v181, 1.0
	v_fma_f32 v174, -v174, v188, 1.0
	v_fma_f32 v175, -v175, v189, 1.0
	v_fma_f32 v172, v180, v172, v180
	v_fma_f32 v173, v181, v173, v181
	v_fma_f32 v176, -v176, v190, 1.0
	v_fma_f32 v177, -v177, v191, 1.0
	v_fma_f32 v178, -v178, v192, 1.0
	v_fma_f32 v179, -v179, v193, 1.0
	v_fma_f32 v174, v188, v174, v188
	v_fma_f32 v175, v189, v175, v189
	v_ashrrev_i32_e32 v145, 31, v144
	v_fma_f32 v176, v190, v176, v190
	v_fma_f32 v177, v191, v177, v191
	v_fma_f32 v178, v192, v178, v192
	v_fma_f32 v179, v193, v179, v193
	v_max_f32_e64 v134, -v114, -v114
	v_lshl_add_u64 v[148:149], s[14:15], 0, v[142:143]
	v_min_f32_e32 v134, 0x42a00000, v134
	v_mul_f32_e32 v134, 0x3fb8aa3b, v134
	v_ashrrev_i32_e32 v171, 31, v170
	v_lshlrev_b64 v[170:171], 11, v[170:171]
	v_lshl_add_u64 v[170:171], v[148:149], 0, v[170:171]
	v_readlane_b32 s29, v244, 1
	s_waitcnt vmcnt(0)
	v_lshlrev_b32_e32 v180, 16, v162
	v_and_b32_e32 v181, 0xffff0000, v162
	v_lshlrev_b32_e32 v162, 16, v163
	v_and_b32_e32 v163, 0xffff0000, v163
	v_lshlrev_b32_e32 v188, 16, v164
	v_and_b32_e32 v189, 0xffff0000, v164
	v_lshlrev_b32_e32 v164, 16, v165
	v_and_b32_e32 v165, 0xffff0000, v165
	v_mul_f32_e64 v180, v126, v180
	v_mul_f32_e64 v181, v127, v181
	v_mul_f32_e64 v162, v128, v162
	v_mul_f32_e64 v163, v129, v163
	v_mul_f32_e64 v188, v110, v188
	v_mul_f32_e64 v189, v111, v189
	v_mul_f32_e64 v164, v112, v164
	v_mul_f32_e64 v165, v113, v165
	v_mul_f32_e64 v172, v172, v180
	v_mul_f32_e64 v173, v173, v181
	v_mul_f32_e64 v174, v174, v162
	v_mul_f32_e64 v175, v175, v163
	v_mul_f32_e64 v176, v176, v188
	v_mul_f32_e64 v177, v177, v189
	v_mul_f32_e64 v178, v178, v164
	v_mul_f32_e64 v179, v179, v165
	v_cvt_pk_bf16_f32 v162, v172, v173
	v_lshlrev_b64 v[172:173], 11, v[144:145]
	v_cvt_pk_bf16_f32 v163, v174, v175
	v_cvt_pk_bf16_f32 v164, v176, v177
	v_cvt_pk_bf16_f32 v165, v178, v179
	v_lshl_add_u64 v[172:173], v[148:149], 0, v[172:173]
	v_or_b32_e32 v176, 32, v144
	global_store_dwordx4 v[172:173], v[162:165], off
	v_exp_f32_e32 v172, v134
	v_max_f32_e64 v134, -v115, -v115
	v_mad_i64_i32 v[162:163], s[26:27], v176, s50, v[146:147]
	v_min_f32_e32 v134, 0x42a00000, v134
	v_lshl_add_u64 v[162:163], v[162:163], 0, v[142:143]
	v_mul_f32_e32 v134, 0x3fb8aa3b, v134
	global_load_dwordx4 v[162:165], v[162:163], off offset:2048
	v_exp_f32_e32 v173, v134
	v_max_f32_e64 v134, -v116, -v116
	v_min_f32_e32 v134, 0x42a00000, v134
	v_mul_f32_e32 v134, 0x3fb8aa3b, v134
	v_add_f32_e64 v172, v172, 1.0
	v_add_f32_e64 v173, v173, 1.0
	v_exp_f32_e32 v180, v134
	v_max_f32_e64 v134, -v117, -v117
	v_rcp_f32_e32 v178, v172
	v_rcp_f32_e32 v179, v173
	v_min_f32_e32 v134, 0x42a00000, v134
	v_mul_f32_e32 v134, 0x3fb8aa3b, v134
	v_exp_f32_e32 v181, v134
	v_lshlrev_b32_e32 v174, 16, v166
	v_and_b32_e32 v175, 0xffff0000, v166
	v_fma_f32 v172, -v172, v178, 1.0
	v_fma_f32 v173, -v173, v179, 1.0
	v_mul_f32_e64 v174, v118, v174
	v_mul_f32_e64 v175, v119, v175
	v_fma_f32 v172, v178, v172, v178
	v_fma_f32 v173, v179, v173, v179
	v_max_f32_e64 v134, -v86, -v86
	v_mul_f32_e64 v172, v172, v174
	v_mul_f32_e64 v173, v173, v175
	v_add_f32_e64 v174, v180, 1.0
	v_add_f32_e64 v175, v181, 1.0
	v_lshlrev_b32_e32 v166, 16, v167
	v_rcp_f32_e32 v178, v174
	v_rcp_f32_e32 v179, v175
	v_and_b32_e32 v167, 0xffff0000, v167
	v_min_f32_e32 v134, 0x42a00000, v134
	v_mul_f32_e64 v166, v120, v166
	v_mul_f32_e64 v167, v121, v167
	v_fma_f32 v174, -v174, v178, 1.0
; __device__ __forceinline__ u32x2 pk4(f32x4 v) { u32x2 r; r.x = pk2(v.x, v.y); r.y = pk2(v.z, v.w); return r; }
; __device__ __forceinline__ f32x4 unpk4(u32x2 w) { f32x4 r; r.x = bflo(w.x); r.y = bfhi(w.x); r.z = bflo(w.y); r.w = bfhi(w.y); return r; }
; __device__ __forceinline__ float rcp_nr(float d) { const float r = __builtin_amdgcn_rcpf(d); return fmaf(r, fmaf(-d, r, 1.f), r); }
; __device__ __forceinline__ float sigmoidf_(float x) { return rcp_nr(1.f + __expf(fminf(-x, 80.f))); }
; template <int EPI>
; __device__ __forceinline__ void epilogue(const Params& p, f32x4 (&acc)[2][2][4][2], const int pm, const int pn, const int wr, const int wc, const int fr, const int fq) {
;     ...
;       for (int m = 0; m < 4; ++m) {
;         const int row = pm * 256 + ai * 128 + wr * 64 + m * 16 + fr;
;         const int j0 = pn * 128 + wc * 32 + fq * 8;
;         const u32x4 gw4 = *(const u32x4*)(P + (size_t)row * PW + 1024 + j0);
;         u32x2 o[2];
; #pragma unroll
;         for (int bj = 0; bj < 2; ++bj) {
;           const f32x4 ya = acc[ai][bj][m][0], yb = acc[ai][bj][m][1];
;           const f32x4 gs = unpk4(bj == 0 ? u32x2{gw4.x, gw4.y} : u32x2{gw4.z, gw4.w});
;           f32x4 sv;
;           sv.x = gs.x * ya.x * sigmoidf_(yb.x); sv.y = gs.y * ya.y * sigmoidf_(yb.y);
;           sv.z = gs.z * ya.z * sigmoidf_(yb.z); sv.w = gs.w * ya.w * sigmoidf_(yb.w);
;           o[bj] = pk4(sv);
;         }
;         *(u32x4*)(Mg + (size_t)row * DM + j0) = u32x4{o[0].x, o[0].y, o[1].x, o[1].y};
	v_fma_f32 v175, -v175, v179, 1.0
	v_mul_f32_e32 v134, 0x3fb8aa3b, v134
	v_fma_f32 v174, v178, v174, v178
	v_fma_f32 v175, v179, v175, v179
	v_ashrrev_i32_e32 v177, 31, v176
	v_mul_f32_e64 v174, v174, v166
	v_mul_f32_e64 v175, v175, v167
	v_cvt_pk_bf16_f32 v166, v172, v173
	v_exp_f32_e32 v172, v134
	v_max_f32_e64 v134, -v87, -v87
	v_min_f32_e32 v134, 0x42a00000, v134
	v_mul_f32_e32 v134, 0x3fb8aa3b, v134
	v_exp_f32_e32 v173, v134
	v_max_f32_e64 v134, -v88, -v88
	v_min_f32_e32 v134, 0x42a00000, v134
	v_mul_f32_e32 v134, 0x3fb8aa3b, v134
	v_add_f32_e64 v172, v172, 1.0
	v_add_f32_e64 v173, v173, 1.0
	v_exp_f32_e32 v180, v134
	v_max_f32_e64 v134, -v89, -v89
	v_rcp_f32_e32 v178, v172
	v_rcp_f32_e32 v179, v173
	v_min_f32_e32 v134, 0x42a00000, v134
	v_mul_f32_e32 v134, 0x3fb8aa3b, v134
	v_exp_f32_e32 v181, v134
	v_cvt_pk_bf16_f32 v167, v174, v175
	v_lshlrev_b32_e32 v174, 16, v168
	v_and_b32_e32 v175, 0xffff0000, v168
	v_fma_f32 v172, -v172, v178, 1.0
	v_fma_f32 v173, -v173, v179, 1.0
	v_mul_f32_e64 v174, v94, v174
	v_mul_f32_e64 v175, v95, v175
	v_fma_f32 v172, v178, v172, v178
	v_fma_f32 v173, v179, v173, v179
	v_lshlrev_b32_e32 v168, 16, v169
	v_mul_f32_e64 v172, v172, v174
	v_mul_f32_e64 v173, v173, v175
	v_add_f32_e64 v174, v180, 1.0
	v_add_f32_e64 v175, v181, 1.0
	v_and_b32_e32 v169, 0xffff0000, v169
	v_rcp_f32_e32 v178, v174
	v_rcp_f32_e32 v179, v175
	v_mul_f32_e64 v168, v96, v168
	v_mul_f32_e64 v169, v97, v169
	v_max_f32_e64 v134, -v98, -v98
	v_min_f32_e32 v134, 0x42a00000, v134
	v_fma_f32 v174, -v174, v178, 1.0
	v_fma_f32 v175, -v175, v179, 1.0
	v_mul_f32_e32 v134, 0x3fb8aa3b, v134
	v_fma_f32 v174, v178, v174, v178
	v_fma_f32 v175, v179, v175, v179
	s_nop 0
	v_mul_f32_e64 v174, v174, v168
	v_mul_f32_e64 v175, v175, v169
	v_cvt_pk_bf16_f32 v168, v172, v173
	v_cvt_pk_bf16_f32 v169, v174, v175
	v_or_b32_e32 v172, 48, v144
	global_store_dwordx4 v[170:171], v[166:169], off
	v_exp_f32_e32 v170, v134
	v_max_f32_e64 v134, -v99, -v99
	v_mad_i64_i32 v[166:167], s[26:27], v172, s50, v[146:147]
	v_lshl_add_u64 v[166:167], v[166:167], 0, v[142:143]
	global_load_dwordx4 v[166:169], v[166:167], off offset:2048
	v_min_f32_e32 v134, 0x42a00000, v134
	v_mul_f32_e32 v134, 0x3fb8aa3b, v134
	v_exp_f32_e32 v171, v134
	v_max_f32_e64 v134, -v100, -v100
	v_min_f32_e32 v134, 0x42a00000, v134
	v_mul_f32_e32 v134, 0x3fb8aa3b, v134
	v_add_f32_e64 v170, v170, 1.0
	v_add_f32_e64 v171, v171, 1.0
	v_exp_f32_e32 v180, v134
	v_max_f32_e64 v134, -v101, -v101
	v_rcp_f32_e32 v178, v170
	v_rcp_f32_e32 v179, v171
	v_min_f32_e32 v134, 0x42a00000, v134
	v_mul_f32_e32 v134, 0x3fb8aa3b, v134
	v_exp_f32_e32 v181, v134
	s_waitcnt vmcnt(2)
	v_lshlrev_b32_e32 v174, 16, v162
	v_and_b32_e32 v175, 0xffff0000, v162
	v_fma_f32 v170, -v170, v178, 1.0
	v_fma_f32 v171, -v171, v179, 1.0
	v_mul_f32_e64 v174, v106, v174
	v_mul_f32_e64 v175, v107, v175
	v_fma_f32 v170, v178, v170, v178
	v_fma_f32 v171, v179, v171, v179
	v_max_f32_e64 v134, -v74, -v74
	v_mul_f32_e64 v170, v170, v174
	v_mul_f32_e64 v171, v171, v175
	v_add_f32_e64 v174, v180, 1.0
	v_add_f32_e64 v175, v181, 1.0
	v_lshlrev_b32_e32 v162, 16, v163
	v_rcp_f32_e32 v178, v174
	v_rcp_f32_e32 v179, v175
	v_and_b32_e32 v163, 0xffff0000, v163
	v_min_f32_e32 v134, 0x42a00000, v134
	v_mul_f32_e64 v162, v108, v162
	v_mul_f32_e64 v163, v109, v163
	v_fma_f32 v174, -v174, v178, 1.0
	v_fma_f32 v175, -v175, v179, 1.0
	v_mul_f32_e32 v134, 0x3fb8aa3b, v134
	v_fma_f32 v174, v178, v174, v178
	v_fma_f32 v175, v179, v175, v179
	v_ashrrev_i32_e32 v173, 31, v172
	v_mul_f32_e64 v174, v174, v162
	v_mul_f32_e64 v175, v175, v163
	v_cvt_pk_bf16_f32 v162, v170, v171
	v_exp_f32_e32 v170, v134
	v_max_f32_e64 v134, -v75, -v75
	v_min_f32_e32 v134, 0x42a00000, v134
	v_mul_f32_e32 v134, 0x3fb8aa3b, v134
	v_exp_f32_e32 v171, v134
	v_max_f32_e64 v134, -v76, -v76
	v_min_f32_e32 v134, 0x42a00000, v134
	v_mul_f32_e32 v134, 0x3fb8aa3b, v134
	v_add_f32_e64 v170, v170, 1.0
	v_add_f32_e64 v171, v171, 1.0
	v_exp_f32_e32 v180, v134
	v_max_f32_e64 v134, -v77, -v77
	v_rcp_f32_e32 v178, v170
	v_rcp_f32_e32 v179, v171
	v_min_f32_e32 v134, 0x42a00000, v134
	v_mul_f32_e32 v134, 0x3fb8aa3b, v134
	v_exp_f32_e32 v181, v134
	v_cvt_pk_bf16_f32 v163, v174, v175
	v_lshlrev_b32_e32 v174, 16, v164
	v_and_b32_e32 v175, 0xffff0000, v164
	v_fma_f32 v170, -v170, v178, 1.0
	v_fma_f32 v171, -v171, v179, 1.0
	v_mul_f32_e64 v174, v78, v174
	v_mul_f32_e64 v175, v79, v175
	v_fma_f32 v170, v178, v170, v178
	v_fma_f32 v171, v179, v171, v179
	v_lshlrev_b32_e32 v164, 16, v165
	v_mul_f32_e64 v170, v170, v174
	v_mul_f32_e64 v171, v171, v175
	v_add_f32_e64 v174, v180, 1.0
	v_add_f32_e64 v175, v181, 1.0
	v_and_b32_e32 v165, 0xffff0000, v165
	v_rcp_f32_e32 v178, v174
	v_rcp_f32_e32 v179, v175
	v_mul_f32_e64 v164, v80, v164
	v_mul_f32_e64 v165, v81, v165
	v_max_f32_e64 v134, -v82, -v82
	v_min_f32_e32 v134, 0x42a00000, v134
	v_fma_f32 v174, -v174, v178, 1.0
	v_fma_f32 v175, -v175, v179, 1.0
	v_mul_f32_e32 v134, 0x3fb8aa3b, v134
	v_fma_f32 v174, v178, v174, v178
	v_fma_f32 v175, v179, v175, v179
	s_nop 0
	v_mul_f32_e64 v174, v174, v164
	v_mul_f32_e64 v175, v175, v165
	v_cvt_pk_bf16_f32 v164, v170, v171
	v_lshlrev_b64 v[170:171], 11, v[176:177]
	v_cvt_pk_bf16_f32 v165, v174, v175
	v_lshl_add_u64 v[170:171], v[148:149], 0, v[170:171]
	global_store_dwordx4 v[170:171], v[162:165], off
	s_nop 1
	v_exp_f32_e32 v162, v134
	v_max_f32_e64 v134, -v83, -v83
	v_min_f32_e32 v134, 0x42a00000, v134
	v_mul_f32_e32 v134, 0x3fb8aa3b, v134
	v_exp_f32_e32 v163, v134
	v_max_f32_e64 v134, -v84, -v84
	v_min_f32_e32 v134, 0x42a00000, v134
	v_mul_f32_e32 v134, 0x3fb8aa3b, v134
	v_add_f32_e64 v162, v162, 1.0
	v_add_f32_e64 v163, v163, 1.0
	v_exp_f32_e32 v174, v134
	v_max_f32_e64 v134, -v85, -v85
	v_rcp_f32_e32 v170, v162
	v_rcp_f32_e32 v171, v163
	v_min_f32_e32 v134, 0x42a00000, v134
	v_mul_f32_e32 v134, 0x3fb8aa3b, v134
	v_exp_f32_e32 v175, v134
	s_waitcnt vmcnt(1)
; __device__ __forceinline__ u32x2 pk4(f32x4 v) { u32x2 r; r.x = pk2(v.x, v.y); r.y = pk2(v.z, v.w); return r; }
; __device__ __forceinline__ f32x4 unpk4(u32x2 w) { f32x4 r; r.x = bflo(w.x); r.y = bfhi(w.x); r.z = bflo(w.y); r.w = bfhi(w.y); return r; }
; __device__ __forceinline__ float rcp_nr(float d) { const float r = __builtin_amdgcn_rcpf(d); return fmaf(r, fmaf(-d, r, 1.f), r); }
; __device__ __forceinline__ float sigmoidf_(float x) { return rcp_nr(1.f + __expf(fminf(-x, 80.f))); }
; template <int EPI>
; __device__ __forceinline__ void epilogue(const Params& p, f32x4 (&acc)[2][2][4][2], const int pm, const int pn, const int wr, const int wc, const int fr, const int fq) {
;     ...
;       for (int m = 0; m < 4; ++m) {
;         const int row = pm * 256 + ai * 128 + wr * 64 + m * 16 + fr;
;         const int j0 = pn * 128 + wc * 32 + fq * 8;
;         const u32x4 gw4 = *(const u32x4*)(P + (size_t)row * PW + 1024 + j0);
;         u32x2 o[2];
; #pragma unroll
;         for (int bj = 0; bj < 2; ++bj) {
;           const f32x4 ya = acc[ai][bj][m][0], yb = acc[ai][bj][m][1];
;           const f32x4 gs = unpk4(bj == 0 ? u32x2{gw4.x, gw4.y} : u32x2{gw4.z, gw4.w});
;           f32x4 sv;
;           sv.x = gs.x * ya.x * sigmoidf_(yb.x); sv.y = gs.y * ya.y * sigmoidf_(yb.y);
;           sv.z = gs.z * ya.z * sigmoidf_(yb.z); sv.w = gs.w * ya.w * sigmoidf_(yb.w);
;           o[bj] = pk4(sv);
;         }
;         *(u32x4*)(Mg + (size_t)row * DM + j0) = u32x4{o[0].x, o[0].y, o[1].x, o[1].y};
	v_lshlrev_b32_e32 v164, 16, v166
	v_and_b32_e32 v165, 0xffff0000, v166
	v_fma_f32 v162, -v162, v170, 1.0
	v_fma_f32 v163, -v163, v171, 1.0
	v_mul_f32_e64 v164, v90, v164
	v_mul_f32_e64 v165, v91, v165
	v_fma_f32 v162, v170, v162, v170
	v_fma_f32 v163, v171, v163, v171
	v_max_f32_e64 v134, -v66, -v66
	v_mul_f32_e64 v162, v162, v164
	v_mul_f32_e64 v163, v163, v165
	v_add_f32_e64 v164, v174, 1.0
	v_add_f32_e64 v165, v175, 1.0
	v_lshlrev_b32_e32 v166, 16, v167
	v_rcp_f32_e32 v170, v164
	v_rcp_f32_e32 v171, v165
	v_and_b32_e32 v167, 0xffff0000, v167
	v_min_f32_e32 v134, 0x42a00000, v134
	v_mul_f32_e64 v166, v92, v166
	v_mul_f32_e64 v167, v93, v167
	v_fma_f32 v164, -v164, v170, 1.0
	v_fma_f32 v165, -v165, v171, 1.0
	v_mul_f32_e32 v134, 0x3fb8aa3b, v134
	v_fma_f32 v164, v170, v164, v170
	v_fma_f32 v165, v171, v165, v171
	v_cvt_pk_bf16_f32 v162, v162, v163
	v_mul_f32_e64 v164, v164, v166
	v_mul_f32_e64 v165, v165, v167
	v_exp_f32_e32 v166, v134
	v_max_f32_e64 v134, -v67, -v67
	v_min_f32_e32 v134, 0x42a00000, v134
	v_mul_f32_e32 v134, 0x3fb8aa3b, v134
	v_exp_f32_e32 v167, v134
	v_max_f32_e64 v134, -v68, -v68
	v_min_f32_e32 v134, 0x42a00000, v134
	v_mul_f32_e32 v134, 0x3fb8aa3b, v134
	v_add_f32_e64 v166, v166, 1.0
	v_add_f32_e64 v167, v167, 1.0
	v_exp_f32_e32 v174, v134
	v_max_f32_e64 v134, -v69, -v69
	v_rcp_f32_e32 v170, v166
	v_rcp_f32_e32 v171, v167
	v_min_f32_e32 v134, 0x42a00000, v134
	v_mul_f32_e32 v134, 0x3fb8aa3b, v134
	v_exp_f32_e32 v175, v134
	v_cvt_pk_bf16_f32 v163, v164, v165
	v_lshlrev_b32_e32 v164, 16, v168
	v_and_b32_e32 v165, 0xffff0000, v168
	v_fma_f32 v166, -v166, v170, 1.0
	v_fma_f32 v167, -v167, v171, 1.0
	v_mul_f32_e64 v164, v70, v164
	v_mul_f32_e64 v165, v71, v165
	v_fma_f32 v166, v170, v166, v170
	v_fma_f32 v167, v171, v167, v171
	v_lshlrev_b32_e32 v168, 16, v169
	v_mul_f32_e64 v164, v166, v164
	v_mul_f32_e64 v165, v167, v165
	v_add_f32_e64 v166, v174, 1.0
	v_add_f32_e64 v167, v175, 1.0
	v_and_b32_e32 v169, 0xffff0000, v169
	v_rcp_f32_e32 v170, v166
	v_rcp_f32_e32 v171, v167
	v_mul_f32_e64 v168, v72, v168
	v_mul_f32_e64 v169, v73, v169
	v_cvt_pk_bf16_f32 v164, v164, v165
	v_max_f32_e64 v134, -v58, -v58
	v_fma_f32 v166, -v166, v170, 1.0
	v_fma_f32 v167, -v167, v171, 1.0
	v_min_f32_e32 v134, 0x42a00000, v134
	v_fma_f32 v166, v170, v166, v170
	v_fma_f32 v167, v171, v167, v171
	v_mul_f32_e32 v134, 0x3fb8aa3b, v134
	v_mul_f32_e64 v166, v166, v168
	v_mul_f32_e64 v167, v167, v169
	v_exp_f32_e32 v168, v134
	v_cvt_pk_bf16_f32 v165, v166, v167
	v_lshlrev_b64 v[166:167], 11, v[172:173]
	v_lshl_add_u64 v[166:167], v[148:149], 0, v[166:167]
	global_store_dwordx4 v[166:167], v[162:165], off
	v_add_u32_e32 v166, 0x80, v144
	v_max_f32_e64 v134, -v59, -v59
	v_mad_i64_i32 v[162:163], s[26:27], v166, s50, v[146:147]
	v_lshl_add_u64 v[162:163], v[162:163], 0, v[142:143]
	global_load_dwordx4 v[162:165], v[162:163], off offset:2048
	v_min_f32_e32 v134, 0x42a00000, v134
	v_mul_f32_e32 v134, 0x3fb8aa3b, v134
	v_exp_f32_e32 v169, v134
	v_max_f32_e64 v134, -v60, -v60
	v_min_f32_e32 v134, 0x42a00000, v134
	v_mul_f32_e32 v134, 0x3fb8aa3b, v134
	v_add_f32_e64 v168, v168, 1.0
	v_add_f32_e64 v169, v169, 1.0
	v_exp_f32_e32 v174, v134
	v_max_f32_e64 v134, -v61, -v61
	v_rcp_f32_e32 v172, v168
	v_rcp_f32_e32 v173, v169
	v_min_f32_e32 v134, 0x42a00000, v134
	v_mul_f32_e32 v134, 0x3fb8aa3b, v134
	v_exp_f32_e32 v175, v134
	v_fma_f32 v168, -v168, v172, 1.0
	v_fma_f32 v169, -v169, v173, 1.0
	v_max_f32_e64 v134, -v38, -v38
	v_fma_f32 v168, v172, v168, v172
	v_fma_f32 v169, v173, v169, v173
	v_min_f32_e32 v134, 0x42a00000, v134
	v_mul_f32_e32 v134, 0x3fb8aa3b, v134
	v_ashrrev_i32_e32 v167, 31, v166
	v_lshlrev_b64 v[166:167], 11, v[166:167]
	v_lshl_add_u64 v[166:167], v[148:149], 0, v[166:167]
	s_waitcnt vmcnt(0)
	v_lshlrev_b32_e32 v170, 16, v162
	v_and_b32_e32 v171, 0xffff0000, v162
	v_mul_f32_e64 v170, v62, v170
	v_mul_f32_e64 v171, v63, v171
	v_lshlrev_b32_e32 v162, 16, v163
	v_mul_f32_e64 v168, v168, v170
	v_mul_f32_e64 v169, v169, v171
	v_add_f32_e64 v170, v174, 1.0
	v_add_f32_e64 v171, v175, 1.0
	v_and_b32_e32 v163, 0xffff0000, v163
	v_rcp_f32_e32 v172, v170
	v_rcp_f32_e32 v173, v171
	v_mul_f32_e64 v162, v64, v162
	v_mul_f32_e64 v163, v65, v163
	v_fma_f32 v170, -v170, v172, 1.0
	v_fma_f32 v171, -v171, v173, 1.0
	s_nop 0
	v_fma_f32 v170, v172, v170, v172
	v_fma_f32 v171, v173, v171, v173
	s_nop 0
	v_mul_f32_e64 v170, v170, v162
	v_mul_f32_e64 v171, v171, v163
	v_cvt_pk_bf16_f32 v162, v168, v169
	v_exp_f32_e32 v168, v134
	v_max_f32_e64 v134, -v39, -v39
	v_min_f32_e32 v134, 0x42a00000, v134
	v_mul_f32_e32 v134, 0x3fb8aa3b, v134
	v_exp_f32_e32 v169, v134
	v_max_f32_e64 v134, -v40, -v40
	v_min_f32_e32 v134, 0x42a00000, v134
	v_mul_f32_e32 v134, 0x3fb8aa3b, v134
	v_add_f32_e64 v168, v168, 1.0
	v_add_f32_e64 v169, v169, 1.0
	v_exp_f32_e32 v174, v134
	v_max_f32_e64 v134, -v41, -v41
	v_rcp_f32_e32 v172, v168
	v_rcp_f32_e32 v173, v169
	v_min_f32_e32 v134, 0x42a00000, v134
	v_mul_f32_e32 v134, 0x3fb8aa3b, v134
	v_exp_f32_e32 v175, v134
	v_cvt_pk_bf16_f32 v163, v170, v171
	v_lshlrev_b32_e32 v170, 16, v164
	v_and_b32_e32 v171, 0xffff0000, v164
	v_fma_f32 v168, -v168, v172, 1.0
	v_fma_f32 v169, -v169, v173, 1.0
	v_mul_f32_e64 v170, v46, v170
	v_mul_f32_e64 v171, v47, v171
	v_fma_f32 v168, v172, v168, v172
	v_fma_f32 v169, v173, v169, v173
	v_lshlrev_b32_e32 v164, 16, v165
	v_mul_f32_e64 v168, v168, v170
	v_mul_f32_e64 v169, v169, v171
	v_add_f32_e64 v170, v174, 1.0
	v_add_f32_e64 v171, v175, 1.0
	v_and_b32_e32 v165, 0xffff0000, v165
	v_rcp_f32_e32 v172, v170
	v_rcp_f32_e32 v173, v171
	v_mul_f32_e64 v164, v48, v164
	v_mul_f32_e64 v165, v49, v165
	v_max_f32_e64 v134, -v50, -v50
; __device__ __forceinline__ u32x2 pk4(f32x4 v) { u32x2 r; r.x = pk2(v.x, v.y); r.y = pk2(v.z, v.w); return r; }
; __device__ __forceinline__ f32x4 unpk4(u32x2 w) { f32x4 r; r.x = bflo(w.x); r.y = bfhi(w.x); r.z = bflo(w.y); r.w = bfhi(w.y); return r; }
; __device__ __forceinline__ float rcp_nr(float d) { const float r = __builtin_amdgcn_rcpf(d); return fmaf(r, fmaf(-d, r, 1.f), r); }
; __device__ __forceinline__ float sigmoidf_(float x) { return rcp_nr(1.f + __expf(fminf(-x, 80.f))); }
; template <int EPI>
; __device__ __forceinline__ void epilogue(const Params& p, f32x4 (&acc)[2][2][4][2], const int pm, const int pn, const int wr, const int wc, const int fr, const int fq) {
;     ...
;       for (int m = 0; m < 4; ++m) {
;         const int row = pm * 256 + ai * 128 + wr * 64 + m * 16 + fr;
;         const int j0 = pn * 128 + wc * 32 + fq * 8;
;         const u32x4 gw4 = *(const u32x4*)(P + (size_t)row * PW + 1024 + j0);
;         u32x2 o[2];
; #pragma unroll
;         for (int bj = 0; bj < 2; ++bj) {
;           const f32x4 ya = acc[ai][bj][m][0], yb = acc[ai][bj][m][1];
;           const f32x4 gs = unpk4(bj == 0 ? u32x2{gw4.x, gw4.y} : u32x2{gw4.z, gw4.w});
;           f32x4 sv;
;           sv.x = gs.x * ya.x * sigmoidf_(yb.x); sv.y = gs.y * ya.y * sigmoidf_(yb.y);
;           sv.z = gs.z * ya.z * sigmoidf_(yb.z); sv.w = gs.w * ya.w * sigmoidf_(yb.w);
;           o[bj] = pk4(sv);
;         }
;         *(u32x4*)(Mg + (size_t)row * DM + j0) = u32x4{o[0].x, o[0].y, o[1].x, o[1].y};
	v_min_f32_e32 v134, 0x42a00000, v134
	v_fma_f32 v170, -v170, v172, 1.0
	v_fma_f32 v171, -v171, v173, 1.0
	v_mul_f32_e32 v134, 0x3fb8aa3b, v134
	v_fma_f32 v170, v172, v170, v172
	v_fma_f32 v171, v173, v171, v173
	s_nop 0
	v_mul_f32_e64 v170, v170, v164
	v_mul_f32_e64 v171, v171, v165
	v_cvt_pk_bf16_f32 v164, v168, v169
	v_cvt_pk_bf16_f32 v165, v170, v171
	global_store_dwordx4 v[166:167], v[162:165], off
	v_add_u32_e32 v166, 0x90, v144
	v_exp_f32_e32 v168, v134
	v_mad_i64_i32 v[162:163], s[26:27], v166, s50, v[146:147]
	v_lshl_add_u64 v[162:163], v[162:163], 0, v[142:143]
	global_load_dwordx4 v[162:165], v[162:163], off offset:2048
	v_max_f32_e64 v134, -v51, -v51
	v_min_f32_e32 v134, 0x42a00000, v134
	v_mul_f32_e32 v134, 0x3fb8aa3b, v134
	v_exp_f32_e32 v169, v134
	v_max_f32_e64 v134, -v52, -v52
	v_min_f32_e32 v134, 0x42a00000, v134
	v_mul_f32_e32 v134, 0x3fb8aa3b, v134
	v_add_f32_e64 v168, v168, 1.0
	v_add_f32_e64 v169, v169, 1.0
	v_exp_f32_e32 v174, v134
	v_max_f32_e64 v134, -v53, -v53
	v_rcp_f32_e32 v172, v168
	v_rcp_f32_e32 v173, v169
	v_min_f32_e32 v134, 0x42a00000, v134
	v_mul_f32_e32 v134, 0x3fb8aa3b, v134
	v_exp_f32_e32 v175, v134
	v_fma_f32 v168, -v168, v172, 1.0
	v_fma_f32 v169, -v169, v173, 1.0
	v_max_f32_e64 v134, -v22, -v22
	v_fma_f32 v168, v172, v168, v172
	v_fma_f32 v169, v173, v169, v173
	v_min_f32_e32 v134, 0x42a00000, v134
	v_mul_f32_e32 v134, 0x3fb8aa3b, v134
	v_ashrrev_i32_e32 v167, 31, v166
	v_lshlrev_b64 v[166:167], 11, v[166:167]
	v_lshl_add_u64 v[166:167], v[148:149], 0, v[166:167]
	s_waitcnt vmcnt(0)
	v_lshlrev_b32_e32 v170, 16, v162
	v_and_b32_e32 v171, 0xffff0000, v162
	v_mul_f32_e64 v170, v54, v170
	v_mul_f32_e64 v171, v55, v171
	v_lshlrev_b32_e32 v162, 16, v163
	v_mul_f32_e64 v168, v168, v170
	v_mul_f32_e64 v169, v169, v171
	v_add_f32_e64 v170, v174, 1.0
	v_add_f32_e64 v171, v175, 1.0
	v_and_b32_e32 v163, 0xffff0000, v163
	v_rcp_f32_e32 v172, v170
	v_rcp_f32_e32 v173, v171
	v_mul_f32_e64 v162, v56, v162
	v_mul_f32_e64 v163, v57, v163
	v_fma_f32 v170, -v170, v172, 1.0
	v_fma_f32 v171, -v171, v173, 1.0
	s_nop 0
	v_fma_f32 v170, v172, v170, v172
	v_fma_f32 v171, v173, v171, v173
	s_nop 0
	v_mul_f32_e64 v170, v170, v162
	v_mul_f32_e64 v171, v171, v163
	v_cvt_pk_bf16_f32 v162, v168, v169
	v_exp_f32_e32 v168, v134
	v_max_f32_e64 v134, -v23, -v23
	v_min_f32_e32 v134, 0x42a00000, v134
	v_mul_f32_e32 v134, 0x3fb8aa3b, v134
	v_exp_f32_e32 v169, v134
	v_max_f32_e64 v134, -v24, -v24
	v_min_f32_e32 v134, 0x42a00000, v134
	v_mul_f32_e32 v134, 0x3fb8aa3b, v134
	v_add_f32_e64 v168, v168, 1.0
	v_add_f32_e64 v169, v169, 1.0
	v_exp_f32_e32 v174, v134
	v_max_f32_e64 v134, -v25, -v25
	v_rcp_f32_e32 v172, v168
	v_rcp_f32_e32 v173, v169
	v_min_f32_e32 v134, 0x42a00000, v134
	v_mul_f32_e32 v134, 0x3fb8aa3b, v134
	v_exp_f32_e32 v175, v134
	v_cvt_pk_bf16_f32 v163, v170, v171
	v_lshlrev_b32_e32 v170, 16, v164
	v_and_b32_e32 v171, 0xffff0000, v164
	v_fma_f32 v168, -v168, v172, 1.0
	v_fma_f32 v169, -v169, v173, 1.0
	v_mul_f32_e64 v170, v30, v170
	v_mul_f32_e64 v171, v31, v171
	v_fma_f32 v168, v172, v168, v172
	v_fma_f32 v169, v173, v169, v173
	v_lshlrev_b32_e32 v164, 16, v165
	v_mul_f32_e64 v168, v168, v170
	v_mul_f32_e64 v169, v169, v171
	v_add_f32_e64 v170, v174, 1.0
	v_add_f32_e64 v171, v175, 1.0
	v_and_b32_e32 v165, 0xffff0000, v165
	v_rcp_f32_e32 v172, v170
	v_rcp_f32_e32 v173, v171
	v_mul_f32_e64 v164, v32, v164
	v_mul_f32_e64 v165, v33, v165
	v_max_f32_e64 v134, -v34, -v34
	v_min_f32_e32 v134, 0x42a00000, v134
	v_fma_f32 v170, -v170, v172, 1.0
	v_fma_f32 v171, -v171, v173, 1.0
	v_mul_f32_e32 v134, 0x3fb8aa3b, v134
	v_fma_f32 v170, v172, v170, v172
	v_fma_f32 v171, v173, v171, v173
	s_nop 0
	v_mul_f32_e64 v170, v170, v164
	v_mul_f32_e64 v171, v171, v165
	v_cvt_pk_bf16_f32 v164, v168, v169
	v_cvt_pk_bf16_f32 v165, v170, v171
	global_store_dwordx4 v[166:167], v[162:165], off
	v_add_u32_e32 v166, 0xa0, v144
	v_exp_f32_e32 v168, v134
	v_mad_i64_i32 v[162:163], s[26:27], v166, s50, v[146:147]
	v_lshl_add_u64 v[162:163], v[162:163], 0, v[142:143]
	global_load_dwordx4 v[162:165], v[162:163], off offset:2048
	v_max_f32_e64 v134, -v35, -v35
	v_min_f32_e32 v134, 0x42a00000, v134
	v_mul_f32_e32 v134, 0x3fb8aa3b, v134
	v_exp_f32_e32 v169, v134
	v_max_f32_e64 v134, -v36, -v36
	v_min_f32_e32 v134, 0x42a00000, v134
	v_mul_f32_e32 v134, 0x3fb8aa3b, v134
	v_add_f32_e64 v168, v168, 1.0
	v_add_f32_e64 v169, v169, 1.0
	v_exp_f32_e32 v174, v134
	v_max_f32_e64 v134, -v37, -v37
	v_rcp_f32_e32 v172, v168
	v_rcp_f32_e32 v173, v169
	v_min_f32_e32 v134, 0x42a00000, v134
	v_mul_f32_e32 v134, 0x3fb8aa3b, v134
	v_exp_f32_e32 v175, v134
	v_fma_f32 v168, -v168, v172, 1.0
	v_fma_f32 v169, -v169, v173, 1.0
	v_max_f32_e64 v134, -v10, -v10
	v_fma_f32 v168, v172, v168, v172
	v_fma_f32 v169, v173, v169, v173
	v_min_f32_e32 v134, 0x42a00000, v134
	v_mul_f32_e32 v134, 0x3fb8aa3b, v134
	v_ashrrev_i32_e32 v167, 31, v166
	v_lshlrev_b64 v[166:167], 11, v[166:167]
	v_lshl_add_u64 v[166:167], v[148:149], 0, v[166:167]
	s_waitcnt vmcnt(0)
; __device__ __forceinline__ u32x2 pk4(f32x4 v) { u32x2 r; r.x = pk2(v.x, v.y); r.y = pk2(v.z, v.w); return r; }
; __device__ __forceinline__ f32x4 unpk4(u32x2 w) { f32x4 r; r.x = bflo(w.x); r.y = bfhi(w.x); r.z = bflo(w.y); r.w = bfhi(w.y); return r; }
; __device__ __forceinline__ float rcp_nr(float d) { const float r = __builtin_amdgcn_rcpf(d); return fmaf(r, fmaf(-d, r, 1.f), r); }
; __device__ __forceinline__ float sigmoidf_(float x) { return rcp_nr(1.f + __expf(fminf(-x, 80.f))); }
; template <int EPI>
; __device__ __forceinline__ void epilogue(const Params& p, f32x4 (&acc)[2][2][4][2], const int pm, const int pn, const int wr, const int wc, const int fr, const int fq) {
;     ...
;       for (int m = 0; m < 4; ++m) {
;         const int row = pm * 256 + ai * 128 + wr * 64 + m * 16 + fr;
;         const int j0 = pn * 128 + wc * 32 + fq * 8;
;         const u32x4 gw4 = *(const u32x4*)(P + (size_t)row * PW + 1024 + j0);
;         u32x2 o[2];
; #pragma unroll
;         for (int bj = 0; bj < 2; ++bj) {
;           const f32x4 ya = acc[ai][bj][m][0], yb = acc[ai][bj][m][1];
;           const f32x4 gs = unpk4(bj == 0 ? u32x2{gw4.x, gw4.y} : u32x2{gw4.z, gw4.w});
;           f32x4 sv;
;           sv.x = gs.x * ya.x * sigmoidf_(yb.x); sv.y = gs.y * ya.y * sigmoidf_(yb.y);
;           sv.z = gs.z * ya.z * sigmoidf_(yb.z); sv.w = gs.w * ya.w * sigmoidf_(yb.w);
;           o[bj] = pk4(sv);
;         }
;         *(u32x4*)(Mg + (size_t)row * DM + j0) = u32x4{o[0].x, o[0].y, o[1].x, o[1].y};
	v_lshlrev_b32_e32 v170, 16, v162
	v_and_b32_e32 v171, 0xffff0000, v162
	v_mul_f32_e64 v170, v42, v170
	v_mul_f32_e64 v171, v43, v171
	v_lshlrev_b32_e32 v162, 16, v163
	v_mul_f32_e64 v168, v168, v170
	v_mul_f32_e64 v169, v169, v171
	v_add_f32_e64 v170, v174, 1.0
	v_add_f32_e64 v171, v175, 1.0
	v_and_b32_e32 v163, 0xffff0000, v163
	v_rcp_f32_e32 v172, v170
	v_rcp_f32_e32 v173, v171
	v_mul_f32_e64 v162, v44, v162
	v_mul_f32_e64 v163, v45, v163
	v_fma_f32 v170, -v170, v172, 1.0
	v_fma_f32 v171, -v171, v173, 1.0
	s_nop 0
	v_fma_f32 v170, v172, v170, v172
	v_fma_f32 v171, v173, v171, v173
	s_nop 0
	v_mul_f32_e64 v170, v170, v162
	v_mul_f32_e64 v171, v171, v163
	v_cvt_pk_bf16_f32 v162, v168, v169
	v_exp_f32_e32 v168, v134
	v_max_f32_e64 v134, -v11, -v11
	v_min_f32_e32 v134, 0x42a00000, v134
	v_mul_f32_e32 v134, 0x3fb8aa3b, v134
	v_exp_f32_e32 v169, v134
	v_max_f32_e64 v134, -v12, -v12
	v_min_f32_e32 v134, 0x42a00000, v134
	v_mul_f32_e32 v134, 0x3fb8aa3b, v134
	v_add_f32_e64 v168, v168, 1.0
	v_add_f32_e64 v169, v169, 1.0
	v_exp_f32_e32 v174, v134
	v_max_f32_e64 v134, -v13, -v13
	v_rcp_f32_e32 v172, v168
	v_rcp_f32_e32 v173, v169
	v_min_f32_e32 v134, 0x42a00000, v134
	v_mul_f32_e32 v134, 0x3fb8aa3b, v134
	v_exp_f32_e32 v175, v134
	v_cvt_pk_bf16_f32 v163, v170, v171
	v_lshlrev_b32_e32 v170, 16, v164
	v_and_b32_e32 v171, 0xffff0000, v164
	v_fma_f32 v168, -v168, v172, 1.0
	v_fma_f32 v169, -v169, v173, 1.0
	v_mul_f32_e64 v170, v14, v170
	v_mul_f32_e64 v171, v15, v171
	v_fma_f32 v168, v172, v168, v172
	v_fma_f32 v169, v173, v169, v173
	v_lshlrev_b32_e32 v164, 16, v165
	v_mul_f32_e64 v168, v168, v170
	v_mul_f32_e64 v169, v169, v171
	v_add_f32_e64 v170, v174, 1.0
	v_add_f32_e64 v171, v175, 1.0
	v_and_b32_e32 v165, 0xffff0000, v165
	v_rcp_f32_e32 v172, v170
	v_rcp_f32_e32 v173, v171
	v_mul_f32_e64 v164, v16, v164
	v_mul_f32_e64 v165, v17, v165
	v_max_f32_e64 v134, -v18, -v18
	v_min_f32_e32 v134, 0x42a00000, v134
	v_fma_f32 v170, -v170, v172, 1.0
	v_fma_f32 v171, -v171, v173, 1.0
	v_mul_f32_e32 v134, 0x3fb8aa3b, v134
	v_fma_f32 v170, v172, v170, v172
	v_fma_f32 v171, v173, v171, v173
	s_nop 0
	v_mul_f32_e64 v170, v170, v164
	v_mul_f32_e64 v171, v171, v165
	v_cvt_pk_bf16_f32 v164, v168, v169
	v_cvt_pk_bf16_f32 v165, v170, v171
	global_store_dwordx4 v[166:167], v[162:165], off
	s_nop 1
	v_add_u32_e32 v162, 0xb0, v144
	v_mad_i64_i32 v[144:145], s[26:27], v162, s50, v[146:147]
	v_lshl_add_u64 v[142:143], v[144:145], 0, v[142:143]
	global_load_dwordx4 v[142:145], v[142:143], off offset:2048
	v_exp_f32_e32 v146, v134
	v_max_f32_e64 v134, -v19, -v19
	v_min_f32_e32 v134, 0x42a00000, v134
	v_mul_f32_e32 v134, 0x3fb8aa3b, v134
	v_exp_f32_e32 v147, v134
	v_max_f32_e64 v134, -v20, -v20
	v_min_f32_e32 v134, 0x42a00000, v134
	v_mul_f32_e32 v134, 0x3fb8aa3b, v134
	v_add_f32_e64 v146, v146, 1.0
	v_add_f32_e64 v147, v147, 1.0
	v_exp_f32_e32 v168, v134
	v_max_f32_e64 v134, -v21, -v21
	v_rcp_f32_e32 v166, v146
	v_rcp_f32_e32 v167, v147
	v_min_f32_e32 v134, 0x42a00000, v134
	v_mul_f32_e32 v134, 0x3fb8aa3b, v134
	v_exp_f32_e32 v169, v134
	v_fma_f32 v146, -v146, v166, 1.0
	v_fma_f32 v147, -v147, v167, 1.0
	v_max_f32_e64 v134, -v2, -v2
	v_fma_f32 v146, v166, v146, v166
	v_fma_f32 v147, v167, v147, v167
	v_min_f32_e32 v134, 0x42a00000, v134
	v_mul_f32_e32 v134, 0x3fb8aa3b, v134
	v_ashrrev_i32_e32 v163, 31, v162
	s_waitcnt vmcnt(0)
	v_lshlrev_b32_e32 v164, 16, v142
	v_and_b32_e32 v165, 0xffff0000, v142
	v_mul_f32_e64 v164, v26, v164
	v_mul_f32_e64 v165, v27, v165
	v_lshlrev_b32_e32 v142, 16, v143
	v_mul_f32_e64 v146, v146, v164
	v_mul_f32_e64 v147, v147, v165
	v_add_f32_e64 v164, v168, 1.0
	v_add_f32_e64 v165, v169, 1.0
	v_and_b32_e32 v143, 0xffff0000, v143
	v_rcp_f32_e32 v166, v164
	v_rcp_f32_e32 v167, v165
	v_mul_f32_e64 v142, v28, v142
	v_mul_f32_e64 v143, v29, v143
	v_fma_f32 v164, -v164, v166, 1.0
	v_fma_f32 v165, -v165, v167, 1.0
	s_nop 0
	v_fma_f32 v164, v166, v164, v166
	v_fma_f32 v165, v167, v165, v167
	s_nop 0
	v_mul_f32_e64 v164, v164, v142
	v_mul_f32_e64 v165, v165, v143
	v_cvt_pk_bf16_f32 v142, v146, v147
	v_exp_f32_e32 v146, v134
	v_max_f32_e64 v134, -v3, -v3
	v_min_f32_e32 v134, 0x42a00000, v134
	v_mul_f32_e32 v134, 0x3fb8aa3b, v134
	v_exp_f32_e32 v147, v134
	v_max_f32_e64 v134, -v4, -v4
	v_min_f32_e32 v134, 0x42a00000, v134
	v_mul_f32_e32 v134, 0x3fb8aa3b, v134
	v_add_f32_e64 v146, v146, 1.0
	v_add_f32_e64 v147, v147, 1.0
	v_exp_f32_e32 v168, v134
	v_max_f32_e64 v134, -v5, -v5
	v_rcp_f32_e32 v166, v146
	v_rcp_f32_e32 v167, v147
	v_min_f32_e32 v134, 0x42a00000, v134
	v_mul_f32_e32 v134, 0x3fb8aa3b, v134
	v_exp_f32_e32 v169, v134
	v_cvt_pk_bf16_f32 v143, v164, v165
	v_lshlrev_b32_e32 v164, 16, v144
	v_and_b32_e32 v165, 0xffff0000, v144
	v_fma_f32 v146, -v146, v166, 1.0
	v_fma_f32 v147, -v147, v167, 1.0
	v_mul_f32_e64 v164, v6, v164
	v_mul_f32_e64 v165, v7, v165
	v_fma_f32 v146, v166, v146, v166
	v_fma_f32 v147, v167, v147, v167
	v_lshlrev_b32_e32 v144, 16, v145
	v_mul_f32_e64 v146, v146, v164
	v_mul_f32_e64 v147, v147, v165
	v_add_f32_e64 v164, v168, 1.0
	v_add_f32_e64 v165, v169, 1.0
	v_and_b32_e32 v145, 0xffff0000, v145
	v_rcp_f32_e32 v166, v164
	v_rcp_f32_e32 v167, v165
	v_mul_f32_e64 v144, v8, v144
	v_mul_f32_e64 v145, v9, v145
	v_fma_f32 v164, -v164, v166, 1.0
	v_fma_f32 v165, -v165, v167, 1.0
	s_nop 0
	v_fma_f32 v164, v166, v164, v166
	v_fma_f32 v165, v167, v165, v167
	s_nop 0
	v_mul_f32_e64 v164, v164, v144
	v_mul_f32_e64 v165, v165, v145
	v_cvt_pk_bf16_f32 v144, v146, v147
	v_lshlrev_b64 v[146:147], 11, v[162:163]
	v_cvt_pk_bf16_f32 v145, v164, v165
	v_lshl_add_u64 v[146:147], v[148:149], 0, v[146:147]
	global_store_dwordx4 v[146:147], v[142:145], off
	s_cbranch_execz .LBB0_660

; __device__ __forceinline__ u32x2 pk4(f32x4 v) { u32x2 r; r.x = pk2(v.x, v.y); r.y = pk2(v.z, v.w); return r; }
; __device__ __forceinline__ f32x4 unpk4(u32x2 w) { f32x4 r; r.x = bflo(w.x); r.y = bfhi(w.x); r.z = bflo(w.y); r.w = bfhi(w.y); return r; }
; template <int EPI>
; __device__ __forceinline__ void epilogue(const Params& p, f32x4 (&acc)[2][2][4][2], const int pm, const int pn, const int wr, const int wc, const int fr, const int fq) {
;     ...
;     for (int ai = 0; ai < 2; ++ai)
; #pragma unroll
;       for (int m = 0; m < 4; ++m) {
;         const int row = pm * 256 + ai * 128 + wr * 64 + m * 16 + fr;
; #pragma unroll
;         for (int bj = 0; bj < 2; ++bj) {
;           const int col = pn * 256 + bj * 128 + wc * 32 + fq * 8;
;           const u32x4 gw4 = *(const u32x4*)(P + (size_t)row * PW + 2048 + col);
;           const u32x4 sw4 = *(const u32x4*)(Mg + (size_t)row * DM + col);
;           const f32x4 ga0 = unpk4(u32x2{gw4.x, gw4.y}), ga1 = unpk4(u32x2{gw4.z, gw4.w});
;           const f32x4 s0 = unpk4(u32x2{sw4.x, sw4.y}), s1 = unpk4(u32x2{sw4.z, sw4.w});
;           f32x4 v0 = acc[ai][bj][m][0], v1 = acc[ai][bj][m][1];
;           v0.x = s0.x + ga0.x * v0.x; v0.y = s0.y + ga0.y * v0.y; v0.z = s0.z + ga0.z * v0.z; v0.w = s0.w + ga0.w * v0.w;
;           v1.x = s1.x + ga1.x * v1.x; v1.y = s1.y + ga1.y * v1.y; v1.z = s1.z + ga1.z * v1.z; v1.w = s1.w + ga1.w * v1.w;
;           const u32x2 lo = pk4(v0), hi = pk4(v1);
;           *(u32x4*)(Mg + (size_t)row * DM + col) = u32x4{lo.x, lo.y, hi.x, hi.y};
;         }
.LBB0_740:
	v_readlane_b32 s24, v244, 0
	v_lshl_add_u32 v144, s22, 8, v150
	v_readlane_b32 s26, v244, 2
	v_readlane_b32 s27, v244, 3
	v_lshl_or_b32 v148, s47, 8, v152
	v_readlane_b32 s25, v244, 1
	v_mov_b64_e32 v[146:147], s[26:27]
	v_ashrrev_i32_e32 v145, 31, v144
	v_ashrrev_i32_e32 v149, 31, v148
	v_mad_i64_i32 v[142:143], s[24:25], v144, s46, v[146:147]
	v_lshlrev_b64 v[160:161], 11, v[144:145]
	v_lshl_add_u64 v[164:165], v[142:143], 0, s[12:13]
	v_lshlrev_b64 v[142:143], 1, v[148:149]
	v_lshl_add_u64 v[160:161], s[10:11], 0, v[160:161]
	v_or_b32_e32 v148, 0x80, v148
	v_lshl_add_u64 v[156:157], v[164:165], 0, v[142:143]
	v_lshl_add_u64 v[172:173], v[160:161], 0, v[142:143]
	v_ashrrev_i32_e32 v149, 31, v148
	global_load_dwordx4 v[156:159], v[156:157], off
	v_lshlrev_b64 v[148:149], 1, v[148:149]
	global_load_dwordx4 v[160:163], v[172:173], off
	v_lshl_add_u64 v[164:165], v[164:165], 0, v[148:149]
	global_load_dwordx4 v[164:167], v[164:165], off
	s_nop 0
	global_load_dwordx4 v[168:171], v[172:173], off offset:256
	v_or_b32_e32 v174, 16, v144
	v_ashrrev_i32_e32 v175, 31, v174
	v_mad_i64_i32 v[176:177], s[24:25], v174, s46, v[146:147]
	v_lshlrev_b64 v[174:175], 11, v[174:175]
	v_lshl_add_u64 v[176:177], v[176:177], 0, s[12:13]
	v_lshl_add_u64 v[174:175], s[10:11], 0, v[174:175]
	v_lshl_add_u64 v[178:179], v[176:177], 0, v[142:143]
	v_lshl_add_u64 v[174:175], v[174:175], 0, v[142:143]
	v_lshl_add_u64 v[176:177], v[176:177], 0, v[148:149]
	s_andn2_b64 vcc, exec, s[0:1]
	s_mov_b64 s[0:1], -1
	s_waitcnt vmcnt(0)
	v_lshlrev_b32_e32 v180, 16, v156
	v_and_b32_e32 v181, 0xffff0000, v156
	v_lshlrev_b32_e32 v156, 16, v157
	v_and_b32_e32 v157, 0xffff0000, v157
	v_lshlrev_b32_e32 v188, 16, v158
	v_and_b32_e32 v189, 0xffff0000, v158
	v_lshlrev_b32_e32 v158, 16, v159
	v_and_b32_e32 v159, 0xffff0000, v159
	v_lshlrev_b32_e32 v190, 16, v160
	v_and_b32_e32 v191, 0xffff0000, v160
	v_lshlrev_b32_e32 v160, 16, v161
	v_and_b32_e32 v161, 0xffff0000, v161
	v_lshlrev_b32_e32 v192, 16, v162
	v_and_b32_e32 v193, 0xffff0000, v162
	v_lshlrev_b32_e32 v162, 16, v163
	v_and_b32_e32 v163, 0xffff0000, v163
	v_fma_f32 v128, v128, v156, v160
	v_fma_f32 v129, v129, v157, v161
	v_fma_f32 v156, v122, v188, v192
	v_fma_f32 v157, v123, v189, v193
	v_fma_f32 v158, v124, v158, v162
	v_fma_f32 v159, v125, v159, v163
	v_lshlrev_b32_e32 v194, 16, v164
	v_and_b32_e32 v195, 0xffff0000, v164
	v_lshlrev_b32_e32 v196, 16, v168
	v_and_b32_e32 v197, 0xffff0000, v168
	v_lshlrev_b32_e32 v164, 16, v165
	v_and_b32_e32 v165, 0xffff0000, v165
	v_lshlrev_b32_e32 v168, 16, v169
	v_and_b32_e32 v169, 0xffff0000, v169
	v_lshlrev_b32_e32 v198, 16, v166
	v_and_b32_e32 v199, 0xffff0000, v166
	v_lshlrev_b32_e32 v200, 16, v170
	v_fma_f32 v126, v126, v180, v190
	v_fma_f32 v127, v127, v181, v191
	v_cvt_pk_bf16_f32 v124, v156, v157
	v_cvt_pk_bf16_f32 v125, v158, v159
	v_and_b32_e32 v201, 0xffff0000, v170
	v_lshlrev_b32_e32 v156, 16, v167
	v_and_b32_e32 v157, 0xffff0000, v167
	v_lshlrev_b32_e32 v158, 16, v171
	v_and_b32_e32 v159, 0xffff0000, v171
	v_cvt_pk_bf16_f32 v122, v126, v127
	v_cvt_pk_bf16_f32 v123, v128, v129
	v_fma_f32 v118, v118, v194, v196
	v_fma_f32 v119, v119, v195, v197
	v_fma_f32 v120, v120, v164, v168
	v_fma_f32 v121, v121, v165, v169
	v_fma_f32 v160, v114, v198, v200
	v_fma_f32 v161, v115, v199, v201
	v_fma_f32 v156, v116, v156, v158
	v_fma_f32 v157, v117, v157, v159
	global_store_dwordx4 v[172:173], v[122:125], off
	v_cvt_pk_bf16_f32 v114, v118, v119
	v_cvt_pk_bf16_f32 v115, v120, v121
	v_cvt_pk_bf16_f32 v116, v160, v161
	v_cvt_pk_bf16_f32 v117, v156, v157
	global_load_dwordx4 v[122:125], v[178:179], off
	global_load_dwordx4 v[126:129], v[174:175], off
	v_or_b32_e32 v156, 32, v144
	global_store_dwordx4 v[172:173], v[114:117], off offset:256
	global_load_dwordx4 v[114:117], v[176:177], off
	s_nop 0
	global_load_dwordx4 v[118:121], v[174:175], off offset:256
	v_ashrrev_i32_e32 v157, 31, v156
	v_mad_i64_i32 v[158:159], s[24:25], v156, s46, v[146:147]
	v_lshlrev_b64 v[156:157], 11, v[156:157]
	v_lshl_add_u64 v[158:159], v[158:159], 0, s[12:13]
	v_lshl_add_u64 v[156:157], s[10:11], 0, v[156:157]
	v_lshl_add_u64 v[160:161], v[158:159], 0, v[142:143]
	v_lshl_add_u64 v[156:157], v[156:157], 0, v[142:143]
	v_lshl_add_u64 v[158:159], v[158:159], 0, v[148:149]
	s_waitcnt vmcnt(4)
	v_lshlrev_b32_e32 v162, 16, v122
	v_and_b32_e32 v163, 0xffff0000, v122
	s_waitcnt vmcnt(3)
	v_lshlrev_b32_e32 v164, 16, v126
	v_and_b32_e32 v165, 0xffff0000, v126
	v_lshlrev_b32_e32 v122, 16, v123
	v_and_b32_e32 v123, 0xffff0000, v123
	v_lshlrev_b32_e32 v126, 16, v127
	v_and_b32_e32 v127, 0xffff0000, v127
	v_lshlrev_b32_e32 v166, 16, v124
	v_and_b32_e32 v167, 0xffff0000, v124
	v_lshlrev_b32_e32 v168, 16, v128
	v_and_b32_e32 v169, 0xffff0000, v128
	v_lshlrev_b32_e32 v124, 16, v125
	v_and_b32_e32 v125, 0xffff0000, v125
	v_lshlrev_b32_e32 v128, 16, v129
	v_and_b32_e32 v129, 0xffff0000, v129
	s_waitcnt vmcnt(1)
	v_lshlrev_b32_e32 v170, 16, v114
	v_and_b32_e32 v171, 0xffff0000, v114
	s_waitcnt vmcnt(0)
; __device__ __forceinline__ u32x2 pk4(f32x4 v) { u32x2 r; r.x = pk2(v.x, v.y); r.y = pk2(v.z, v.w); return r; }
; __device__ __forceinline__ f32x4 unpk4(u32x2 w) { f32x4 r; r.x = bflo(w.x); r.y = bfhi(w.x); r.z = bflo(w.y); r.w = bfhi(w.y); return r; }
; template <int EPI>
; __device__ __forceinline__ void epilogue(const Params& p, f32x4 (&acc)[2][2][4][2], const int pm, const int pn, const int wr, const int wc, const int fr, const int fq) {
;     ...
;     for (int ai = 0; ai < 2; ++ai)
; #pragma unroll
;       for (int m = 0; m < 4; ++m) {
;         const int row = pm * 256 + ai * 128 + wr * 64 + m * 16 + fr;
; #pragma unroll
;         for (int bj = 0; bj < 2; ++bj) {
;           const int col = pn * 256 + bj * 128 + wc * 32 + fq * 8;
;           const u32x4 gw4 = *(const u32x4*)(P + (size_t)row * PW + 2048 + col);
;           const u32x4 sw4 = *(const u32x4*)(Mg + (size_t)row * DM + col);
;           const f32x4 ga0 = unpk4(u32x2{gw4.x, gw4.y}), ga1 = unpk4(u32x2{gw4.z, gw4.w});
;           const f32x4 s0 = unpk4(u32x2{sw4.x, sw4.y}), s1 = unpk4(u32x2{sw4.z, sw4.w});
;           f32x4 v0 = acc[ai][bj][m][0], v1 = acc[ai][bj][m][1];
;           v0.x = s0.x + ga0.x * v0.x; v0.y = s0.y + ga0.y * v0.y; v0.z = s0.z + ga0.z * v0.z; v0.w = s0.w + ga0.w * v0.w;
;           v1.x = s1.x + ga1.x * v1.x; v1.y = s1.y + ga1.y * v1.y; v1.z = s1.z + ga1.z * v1.z; v1.w = s1.w + ga1.w * v1.w;
;           const u32x2 lo = pk4(v0), hi = pk4(v1);
;           *(u32x4*)(Mg + (size_t)row * DM + col) = u32x4{lo.x, lo.y, hi.x, hi.y};
;         }
	v_lshlrev_b32_e32 v172, 16, v118
	v_and_b32_e32 v173, 0xffff0000, v118
	v_lshlrev_b32_e32 v114, 16, v115
	v_and_b32_e32 v115, 0xffff0000, v115
	v_lshlrev_b32_e32 v118, 16, v119
	v_and_b32_e32 v119, 0xffff0000, v119
	v_lshlrev_b32_e32 v176, 16, v116
	v_and_b32_e32 v177, 0xffff0000, v116
	v_lshlrev_b32_e32 v178, 16, v120
	v_fma_f32 v110, v110, v162, v164
	v_fma_f32 v111, v111, v163, v165
	v_fma_f32 v112, v112, v122, v126
	v_fma_f32 v113, v113, v123, v127
	v_fma_f32 v122, v106, v166, v168
	v_fma_f32 v123, v107, v167, v169
	v_fma_f32 v124, v108, v124, v128
	v_fma_f32 v125, v109, v125, v129
	v_and_b32_e32 v179, 0xffff0000, v120
	v_lshlrev_b32_e32 v116, 16, v117
	v_and_b32_e32 v117, 0xffff0000, v117
	v_lshlrev_b32_e32 v120, 16, v121
	v_and_b32_e32 v121, 0xffff0000, v121
	v_cvt_pk_bf16_f32 v106, v110, v111
	v_cvt_pk_bf16_f32 v107, v112, v113
	v_cvt_pk_bf16_f32 v108, v122, v123
	v_cvt_pk_bf16_f32 v109, v124, v125
	v_fma_f32 v102, v102, v170, v172
	v_fma_f32 v103, v103, v171, v173
	v_fma_f32 v104, v104, v114, v118
	v_fma_f32 v105, v105, v115, v119
	v_fma_f32 v114, v98, v176, v178
	v_fma_f32 v115, v99, v177, v179
	v_fma_f32 v116, v100, v116, v120
	v_fma_f32 v117, v101, v117, v121
	global_store_dwordx4 v[174:175], v[106:109], off
	v_cvt_pk_bf16_f32 v98, v102, v103
	v_cvt_pk_bf16_f32 v99, v104, v105
	v_cvt_pk_bf16_f32 v100, v114, v115
	v_cvt_pk_bf16_f32 v101, v116, v117
	global_load_dwordx4 v[106:109], v[160:161], off
	global_load_dwordx4 v[110:113], v[156:157], off
	v_or_b32_e32 v114, 48, v144
	global_store_dwordx4 v[174:175], v[98:101], off offset:256
	global_load_dwordx4 v[98:101], v[158:159], off
	s_nop 0
	global_load_dwordx4 v[102:105], v[156:157], off offset:256
	v_ashrrev_i32_e32 v115, 31, v114
	v_mad_i64_i32 v[116:117], s[24:25], v114, s46, v[146:147]
	v_lshlrev_b64 v[114:115], 11, v[114:115]
	v_lshl_add_u64 v[116:117], v[116:117], 0, s[12:13]
	v_lshl_add_u64 v[114:115], s[10:11], 0, v[114:115]
	v_lshl_add_u64 v[118:119], v[116:117], 0, v[142:143]
	v_lshl_add_u64 v[114:115], v[114:115], 0, v[142:143]
	v_lshl_add_u64 v[116:117], v[116:117], 0, v[148:149]
	s_waitcnt vmcnt(4)
	v_lshlrev_b32_e32 v120, 16, v106
	v_and_b32_e32 v121, 0xffff0000, v106
	s_waitcnt vmcnt(3)
	v_lshlrev_b32_e32 v122, 16, v110
	v_and_b32_e32 v123, 0xffff0000, v110
	v_lshlrev_b32_e32 v106, 16, v107
	v_and_b32_e32 v107, 0xffff0000, v107
	v_lshlrev_b32_e32 v110, 16, v111
	v_and_b32_e32 v111, 0xffff0000, v111
	v_lshlrev_b32_e32 v124, 16, v108
	v_and_b32_e32 v125, 0xffff0000, v108
	v_lshlrev_b32_e32 v126, 16, v112
	v_and_b32_e32 v127, 0xffff0000, v112
	v_lshlrev_b32_e32 v108, 16, v109
	v_and_b32_e32 v109, 0xffff0000, v109
	v_lshlrev_b32_e32 v112, 16, v113
	v_and_b32_e32 v113, 0xffff0000, v113
	s_waitcnt vmcnt(1)
	v_lshlrev_b32_e32 v128, 16, v98
	v_and_b32_e32 v129, 0xffff0000, v98
	s_waitcnt vmcnt(0)
	v_lshlrev_b32_e32 v158, 16, v102
	v_and_b32_e32 v159, 0xffff0000, v102
	v_lshlrev_b32_e32 v98, 16, v99
	v_and_b32_e32 v99, 0xffff0000, v99
	v_lshlrev_b32_e32 v102, 16, v103
	v_and_b32_e32 v103, 0xffff0000, v103
	v_lshlrev_b32_e32 v160, 16, v100
	v_and_b32_e32 v161, 0xffff0000, v100
	v_lshlrev_b32_e32 v162, 16, v104
	v_fma_f32 v94, v94, v120, v122
	v_fma_f32 v95, v95, v121, v123
	v_fma_f32 v96, v96, v106, v110
	v_fma_f32 v97, v97, v107, v111
	v_fma_f32 v106, v90, v124, v126
	v_fma_f32 v107, v91, v125, v127
	v_fma_f32 v108, v92, v108, v112
	v_fma_f32 v109, v93, v109, v113
	v_and_b32_e32 v163, 0xffff0000, v104
	v_lshlrev_b32_e32 v100, 16, v101
	v_and_b32_e32 v101, 0xffff0000, v101
	v_lshlrev_b32_e32 v104, 16, v105
	v_and_b32_e32 v105, 0xffff0000, v105
	v_cvt_pk_bf16_f32 v90, v94, v95
	v_cvt_pk_bf16_f32 v91, v96, v97
	v_cvt_pk_bf16_f32 v92, v106, v107
	v_cvt_pk_bf16_f32 v93, v108, v109
	v_fma_f32 v86, v86, v128, v158
	v_fma_f32 v87, v87, v129, v159
	v_fma_f32 v88, v88, v98, v102
	v_fma_f32 v89, v89, v99, v103
	v_fma_f32 v98, v82, v160, v162
	v_fma_f32 v99, v83, v161, v163
	v_fma_f32 v100, v84, v100, v104
	v_fma_f32 v101, v85, v101, v105
	global_store_dwordx4 v[156:157], v[90:93], off
	v_cvt_pk_bf16_f32 v82, v86, v87
	v_cvt_pk_bf16_f32 v83, v88, v89
	v_cvt_pk_bf16_f32 v84, v98, v99
	v_cvt_pk_bf16_f32 v85, v100, v101
	global_load_dwordx4 v[90:93], v[118:119], off
	global_load_dwordx4 v[94:97], v[114:115], off
	v_add_u32_e32 v98, 0x80, v144
	global_store_dwordx4 v[156:157], v[82:85], off offset:256
	global_load_dwordx4 v[82:85], v[116:117], off
	s_nop 0
	global_load_dwordx4 v[86:89], v[114:115], off offset:256
	v_ashrrev_i32_e32 v99, 31, v98
	v_mad_i64_i32 v[100:101], s[24:25], v98, s46, v[146:147]
	v_lshlrev_b64 v[98:99], 11, v[98:99]
	v_lshl_add_u64 v[100:101], v[100:101], 0, s[12:13]
	v_lshl_add_u64 v[98:99], s[10:11], 0, v[98:99]
	v_lshl_add_u64 v[102:103], v[100:101], 0, v[142:143]
	v_lshl_add_u64 v[98:99], v[98:99], 0, v[142:143]
	v_lshl_add_u64 v[100:101], v[100:101], 0, v[148:149]
	s_waitcnt vmcnt(4)
	v_lshlrev_b32_e32 v104, 16, v90
	v_and_b32_e32 v105, 0xffff0000, v90
	s_waitcnt vmcnt(3)
	v_lshlrev_b32_e32 v106, 16, v94
	v_and_b32_e32 v107, 0xffff0000, v94
	v_lshlrev_b32_e32 v90, 16, v91
	v_and_b32_e32 v91, 0xffff0000, v91
	v_lshlrev_b32_e32 v94, 16, v95
	v_and_b32_e32 v95, 0xffff0000, v95
	v_lshlrev_b32_e32 v108, 16, v92
	v_and_b32_e32 v109, 0xffff0000, v92
	v_lshlrev_b32_e32 v110, 16, v96
	v_and_b32_e32 v111, 0xffff0000, v96
	v_lshlrev_b32_e32 v92, 16, v93
	v_and_b32_e32 v93, 0xffff0000, v93
	v_lshlrev_b32_e32 v96, 16, v97
	v_and_b32_e32 v97, 0xffff0000, v97
	s_waitcnt vmcnt(1)
	v_lshlrev_b32_e32 v112, 16, v82
	v_and_b32_e32 v113, 0xffff0000, v82
	s_waitcnt vmcnt(0)
; __device__ __forceinline__ u32x2 pk4(f32x4 v) { u32x2 r; r.x = pk2(v.x, v.y); r.y = pk2(v.z, v.w); return r; }
; __device__ __forceinline__ f32x4 unpk4(u32x2 w) { f32x4 r; r.x = bflo(w.x); r.y = bfhi(w.x); r.z = bflo(w.y); r.w = bfhi(w.y); return r; }
; template <int EPI>
; __device__ __forceinline__ void epilogue(const Params& p, f32x4 (&acc)[2][2][4][2], const int pm, const int pn, const int wr, const int wc, const int fr, const int fq) {
;     ...
;     for (int ai = 0; ai < 2; ++ai)
; #pragma unroll
;       for (int m = 0; m < 4; ++m) {
;         const int row = pm * 256 + ai * 128 + wr * 64 + m * 16 + fr;
; #pragma unroll
;         for (int bj = 0; bj < 2; ++bj) {
;           const int col = pn * 256 + bj * 128 + wc * 32 + fq * 8;
;           const u32x4 gw4 = *(const u32x4*)(P + (size_t)row * PW + 2048 + col);
;           const u32x4 sw4 = *(const u32x4*)(Mg + (size_t)row * DM + col);
;           const f32x4 ga0 = unpk4(u32x2{gw4.x, gw4.y}), ga1 = unpk4(u32x2{gw4.z, gw4.w});
;           const f32x4 s0 = unpk4(u32x2{sw4.x, sw4.y}), s1 = unpk4(u32x2{sw4.z, sw4.w});
;           f32x4 v0 = acc[ai][bj][m][0], v1 = acc[ai][bj][m][1];
;           v0.x = s0.x + ga0.x * v0.x; v0.y = s0.y + ga0.y * v0.y; v0.z = s0.z + ga0.z * v0.z; v0.w = s0.w + ga0.w * v0.w;
;           v1.x = s1.x + ga1.x * v1.x; v1.y = s1.y + ga1.y * v1.y; v1.z = s1.z + ga1.z * v1.z; v1.w = s1.w + ga1.w * v1.w;
;           const u32x2 lo = pk4(v0), hi = pk4(v1);
;           *(u32x4*)(Mg + (size_t)row * DM + col) = u32x4{lo.x, lo.y, hi.x, hi.y};
;         }
	v_lshlrev_b32_e32 v116, 16, v86
	v_and_b32_e32 v117, 0xffff0000, v86
	v_lshlrev_b32_e32 v82, 16, v83
	v_and_b32_e32 v83, 0xffff0000, v83
	v_lshlrev_b32_e32 v86, 16, v87
	v_and_b32_e32 v87, 0xffff0000, v87
	v_lshlrev_b32_e32 v118, 16, v84
	v_and_b32_e32 v119, 0xffff0000, v84
	v_lshlrev_b32_e32 v120, 16, v88
	v_fma_f32 v78, v78, v104, v106
	v_fma_f32 v79, v79, v105, v107
	v_fma_f32 v80, v80, v90, v94
	v_fma_f32 v81, v81, v91, v95
	v_fma_f32 v90, v74, v108, v110
	v_fma_f32 v91, v75, v109, v111
	v_fma_f32 v92, v76, v92, v96
	v_fma_f32 v93, v77, v93, v97
	v_and_b32_e32 v121, 0xffff0000, v88
	v_lshlrev_b32_e32 v84, 16, v85
	v_and_b32_e32 v85, 0xffff0000, v85
	v_lshlrev_b32_e32 v88, 16, v89
	v_and_b32_e32 v89, 0xffff0000, v89
	v_cvt_pk_bf16_f32 v74, v78, v79
	v_cvt_pk_bf16_f32 v75, v80, v81
	v_cvt_pk_bf16_f32 v76, v90, v91
	v_cvt_pk_bf16_f32 v77, v92, v93
	v_fma_f32 v70, v70, v112, v116
	v_fma_f32 v71, v71, v113, v117
	v_fma_f32 v72, v72, v82, v86
	v_fma_f32 v73, v73, v83, v87
	v_fma_f32 v82, v66, v118, v120
	v_fma_f32 v83, v67, v119, v121
	v_fma_f32 v84, v68, v84, v88
	v_fma_f32 v85, v69, v85, v89
	global_store_dwordx4 v[114:115], v[74:77], off
	v_cvt_pk_bf16_f32 v66, v70, v71
	v_cvt_pk_bf16_f32 v67, v72, v73
	v_cvt_pk_bf16_f32 v68, v82, v83
	v_cvt_pk_bf16_f32 v69, v84, v85
	global_load_dwordx4 v[74:77], v[102:103], off
	global_load_dwordx4 v[78:81], v[98:99], off
	v_add_u32_e32 v82, 0x90, v144
	global_store_dwordx4 v[114:115], v[66:69], off offset:256
	global_load_dwordx4 v[66:69], v[100:101], off
	s_nop 0
	global_load_dwordx4 v[70:73], v[98:99], off offset:256
	v_ashrrev_i32_e32 v83, 31, v82
	v_mad_i64_i32 v[84:85], s[24:25], v82, s46, v[146:147]
	v_lshlrev_b64 v[82:83], 11, v[82:83]
	v_lshl_add_u64 v[84:85], v[84:85], 0, s[12:13]
	v_lshl_add_u64 v[82:83], s[10:11], 0, v[82:83]
	v_lshl_add_u64 v[86:87], v[84:85], 0, v[142:143]
	v_lshl_add_u64 v[82:83], v[82:83], 0, v[142:143]
	v_lshl_add_u64 v[84:85], v[84:85], 0, v[148:149]
	s_waitcnt vmcnt(4)
	v_lshlrev_b32_e32 v88, 16, v74
	v_and_b32_e32 v89, 0xffff0000, v74
	s_waitcnt vmcnt(3)
	v_lshlrev_b32_e32 v90, 16, v78
	v_and_b32_e32 v91, 0xffff0000, v78
	v_lshlrev_b32_e32 v74, 16, v75
	v_and_b32_e32 v75, 0xffff0000, v75
	v_lshlrev_b32_e32 v78, 16, v79
	v_and_b32_e32 v79, 0xffff0000, v79
	v_lshlrev_b32_e32 v92, 16, v76
	v_and_b32_e32 v93, 0xffff0000, v76
	v_lshlrev_b32_e32 v94, 16, v80
	v_and_b32_e32 v95, 0xffff0000, v80
	v_lshlrev_b32_e32 v76, 16, v77
	v_and_b32_e32 v77, 0xffff0000, v77
	v_lshlrev_b32_e32 v80, 16, v81
	v_and_b32_e32 v81, 0xffff0000, v81
	s_waitcnt vmcnt(1)
	v_lshlrev_b32_e32 v96, 16, v66
	v_and_b32_e32 v97, 0xffff0000, v66
	s_waitcnt vmcnt(0)
	v_lshlrev_b32_e32 v100, 16, v70
	v_and_b32_e32 v101, 0xffff0000, v70
	v_lshlrev_b32_e32 v66, 16, v67
	v_and_b32_e32 v67, 0xffff0000, v67
	v_lshlrev_b32_e32 v70, 16, v71
	v_and_b32_e32 v71, 0xffff0000, v71
	v_lshlrev_b32_e32 v102, 16, v68
	v_and_b32_e32 v103, 0xffff0000, v68
	v_lshlrev_b32_e32 v104, 16, v72
	v_fma_f32 v62, v62, v88, v90
	v_fma_f32 v63, v63, v89, v91
	v_fma_f32 v64, v64, v74, v78
	v_fma_f32 v65, v65, v75, v79
	v_fma_f32 v74, v58, v92, v94
	v_fma_f32 v75, v59, v93, v95
	v_fma_f32 v76, v60, v76, v80
	v_fma_f32 v77, v61, v77, v81
	v_and_b32_e32 v105, 0xffff0000, v72
	v_lshlrev_b32_e32 v68, 16, v69
	v_and_b32_e32 v69, 0xffff0000, v69
	v_lshlrev_b32_e32 v72, 16, v73
	v_and_b32_e32 v73, 0xffff0000, v73
	v_cvt_pk_bf16_f32 v58, v62, v63
	v_cvt_pk_bf16_f32 v59, v64, v65
	v_cvt_pk_bf16_f32 v60, v74, v75
	v_cvt_pk_bf16_f32 v61, v76, v77
	v_fma_f32 v54, v54, v96, v100
	v_fma_f32 v55, v55, v97, v101
	v_fma_f32 v56, v56, v66, v70
	v_fma_f32 v57, v57, v67, v71
	v_fma_f32 v66, v50, v102, v104
	v_fma_f32 v67, v51, v103, v105
	v_fma_f32 v68, v52, v68, v72
	v_fma_f32 v69, v53, v69, v73
	global_store_dwordx4 v[98:99], v[58:61], off
	v_cvt_pk_bf16_f32 v50, v54, v55
	v_cvt_pk_bf16_f32 v51, v56, v57
	v_cvt_pk_bf16_f32 v52, v66, v67
	v_cvt_pk_bf16_f32 v53, v68, v69
	global_load_dwordx4 v[58:61], v[86:87], off
	global_load_dwordx4 v[62:65], v[82:83], off
	v_add_u32_e32 v66, 0xa0, v144
	global_store_dwordx4 v[98:99], v[50:53], off offset:256
	global_load_dwordx4 v[50:53], v[84:85], off
	s_nop 0
	global_load_dwordx4 v[54:57], v[82:83], off offset:256
	v_ashrrev_i32_e32 v67, 31, v66
	v_mad_i64_i32 v[68:69], s[24:25], v66, s46, v[146:147]
	v_lshlrev_b64 v[66:67], 11, v[66:67]
	v_lshl_add_u64 v[68:69], v[68:69], 0, s[12:13]
	v_lshl_add_u64 v[66:67], s[10:11], 0, v[66:67]
	v_lshl_add_u64 v[70:71], v[68:69], 0, v[142:143]
	v_lshl_add_u64 v[66:67], v[66:67], 0, v[142:143]
	v_lshl_add_u64 v[68:69], v[68:69], 0, v[148:149]
	s_waitcnt vmcnt(4)
	v_lshlrev_b32_e32 v72, 16, v58
	v_and_b32_e32 v73, 0xffff0000, v58
	s_waitcnt vmcnt(3)
	v_lshlrev_b32_e32 v74, 16, v62
	v_and_b32_e32 v75, 0xffff0000, v62
	v_lshlrev_b32_e32 v58, 16, v59
	v_and_b32_e32 v59, 0xffff0000, v59
	v_lshlrev_b32_e32 v62, 16, v63
	v_and_b32_e32 v63, 0xffff0000, v63
	v_lshlrev_b32_e32 v76, 16, v60
	v_and_b32_e32 v77, 0xffff0000, v60
	v_lshlrev_b32_e32 v78, 16, v64
	v_and_b32_e32 v79, 0xffff0000, v64
	v_lshlrev_b32_e32 v60, 16, v61
	v_and_b32_e32 v61, 0xffff0000, v61
	v_lshlrev_b32_e32 v64, 16, v65
	v_and_b32_e32 v65, 0xffff0000, v65
	s_waitcnt vmcnt(1)
	v_lshlrev_b32_e32 v80, 16, v50
	v_and_b32_e32 v81, 0xffff0000, v50
	s_waitcnt vmcnt(0)
; __device__ __forceinline__ u32x2 pk4(f32x4 v) { u32x2 r; r.x = pk2(v.x, v.y); r.y = pk2(v.z, v.w); return r; }
; __device__ __forceinline__ f32x4 unpk4(u32x2 w) { f32x4 r; r.x = bflo(w.x); r.y = bfhi(w.x); r.z = bflo(w.y); r.w = bfhi(w.y); return r; }
; #define PG8_BAR __builtin_amdgcn_s_barrier()
; template <int EPI>
; __device__ __forceinline__ void epilogue(const Params& p, f32x4 (&acc)[2][2][4][2], const int pm, const int pn, const int wr, const int wc, const int fr, const int fq) {
;     ...
;     for (int ai = 0; ai < 2; ++ai)
; #pragma unroll
;       for (int m = 0; m < 4; ++m) {
;         const int row = pm * 256 + ai * 128 + wr * 64 + m * 16 + fr;
; #pragma unroll
;         for (int bj = 0; bj < 2; ++bj) {
;           const int col = pn * 256 + bj * 128 + wc * 32 + fq * 8;
;           const u32x4 gw4 = *(const u32x4*)(P + (size_t)row * PW + 2048 + col);
;           const u32x4 sw4 = *(const u32x4*)(Mg + (size_t)row * DM + col);
;           const f32x4 ga0 = unpk4(u32x2{gw4.x, gw4.y}), ga1 = unpk4(u32x2{gw4.z, gw4.w});
;           const f32x4 s0 = unpk4(u32x2{sw4.x, sw4.y}), s1 = unpk4(u32x2{sw4.z, sw4.w});
;           f32x4 v0 = acc[ai][bj][m][0], v1 = acc[ai][bj][m][1];
;           v0.x = s0.x + ga0.x * v0.x; v0.y = s0.y + ga0.y * v0.y; v0.z = s0.z + ga0.z * v0.z; v0.w = s0.w + ga0.w * v0.w;
;           v1.x = s1.x + ga1.x * v1.x; v1.y = s1.y + ga1.y * v1.y; v1.z = s1.z + ga1.z * v1.z; v1.w = s1.w + ga1.w * v1.w;
;           const u32x2 lo = pk4(v0), hi = pk4(v1);
;           *(u32x4*)(Mg + (size_t)row * DM + col) = u32x4{lo.x, lo.y, hi.x, hi.y};
;         }
; template <int EPI> ...
;     ...
;         if (!has_next) break;
; #pragma unroll
;         for (int a = 0; a < 2; ++a)
; #pragma unroll
;             for (int b = 0; b < 2; ++b)
; #pragma unroll
;                 for (int m = 0; m < 4; ++m)
; #pragma unroll
;                     for (int n = 0; n < 2; ++n) acc[a][b][m][n] = (f32x4){0.f, 0.f, 0.f, 0.f};
;         cur_pm = nxt_pm; cur_pn = nxt_pn; cur_k0 = nxt_k0; cur_nk = nxt_nk; cur_slice = nxt_slice; cur_src = nxt_src; cA = nA; cB = nB; ++ui;
;         if (wr == 1) PG8_BAR;
	v_lshlrev_b32_e32 v84, 16, v54
	v_and_b32_e32 v85, 0xffff0000, v54
	v_lshlrev_b32_e32 v50, 16, v51
	v_and_b32_e32 v51, 0xffff0000, v51
	v_lshlrev_b32_e32 v54, 16, v55
	v_and_b32_e32 v55, 0xffff0000, v55
	v_lshlrev_b32_e32 v86, 16, v52
	v_and_b32_e32 v87, 0xffff0000, v52
	v_lshlrev_b32_e32 v88, 16, v56
	v_fma_f32 v46, v46, v72, v74
	v_fma_f32 v47, v47, v73, v75
	v_fma_f32 v48, v48, v58, v62
	v_fma_f32 v49, v49, v59, v63
	v_fma_f32 v58, v42, v76, v78
	v_fma_f32 v59, v43, v77, v79
	v_fma_f32 v60, v44, v60, v64
	v_fma_f32 v61, v45, v61, v65
	v_and_b32_e32 v89, 0xffff0000, v56
	v_lshlrev_b32_e32 v52, 16, v53
	v_and_b32_e32 v53, 0xffff0000, v53
	v_lshlrev_b32_e32 v56, 16, v57
	v_and_b32_e32 v57, 0xffff0000, v57
	v_cvt_pk_bf16_f32 v42, v46, v47
	v_cvt_pk_bf16_f32 v43, v48, v49
	v_cvt_pk_bf16_f32 v44, v58, v59
	v_cvt_pk_bf16_f32 v45, v60, v61
	v_fma_f32 v38, v38, v80, v84
	v_fma_f32 v39, v39, v81, v85
	v_fma_f32 v40, v40, v50, v54
	v_fma_f32 v41, v41, v51, v55
	v_fma_f32 v50, v34, v86, v88
	v_fma_f32 v51, v35, v87, v89
	v_fma_f32 v52, v36, v52, v56
	v_fma_f32 v53, v37, v53, v57
	global_store_dwordx4 v[82:83], v[42:45], off
	v_cvt_pk_bf16_f32 v34, v38, v39
	v_cvt_pk_bf16_f32 v35, v40, v41
	v_cvt_pk_bf16_f32 v36, v50, v51
	v_cvt_pk_bf16_f32 v37, v52, v53
	global_load_dwordx4 v[42:45], v[70:71], off
	global_load_dwordx4 v[46:49], v[66:67], off
	v_add_u32_e32 v50, 0xb0, v144
	global_store_dwordx4 v[82:83], v[34:37], off offset:256
	global_load_dwordx4 v[34:37], v[68:69], off
	s_nop 0
	global_load_dwordx4 v[38:41], v[66:67], off offset:256
	v_ashrrev_i32_e32 v51, 31, v50
	v_mad_i64_i32 v[52:53], s[24:25], v50, s46, v[146:147]
	v_lshlrev_b64 v[50:51], 11, v[50:51]
	v_lshl_add_u64 v[52:53], v[52:53], 0, s[12:13]
	v_lshl_add_u64 v[50:51], s[10:11], 0, v[50:51]
	v_lshl_add_u64 v[54:55], v[52:53], 0, v[142:143]
	v_lshl_add_u64 v[50:51], v[50:51], 0, v[142:143]
	v_lshl_add_u64 v[52:53], v[52:53], 0, v[148:149]
	s_waitcnt vmcnt(4)
	v_lshlrev_b32_e32 v56, 16, v42
	v_and_b32_e32 v57, 0xffff0000, v42
	s_waitcnt vmcnt(3)
	v_lshlrev_b32_e32 v58, 16, v46
	v_and_b32_e32 v59, 0xffff0000, v46
	v_lshlrev_b32_e32 v42, 16, v43
	v_and_b32_e32 v43, 0xffff0000, v43
	v_lshlrev_b32_e32 v46, 16, v47
	v_and_b32_e32 v47, 0xffff0000, v47
	v_lshlrev_b32_e32 v60, 16, v44
	v_and_b32_e32 v61, 0xffff0000, v44
	v_lshlrev_b32_e32 v62, 16, v48
	v_and_b32_e32 v63, 0xffff0000, v48
	v_lshlrev_b32_e32 v44, 16, v45
	v_and_b32_e32 v45, 0xffff0000, v45
	v_lshlrev_b32_e32 v48, 16, v49
	v_and_b32_e32 v49, 0xffff0000, v49
	s_waitcnt vmcnt(1)
	v_lshlrev_b32_e32 v64, 16, v34
	v_and_b32_e32 v65, 0xffff0000, v34
	s_waitcnt vmcnt(0)
	v_lshlrev_b32_e32 v68, 16, v38
	v_and_b32_e32 v69, 0xffff0000, v38
	v_lshlrev_b32_e32 v34, 16, v35
	v_and_b32_e32 v35, 0xffff0000, v35
	v_lshlrev_b32_e32 v38, 16, v39
	v_and_b32_e32 v39, 0xffff0000, v39
	v_lshlrev_b32_e32 v70, 16, v36
	v_and_b32_e32 v71, 0xffff0000, v36
	v_lshlrev_b32_e32 v72, 16, v40
	v_fma_f32 v30, v30, v56, v58
	v_fma_f32 v31, v31, v57, v59
	v_fma_f32 v32, v32, v42, v46
	v_fma_f32 v33, v33, v43, v47
	v_fma_f32 v42, v26, v60, v62
	v_fma_f32 v43, v27, v61, v63
	v_fma_f32 v44, v28, v44, v48
	v_fma_f32 v45, v29, v45, v49
	v_and_b32_e32 v73, 0xffff0000, v40
	v_lshlrev_b32_e32 v36, 16, v37
	v_and_b32_e32 v37, 0xffff0000, v37
	v_lshlrev_b32_e32 v40, 16, v41
	v_and_b32_e32 v41, 0xffff0000, v41
	v_cvt_pk_bf16_f32 v26, v30, v31
	v_cvt_pk_bf16_f32 v27, v32, v33
	v_cvt_pk_bf16_f32 v28, v42, v43
	v_cvt_pk_bf16_f32 v29, v44, v45
	v_fma_f32 v22, v22, v64, v68
	v_fma_f32 v23, v23, v65, v69
	v_fma_f32 v24, v24, v34, v38
	v_fma_f32 v25, v25, v35, v39
	v_fma_f32 v34, v18, v70, v72
	v_fma_f32 v35, v19, v71, v73
	v_fma_f32 v36, v20, v36, v40
	v_fma_f32 v37, v21, v37, v41
	global_store_dwordx4 v[66:67], v[26:29], off
	v_cvt_pk_bf16_f32 v18, v22, v23
	v_cvt_pk_bf16_f32 v19, v24, v25
	v_cvt_pk_bf16_f32 v20, v34, v35
	v_cvt_pk_bf16_f32 v21, v36, v37
	global_load_dwordx4 v[26:29], v[54:55], off
	global_load_dwordx4 v[30:33], v[50:51], off
	s_waitcnt vmcnt(1)
	v_lshlrev_b32_e32 v34, 16, v26
	global_store_dwordx4 v[66:67], v[18:21], off offset:256
	global_load_dwordx4 v[18:21], v[52:53], off
	s_nop 0
	global_load_dwordx4 v[22:25], v[50:51], off offset:256
	v_and_b32_e32 v35, 0xffff0000, v26
	s_waitcnt vmcnt(3)
	v_lshlrev_b32_e32 v36, 16, v30
	v_and_b32_e32 v37, 0xffff0000, v30
	v_lshlrev_b32_e32 v26, 16, v27
	v_and_b32_e32 v27, 0xffff0000, v27
	v_lshlrev_b32_e32 v30, 16, v31
	v_and_b32_e32 v31, 0xffff0000, v31
	v_lshlrev_b32_e32 v38, 16, v28
	v_and_b32_e32 v39, 0xffff0000, v28
	v_lshlrev_b32_e32 v40, 16, v32
	v_and_b32_e32 v41, 0xffff0000, v32
	v_lshlrev_b32_e32 v28, 16, v29
	v_and_b32_e32 v29, 0xffff0000, v29
	v_lshlrev_b32_e32 v32, 16, v33
	v_and_b32_e32 v33, 0xffff0000, v33
	v_fma_f32 v14, v14, v34, v36
	v_fma_f32 v15, v15, v35, v37
	v_fma_f32 v16, v16, v26, v30
	v_fma_f32 v17, v17, v27, v31
	v_fma_f32 v10, v10, v38, v40
	v_fma_f32 v11, v11, v39, v41
	v_fma_f32 v12, v12, v28, v32
	v_fma_f32 v13, v13, v29, v33
	s_waitcnt vmcnt(1)
	v_lshlrev_b32_e32 v42, 16, v18
	v_and_b32_e32 v43, 0xffff0000, v18
	s_waitcnt vmcnt(0)
	v_lshlrev_b32_e32 v44, 16, v22
	v_and_b32_e32 v45, 0xffff0000, v22
	v_lshlrev_b32_e32 v18, 16, v19
	v_and_b32_e32 v19, 0xffff0000, v19
	v_lshlrev_b32_e32 v22, 16, v23
	v_and_b32_e32 v23, 0xffff0000, v23
	v_lshlrev_b32_e32 v46, 16, v20
	v_and_b32_e32 v47, 0xffff0000, v20
	v_lshlrev_b32_e32 v48, 16, v24
	v_and_b32_e32 v49, 0xffff0000, v24
	v_lshlrev_b32_e32 v20, 16, v21
	v_and_b32_e32 v21, 0xffff0000, v21
	v_lshlrev_b32_e32 v24, 16, v25
	v_and_b32_e32 v25, 0xffff0000, v25
	v_fma_f32 v6, v6, v42, v44
	v_fma_f32 v7, v7, v43, v45
	v_fma_f32 v8, v8, v18, v22
	v_fma_f32 v9, v9, v19, v23
	v_fma_f32 v18, v2, v46, v48
	v_fma_f32 v19, v3, v47, v49
	v_fma_f32 v20, v4, v20, v24
	v_fma_f32 v21, v5, v21, v25
	v_cvt_pk_bf16_f32 v2, v14, v15
	v_cvt_pk_bf16_f32 v3, v16, v17
	v_cvt_pk_bf16_f32 v4, v10, v11
	v_cvt_pk_bf16_f32 v5, v12, v13
	v_cvt_pk_bf16_f32 v6, v6, v7
	v_cvt_pk_bf16_f32 v7, v8, v9
	v_cvt_pk_bf16_f32 v8, v18, v19
	v_cvt_pk_bf16_f32 v9, v20, v21
	global_store_dwordx4 v[50:51], v[2:5], off
	global_store_dwordx4 v[50:51], v[6:9], off offset:256
	s_cbranch_vccnz .LBB0_729
	s_andn2_b64 vcc, exec, s[4:5]
	s_cbranch_vccnz .LBB0_728
	s_barrier
	s_branch .LBB0_728

; __device__ __forceinline__ float sigmoidf_(float x) { return rcp_nr(1.f + __expf(fminf(-x, 80.f))); }
; __device__ __forceinline__ u32x2 pk4(f32x4 v) { u32x2 r; r.x = pk2(v.x, v.y); r.y = pk2(v.z, v.w); return r; }
; __device__ __forceinline__ f32x4 unpk4(u32x2 w) { f32x4 r; r.x = bflo(w.x); r.y = bfhi(w.x); r.z = bflo(w.y); r.w = bfhi(w.y); return r; }
; __device__ __forceinline__ void sample_merge(const Params& p) {
;     ...
;   for (int i = blockIdx.x * NTHR + threadIdx.x; i < MS * (DM / 4); i += gridDim.x * NTHR) {
;     const int r = i >> 8, j = (i & 255) * 4;
;     const int tj = j >> 7, jl = j & 127, va = tj * 256 + ((jl >> 2) & 1) * 128 + (jl >> 5) * 32 + ((jl >> 3) & 3) * 4 + (jl & 3);
;     f32x4 ya = f32x4{0.f, 0.f, 0.f, 0.f}, yb = ya, at = ya;
; #pragma unroll
;     for (int q = 0; q < 4; ++q) {
;       ya += *(const f32x4*)(SLG + ((size_t)q * MS + r) * 2048 + va);
;       yb += *(const f32x4*)(SLG + ((size_t)q * MS + r) * 2048 + va + 16);
;       at += *(const f32x4*)(SLA + ((size_t)q * MS + r) * DM + j);
;     }
;     const size_t row = (size_t)MP + r;
;     const f32x4 gs = unpk4(*(const u32x2*)(P + row * PW + 1024 + j)), ga = unpk4(*(const u32x2*)(P + row * PW + 2048 + j));
;     f32x4 sv;
;     sv.x = gs.x * ya.x * sigmoidf_(yb.x); sv.y = gs.y * ya.y * sigmoidf_(yb.y); sv.z = gs.z * ya.z * sigmoidf_(yb.z); sv.w = gs.w * ya.w * sigmoidf_(yb.w);
;     sv = unpk4(pk4(sv));
;     sv.x += ga.x * at.x; sv.y += ga.y * at.y; sv.z += ga.z * at.z; sv.w += ga.w * at.w;
;     *(u32x2*)(Mg + row * DM + j) = pk4(sv);
;   }
.LBB0_746:
	v_and_b32_e32 v9, 0x3fc, v7
	v_ashrrev_i32_e32 v10, 8, v8
	v_and_b32_e32 v2, 0x80, v6
	v_lshrrev_b32_e32 v11, 1, v7
	v_lshlrev_b32_e32 v58, 1, v9
	v_and_b32_e32 v22, 12, v11
	v_and_or_b32 v2, v7, s15, v2
	v_ashrrev_i32_e32 v11, 31, v10
	v_add_u32_e32 v60, 0x4000, v10
	v_and_b32_e32 v23, 0x700, v58
	v_mov_b32_e32 v59, v3
	v_lshlrev_b64 v[12:13], 13, v[10:11]
	v_lshlrev_b64 v[18:19], 12, v[10:11]
	v_lshl_add_u64 v[14:15], v[10:11], 0, s[8:9]
	v_lshl_add_u64 v[16:17], v[10:11], 0, s[10:11]
	v_lshl_add_u64 v[10:11], v[10:11], 0, s[12:13]
	v_mad_i64_i32 v[20:21], s[24:25], v60, s16, v[4:5]
	v_or3_b32 v2, v2, v22, v23
	v_lshlrev_b64 v[22:23], 13, v[14:15]
	v_lshlrev_b64 v[24:25], 12, v[14:15]
	v_lshlrev_b64 v[14:15], 13, v[16:17]
	v_lshlrev_b64 v[30:31], 12, v[16:17]
	v_lshlrev_b64 v[16:17], 13, v[10:11]
	v_lshlrev_b64 v[34:35], 12, v[10:11]
	v_lshl_add_u64 v[10:11], v[20:21], 0, v[58:59]
	v_lshlrev_b32_e32 v2, 2, v2
	global_load_dwordx2 v[62:63], v[10:11], off offset:2048
	v_add_co_u32_e32 v10, vcc, s17, v10
	v_lshl_add_u64 v[20:21], s[20:21], 0, v[2:3]
	s_nop 0
	v_addc_co_u32_e32 v11, vcc, 0, v11, vcc
	v_lshlrev_b32_e32 v2, 2, v9
	v_lshl_add_u64 v[26:27], v[20:21], 0, v[12:13]
	global_load_dwordx2 v[64:65], v[10:11], off
	v_lshl_add_u64 v[36:37], s[4:5], 0, v[2:3]
	v_lshl_add_u64 v[38:39], v[20:21], 0, v[22:23]
	v_lshl_add_u64 v[28:29], v[20:21], 0, v[14:15]
	v_lshl_add_u64 v[50:51], v[20:21], 0, v[16:17]
	global_load_dwordx4 v[10:13], v[26:27], off
	global_load_dwordx4 v[14:17], v[26:27], off offset:64
	v_lshl_add_u64 v[40:41], v[36:37], 0, v[18:19]
	global_load_dwordx4 v[18:21], v[38:39], off offset:64
	v_lshl_add_u64 v[42:43], v[36:37], 0, v[24:25]
	global_load_dwordx4 v[22:25], v[28:29], off
	s_nop 0
	global_load_dwordx4 v[26:29], v[28:29], off offset:64
	v_lshl_add_u64 v[46:47], v[36:37], 0, v[30:31]
	global_load_dwordx4 v[30:33], v[50:51], off offset:64
	v_lshl_add_u64 v[54:55], v[36:37], 0, v[34:35]
	global_load_dwordx4 v[34:37], v[40:41], off
	s_nop 0
	global_load_dwordx4 v[38:41], v[38:39], off
	s_nop 0
	global_load_dwordx4 v[42:45], v[42:43], off
	s_nop 0
	global_load_dwordx4 v[46:49], v[46:47], off
	s_nop 0
	global_load_dwordx4 v[50:53], v[50:51], off
	s_nop 0
	global_load_dwordx4 v[54:57], v[54:55], off
	v_ashrrev_i32_e32 v61, 31, v60
	v_lshlrev_b64 v[60:61], 11, v[60:61]
	v_lshl_add_u64 v[60:61], s[22:23], 0, v[60:61]
	v_lshl_add_u64 v[58:59], v[60:61], 0, v[58:59]
	v_add_u32_e32 v8, s2, v8
	v_cmp_lt_i32_e32 vcc, s19, v8
	v_add_u32_e32 v6, s14, v6
	v_add_u32_e32 v7, s26, v7
	s_or_b64 s[6:7], vcc, s[6:7]
	s_waitcnt vmcnt(13)
	v_lshlrev_b32_e32 v60, 16, v62
	v_and_b32_e32 v61, 0xffff0000, v62
	v_lshlrev_b32_e32 v62, 16, v63
	v_and_b32_e32 v63, 0xffff0000, v63
	s_waitcnt vmcnt(12)
	v_lshlrev_b32_e32 v66, 16, v64
	v_and_b32_e32 v67, 0xffff0000, v64
	v_lshlrev_b32_e32 v64, 16, v65
	v_and_b32_e32 v65, 0xffff0000, v65
	s_waitcnt vmcnt(11)
	v_add_f32_e64 v12, v12, 0
	v_add_f32_e64 v13, v13, 0
	s_waitcnt vmcnt(10)
	v_add_f32_e64 v16, v16, 0
	v_add_f32_e64 v17, v17, 0
	v_add_f32_e64 v14, v14, 0
	v_add_f32_e64 v15, v15, 0
	s_waitcnt vmcnt(9)
	v_add_f32_e64 v16, v16, v20
	v_add_f32_e64 v17, v17, v21
	v_add_f32_e64 v14, v14, v18
	v_add_f32_e64 v15, v15, v19
	s_waitcnt vmcnt(7)
	v_add_f32_e64 v16, v16, v28
	v_add_f32_e64 v17, v17, v29
	v_add_f32_e64 v14, v14, v26
	v_add_f32_e64 v15, v15, v27
	s_waitcnt vmcnt(6)
	v_add_f32_e64 v16, v16, v32
	v_add_f32_e64 v17, v17, v33
	v_add_f32_e64 v14, v14, v30
	v_add_f32_e64 v15, v15, v31
	v_add_f32_e64 v10, v10, 0
	v_add_f32_e64 v11, v11, 0
	v_min_f32_e64 v2, -v14, s18
	v_min_f32_e64 v9, -v15, s18
	v_min_f32_e64 v14, -v16, s18
	v_min_f32_e64 v15, -v17, s18
	v_mul_f32_e32 v2, 0x3fb8aa3b, v2
	v_mul_f32_e32 v9, 0x3fb8aa3b, v9
	v_mul_f32_e32 v16, 0x3fb8aa3b, v14
	v_mul_f32_e32 v17, 0x3fb8aa3b, v15
	v_exp_f32_e32 v14, v2
	v_exp_f32_e32 v15, v9
	v_exp_f32_e32 v16, v16
	v_exp_f32_e32 v17, v17
	s_waitcnt vmcnt(4)
	v_add_f32_e64 v12, v12, v40
	v_add_f32_e64 v13, v13, v41
	v_add_f32_e64 v10, v10, v38
	v_add_f32_e64 v11, v11, v39
	v_add_f32_e64 v14, v14, 1.0
	v_add_f32_e64 v15, v15, 1.0
	v_add_f32_e64 v16, v16, 1.0
	v_add_f32_e64 v17, v17, 1.0
	v_add_f32_e64 v12, v12, v24
	v_add_f32_e64 v13, v13, v25
	v_add_f32_e64 v10, v10, v22
	v_add_f32_e64 v11, v11, v23
	v_rcp_f32_e32 v22, v14
	v_rcp_f32_e32 v23, v15
	v_rcp_f32_e32 v24, v16
	v_rcp_f32_e32 v25, v17
	s_waitcnt vmcnt(1)
	v_add_f32_e64 v12, v12, v52
	v_add_f32_e64 v13, v13, v53
	v_add_f32_e64 v10, v10, v50
	v_add_f32_e64 v11, v11, v51
	v_fma_f32 v14, -v14, v22, 1.0
	v_fma_f32 v15, -v15, v23, 1.0
	v_fma_f32 v16, -v16, v24, 1.0
	v_fma_f32 v17, -v17, v25, 1.0
	v_add_f32_e64 v36, v36, 0
	v_add_f32_e64 v37, v37, 0
	v_add_f32_e64 v34, v34, 0
	v_add_f32_e64 v35, v35, 0
	v_mul_f32_e64 v10, v10, v60
	v_mul_f32_e64 v11, v11, v61
	v_mul_f32_e64 v12, v12, v62
	v_mul_f32_e64 v13, v13, v63
	v_fma_f32 v14, v22, v14, v22
	v_fma_f32 v15, v23, v15, v23
	v_fma_f32 v16, v24, v16, v24
	v_fma_f32 v17, v25, v17, v25
	v_add_f32_e64 v18, v36, v44
	v_add_f32_e64 v19, v37, v45
	v_add_f32_e64 v20, v34, v42
	v_add_f32_e64 v21, v35, v43
	v_mul_f32_e64 v10, v10, v14
	v_mul_f32_e64 v11, v11, v15
	v_mul_f32_e64 v12, v12, v16
	v_mul_f32_e64 v13, v13, v17
	v_add_f32_e64 v18, v18, v48
	v_add_f32_e64 v19, v19, v49
	v_add_f32_e64 v20, v20, v46
	v_add_f32_e64 v21, v21, v47
	v_cvt_pk_bf16_f32 v2, v10, v11
	v_cvt_pk_bf16_f32 v9, v12, v13
	s_waitcnt vmcnt(0)
	v_add_f32_e64 v18, v18, v56
	v_add_f32_e64 v19, v19, v57
	v_add_f32_e64 v20, v20, v54
	v_add_f32_e64 v21, v21, v55
	v_lshlrev_b32_e32 v10, 16, v2
	v_and_b32_e32 v11, 0xffff0000, v2
	v_lshlrev_b32_e32 v12, 16, v9
	v_and_b32_e32 v13, 0xffff0000, v9
	v_fma_f32 v10, v20, v66, v10
	v_fma_f32 v11, v21, v67, v11
	v_fma_f32 v12, v18, v64, v12
	v_fma_f32 v13, v19, v65, v13
	v_cvt_pk_bf16_f32 v10, v10, v11
	v_cvt_pk_bf16_f32 v11, v12, v13
	global_store_dwordx2 v[58:59], v[10:11], off
	s_andn2_b64 exec, exec, s[6:7]
	s_cbranch_execnz .LBB0_746

; __device__ __forceinline__ u32x2 pk4(f32x4 v) { u32x2 r; r.x = pk2(v.x, v.y); r.y = pk2(v.z, v.w); return r; }
; __device__ __forceinline__ f32x4 unpk4(u32x2 w) { f32x4 r; r.x = bflo(w.x); r.y = bfhi(w.x); r.z = bflo(w.y); r.w = bfhi(w.y); return r; }
; template <int EPI>
; __device__ __forceinline__ void epilogue(const Params& p, f32x4 (&acc)[2][2][4][2], const int pm, const int pn, const int wr, const int wc, const int fr, const int fq) {
;     ...
;     const bf16_t* X1b = (const bf16_t*)(ws + OFF_X1B);
; #pragma unroll
;     for (int ai = 0; ai < 2; ++ai)
; #pragma unroll
;       for (int m = 0; m < 4; ++m) {
;         const int row = pm * 256 + ai * 128 + wr * 64 + m * 16 + fr;
; #pragma unroll
;         for (int bj = 0; bj < 2; ++bj) {
;           const int col = pn * 256 + bj * 128 + wc * 32 + fq * 8;
;           f32x4 x0, x1;
;           if constexpr (EPI == EPI_WO) { const float* xp = p.in[0] + (size_t)row * DM + col; x0 = *(const f32x4*)xp; x1 = *(const f32x4*)(xp + 4); }
;           else { const u32x4 xw = *(const u32x4*)(X1b + (size_t)row * DM + col); x0 = unpk4(u32x2{xw.x, xw.y}); x1 = unpk4(u32x2{xw.z, xw.w}); }
;           f32x4 v0 = acc[ai][bj][m][0], v1 = acc[ai][bj][m][1];
;           v0.x += ALPHA_F * x0.x; v0.y += ALPHA_F * x0.y; v0.z += ALPHA_F * x0.z; v0.w += ALPHA_F * x0.w;
;           v1.x += ALPHA_F * x1.x; v1.y += ALPHA_F * x1.y; v1.z += ALPHA_F * x1.z; v1.w += ALPHA_F * x1.w;
;           const u32x2 lo = pk4(v0), hi = pk4(v1);
;           *(u32x4*)((bf16_t*)(ws + (EPI == EPI_WO ? OFF_PRE1 : OFF_PRE2)) + (size_t)row * DM + col) = u32x4{lo.x, lo.y, hi.x, hi.y};
;         }
.LBB0_831:
	v_lshl_add_u32 v142, s4, 8, v148
	v_readlane_b32 s68, v244, 14
	v_lshl_or_b32 v144, s6, 8, v151
	v_ashrrev_i32_e32 v143, 31, v142
	v_readlane_b32 s69, v244, 15
	v_lshlrev_b64 v[146:147], 12, v[142:143]
	v_readlane_b32 s70, v244, 16
	v_readlane_b32 s71, v244, 17
	s_mov_b64 s[52:53], s[68:69]
	v_ashrrev_i32_e32 v145, 31, v144
	v_lshl_add_u64 v[156:157], s[52:53], 0, v[146:147]
	v_lshlrev_b64 v[146:147], 2, v[144:145]
	v_lshl_add_u64 v[164:165], v[156:157], 0, v[146:147]
	global_load_dwordx4 v[156:159], v[164:165], off
	global_load_dwordx4 v[160:163], v[164:165], off offset:16
	v_lshlrev_b64 v[166:167], 11, v[142:143]
	v_lshlrev_b64 v[144:145], 1, v[144:145]
	v_lshl_add_u64 v[166:167], s[96:97], 0, v[166:167]
	v_lshl_add_u64 v[166:167], v[166:167], 0, v[144:145]
	v_readlane_b32 s72, v244, 18
	v_readlane_b32 s73, v244, 19
	v_readlane_b32 s74, v244, 20
	v_readlane_b32 s75, v244, 21
	v_readlane_b32 s76, v244, 22
	v_readlane_b32 s77, v244, 23
	v_readlane_b32 s78, v244, 24
	v_readlane_b32 s79, v244, 25
	v_readlane_b32 s80, v244, 26
	v_readlane_b32 s81, v244, 27
	v_readlane_b32 s82, v244, 28
	v_readlane_b32 s83, v244, 29
	s_mov_b64 s[54:55], s[70:71]
	s_waitcnt vmcnt(0)
	v_fma_f32 v156, v156, s14, v126
	v_fma_f32 v157, v157, s14, v127
	v_fma_f32 v158, v158, s14, v128
	v_fma_f32 v159, v159, s14, v129
	v_fma_f32 v160, v160, s14, v122
	v_fma_f32 v161, v161, s14, v123
	v_fma_f32 v162, v162, s14, v124
	v_fma_f32 v163, v163, s14, v125
	v_cvt_pk_bf16_f32 v156, v156, v157
	v_cvt_pk_bf16_f32 v157, v158, v159
	v_cvt_pk_bf16_f32 v158, v160, v161
	v_cvt_pk_bf16_f32 v159, v162, v163
	global_store_dwordx4 v[166:167], v[156:159], off
	global_load_dwordx4 v[156:159], v[164:165], off offset:512
	s_nop 0
	global_load_dwordx4 v[160:163], v[164:165], off offset:528
	v_or_b32_e32 v164, 16, v142
	v_ashrrev_i32_e32 v165, 31, v164
	v_lshlrev_b64 v[168:169], 12, v[164:165]
	v_lshl_add_u64 v[168:169], s[52:53], 0, v[168:169]
	v_lshl_add_u64 v[168:169], v[168:169], 0, v[146:147]
	v_lshlrev_b64 v[164:165], 11, v[164:165]
	v_lshl_add_u64 v[164:165], s[96:97], 0, v[164:165]
	v_lshl_add_u64 v[164:165], v[164:165], 0, v[144:145]
	s_waitcnt vmcnt(1)
	v_fma_f32 v156, v156, s14, v110
	v_fma_f32 v157, v157, s14, v111
	v_fma_f32 v158, v158, s14, v112
	v_fma_f32 v159, v159, s14, v113
	s_waitcnt vmcnt(0)
	v_fma_f32 v160, v160, s14, v102
	v_fma_f32 v161, v161, s14, v103
	v_fma_f32 v162, v162, s14, v104
	v_fma_f32 v163, v163, s14, v105
	v_cvt_pk_bf16_f32 v156, v156, v157
	v_cvt_pk_bf16_f32 v157, v158, v159
	v_cvt_pk_bf16_f32 v158, v160, v161
	v_cvt_pk_bf16_f32 v159, v162, v163
	global_store_dwordx4 v[166:167], v[156:159], off offset:256
	global_load_dwordx4 v[156:159], v[168:169], off
	s_nop 0
	global_load_dwordx4 v[160:163], v[168:169], off offset:16
	v_or_b32_e32 v166, 32, v142
	v_ashrrev_i32_e32 v167, 31, v166
	s_waitcnt vmcnt(1)
	v_fma_f32 v156, v156, s14, v118
	v_fma_f32 v157, v157, s14, v119
	v_fma_f32 v158, v158, s14, v120
	v_fma_f32 v159, v159, s14, v121
	s_waitcnt vmcnt(0)
	v_fma_f32 v160, v160, s14, v114
	v_fma_f32 v161, v161, s14, v115
	v_fma_f32 v162, v162, s14, v116
	v_fma_f32 v163, v163, s14, v117
	v_cvt_pk_bf16_f32 v156, v156, v157
	v_cvt_pk_bf16_f32 v157, v158, v159
	v_cvt_pk_bf16_f32 v158, v160, v161
	v_cvt_pk_bf16_f32 v159, v162, v163
	global_store_dwordx4 v[164:165], v[156:159], off
	global_load_dwordx4 v[156:159], v[168:169], off offset:512
	s_nop 0
	global_load_dwordx4 v[160:163], v[168:169], off offset:528
	v_lshlrev_b64 v[168:169], 12, v[166:167]
	v_lshl_add_u64 v[168:169], s[52:53], 0, v[168:169]
	v_lshl_add_u64 v[168:169], v[168:169], 0, v[146:147]
	s_waitcnt vmcnt(1)
	v_fma_f32 v156, v156, s14, v94
	v_fma_f32 v157, v157, s14, v95
	v_fma_f32 v158, v158, s14, v96
	v_fma_f32 v159, v159, s14, v97
	s_waitcnt vmcnt(0)
	v_fma_f32 v160, v160, s14, v86
	v_fma_f32 v161, v161, s14, v87
	v_fma_f32 v162, v162, s14, v88
	v_fma_f32 v163, v163, s14, v89
	v_cvt_pk_bf16_f32 v156, v156, v157
	v_cvt_pk_bf16_f32 v157, v158, v159
	v_cvt_pk_bf16_f32 v158, v160, v161
	v_cvt_pk_bf16_f32 v159, v162, v163
	global_store_dwordx4 v[164:165], v[156:159], off offset:256
	global_load_dwordx4 v[156:159], v[168:169], off
	s_nop 0
	global_load_dwordx4 v[160:163], v[168:169], off offset:16
	v_lshlrev_b64 v[164:165], 11, v[166:167]
	v_lshl_add_u64 v[164:165], s[96:97], 0, v[164:165]
	v_lshl_add_u64 v[164:165], v[164:165], 0, v[144:145]
	v_or_b32_e32 v166, 48, v142
	v_ashrrev_i32_e32 v167, 31, v166
	s_waitcnt vmcnt(1)
	v_fma_f32 v156, v156, s14, v106
	v_fma_f32 v157, v157, s14, v107
	v_fma_f32 v158, v158, s14, v108
	v_fma_f32 v159, v159, s14, v109
	s_waitcnt vmcnt(0)
	v_fma_f32 v160, v160, s14, v98
	v_fma_f32 v161, v161, s14, v99
	v_fma_f32 v162, v162, s14, v100
	v_fma_f32 v163, v163, s14, v101
	v_cvt_pk_bf16_f32 v156, v156, v157
	v_cvt_pk_bf16_f32 v157, v158, v159
	v_cvt_pk_bf16_f32 v158, v160, v161
	v_cvt_pk_bf16_f32 v159, v162, v163
	global_store_dwordx4 v[164:165], v[156:159], off
	global_load_dwordx4 v[156:159], v[168:169], off offset:512
	s_nop 0
	global_load_dwordx4 v[160:163], v[168:169], off offset:528
	v_lshlrev_b64 v[168:169], 12, v[166:167]
	v_lshl_add_u64 v[168:169], s[52:53], 0, v[168:169]
	v_lshl_add_u64 v[168:169], v[168:169], 0, v[146:147]
	s_waitcnt vmcnt(1)
	v_fma_f32 v156, v156, s14, v78
	v_fma_f32 v157, v157, s14, v79
	v_fma_f32 v158, v158, s14, v80
	v_fma_f32 v159, v159, s14, v81
	s_waitcnt vmcnt(0)
; __device__ __forceinline__ u32x2 pk4(f32x4 v) { u32x2 r; r.x = pk2(v.x, v.y); r.y = pk2(v.z, v.w); return r; }
; __device__ __forceinline__ f32x4 unpk4(u32x2 w) { f32x4 r; r.x = bflo(w.x); r.y = bfhi(w.x); r.z = bflo(w.y); r.w = bfhi(w.y); return r; }
; template <int EPI>
; __device__ __forceinline__ void epilogue(const Params& p, f32x4 (&acc)[2][2][4][2], const int pm, const int pn, const int wr, const int wc, const int fr, const int fq) {
;     ...
;     const bf16_t* X1b = (const bf16_t*)(ws + OFF_X1B);
; #pragma unroll
;     for (int ai = 0; ai < 2; ++ai)
; #pragma unroll
;       for (int m = 0; m < 4; ++m) {
;         const int row = pm * 256 + ai * 128 + wr * 64 + m * 16 + fr;
; #pragma unroll
;         for (int bj = 0; bj < 2; ++bj) {
;           const int col = pn * 256 + bj * 128 + wc * 32 + fq * 8;
;           f32x4 x0, x1;
;           if constexpr (EPI == EPI_WO) { const float* xp = p.in[0] + (size_t)row * DM + col; x0 = *(const f32x4*)xp; x1 = *(const f32x4*)(xp + 4); }
;           else { const u32x4 xw = *(const u32x4*)(X1b + (size_t)row * DM + col); x0 = unpk4(u32x2{xw.x, xw.y}); x1 = unpk4(u32x2{xw.z, xw.w}); }
;           f32x4 v0 = acc[ai][bj][m][0], v1 = acc[ai][bj][m][1];
;           v0.x += ALPHA_F * x0.x; v0.y += ALPHA_F * x0.y; v0.z += ALPHA_F * x0.z; v0.w += ALPHA_F * x0.w;
;           v1.x += ALPHA_F * x1.x; v1.y += ALPHA_F * x1.y; v1.z += ALPHA_F * x1.z; v1.w += ALPHA_F * x1.w;
;           const u32x2 lo = pk4(v0), hi = pk4(v1);
;           *(u32x4*)((bf16_t*)(ws + (EPI == EPI_WO ? OFF_PRE1 : OFF_PRE2)) + (size_t)row * DM + col) = u32x4{lo.x, lo.y, hi.x, hi.y};
;         }
	v_fma_f32 v160, v160, s14, v74
	v_fma_f32 v161, v161, s14, v75
	v_fma_f32 v162, v162, s14, v76
	v_fma_f32 v163, v163, s14, v77
	v_cvt_pk_bf16_f32 v156, v156, v157
	v_cvt_pk_bf16_f32 v157, v158, v159
	v_cvt_pk_bf16_f32 v158, v160, v161
	v_cvt_pk_bf16_f32 v159, v162, v163
	global_store_dwordx4 v[164:165], v[156:159], off offset:256
	global_load_dwordx4 v[156:159], v[168:169], off
	s_nop 0
	global_load_dwordx4 v[160:163], v[168:169], off offset:16
	v_lshlrev_b64 v[164:165], 11, v[166:167]
	v_lshl_add_u64 v[164:165], s[96:97], 0, v[164:165]
	v_lshl_add_u64 v[164:165], v[164:165], 0, v[144:145]
	v_add_u32_e32 v166, 0x80, v142
	v_ashrrev_i32_e32 v167, 31, v166
	s_waitcnt vmcnt(1)
	v_fma_f32 v156, v156, s14, v90
	v_fma_f32 v157, v157, s14, v91
	v_fma_f32 v158, v158, s14, v92
	v_fma_f32 v159, v159, s14, v93
	s_waitcnt vmcnt(0)
	v_fma_f32 v160, v160, s14, v82
	v_fma_f32 v161, v161, s14, v83
	v_fma_f32 v162, v162, s14, v84
	v_fma_f32 v163, v163, s14, v85
	v_cvt_pk_bf16_f32 v156, v156, v157
	v_cvt_pk_bf16_f32 v157, v158, v159
	v_cvt_pk_bf16_f32 v158, v160, v161
	v_cvt_pk_bf16_f32 v159, v162, v163
	global_store_dwordx4 v[164:165], v[156:159], off
	global_load_dwordx4 v[156:159], v[168:169], off offset:512
	s_nop 0
	global_load_dwordx4 v[160:163], v[168:169], off offset:528
	v_lshlrev_b64 v[168:169], 12, v[166:167]
	v_lshl_add_u64 v[168:169], s[52:53], 0, v[168:169]
	v_lshl_add_u64 v[168:169], v[168:169], 0, v[146:147]
	s_waitcnt vmcnt(1)
	v_fma_f32 v156, v156, s14, v70
	v_fma_f32 v157, v157, s14, v71
	v_fma_f32 v158, v158, s14, v72
	v_fma_f32 v159, v159, s14, v73
	s_waitcnt vmcnt(0)
	v_fma_f32 v160, v160, s14, v66
	v_fma_f32 v161, v161, s14, v67
	v_fma_f32 v162, v162, s14, v68
	v_fma_f32 v163, v163, s14, v69
	v_cvt_pk_bf16_f32 v156, v156, v157
	v_cvt_pk_bf16_f32 v157, v158, v159
	v_cvt_pk_bf16_f32 v158, v160, v161
	v_cvt_pk_bf16_f32 v159, v162, v163
	global_store_dwordx4 v[164:165], v[156:159], off offset:256
	global_load_dwordx4 v[156:159], v[168:169], off
	s_nop 0
	global_load_dwordx4 v[160:163], v[168:169], off offset:16
	v_lshlrev_b64 v[164:165], 11, v[166:167]
	v_lshl_add_u64 v[164:165], s[96:97], 0, v[164:165]
	v_lshl_add_u64 v[164:165], v[164:165], 0, v[144:145]
	v_add_u32_e32 v166, 0x90, v142
	v_ashrrev_i32_e32 v167, 31, v166
	s_waitcnt vmcnt(1)
	v_fma_f32 v156, v156, s14, v62
	v_fma_f32 v157, v157, s14, v63
	v_fma_f32 v158, v158, s14, v64
	v_fma_f32 v159, v159, s14, v65
	s_waitcnt vmcnt(0)
	v_fma_f32 v160, v160, s14, v58
	v_fma_f32 v161, v161, s14, v59
	v_fma_f32 v162, v162, s14, v60
	v_fma_f32 v163, v163, s14, v61
	v_cvt_pk_bf16_f32 v156, v156, v157
	v_cvt_pk_bf16_f32 v157, v158, v159
	v_cvt_pk_bf16_f32 v158, v160, v161
	v_cvt_pk_bf16_f32 v159, v162, v163
	global_store_dwordx4 v[164:165], v[156:159], off
	global_load_dwordx4 v[156:159], v[168:169], off offset:512
	s_nop 0
	global_load_dwordx4 v[160:163], v[168:169], off offset:528
	v_lshlrev_b64 v[168:169], 12, v[166:167]
	v_lshl_add_u64 v[168:169], s[52:53], 0, v[168:169]
	v_lshl_add_u64 v[168:169], v[168:169], 0, v[146:147]
	s_waitcnt vmcnt(1)
	v_fma_f32 v156, v156, s14, v46
	v_fma_f32 v157, v157, s14, v47
	v_fma_f32 v158, v158, s14, v48
	v_fma_f32 v159, v159, s14, v49
	s_waitcnt vmcnt(0)
	v_fma_f32 v160, v160, s14, v38
	v_fma_f32 v161, v161, s14, v39
	v_fma_f32 v162, v162, s14, v40
	v_fma_f32 v163, v163, s14, v41
	v_cvt_pk_bf16_f32 v156, v156, v157
	v_cvt_pk_bf16_f32 v157, v158, v159
	v_cvt_pk_bf16_f32 v158, v160, v161
	v_cvt_pk_bf16_f32 v159, v162, v163
	global_store_dwordx4 v[164:165], v[156:159], off offset:256
	global_load_dwordx4 v[156:159], v[168:169], off
	s_nop 0
	global_load_dwordx4 v[160:163], v[168:169], off offset:16
	v_lshlrev_b64 v[164:165], 11, v[166:167]
	v_lshl_add_u64 v[164:165], s[96:97], 0, v[164:165]
	v_lshl_add_u64 v[164:165], v[164:165], 0, v[144:145]
	v_add_u32_e32 v166, 0xa0, v142
	v_ashrrev_i32_e32 v167, 31, v166
	v_add_u32_e32 v142, 0xb0, v142
	v_ashrrev_i32_e32 v143, 31, v142
	s_waitcnt vmcnt(1)
	v_fma_f32 v156, v156, s14, v54
	v_fma_f32 v157, v157, s14, v55
	v_fma_f32 v158, v158, s14, v56
	v_fma_f32 v159, v159, s14, v57
	s_waitcnt vmcnt(0)
; __device__ __forceinline__ u32x2 pk4(f32x4 v) { u32x2 r; r.x = pk2(v.x, v.y); r.y = pk2(v.z, v.w); return r; }
; __device__ __forceinline__ f32x4 unpk4(u32x2 w) { f32x4 r; r.x = bflo(w.x); r.y = bfhi(w.x); r.z = bflo(w.y); r.w = bfhi(w.y); return r; }
; template <int EPI>
; __device__ __forceinline__ void epilogue(const Params& p, f32x4 (&acc)[2][2][4][2], const int pm, const int pn, const int wr, const int wc, const int fr, const int fq) {
;     ...
;     const bf16_t* X1b = (const bf16_t*)(ws + OFF_X1B);
; #pragma unroll
;     for (int ai = 0; ai < 2; ++ai)
; #pragma unroll
;       for (int m = 0; m < 4; ++m) {
;         const int row = pm * 256 + ai * 128 + wr * 64 + m * 16 + fr;
; #pragma unroll
;         for (int bj = 0; bj < 2; ++bj) {
;           const int col = pn * 256 + bj * 128 + wc * 32 + fq * 8;
;           f32x4 x0, x1;
;           if constexpr (EPI == EPI_WO) { const float* xp = p.in[0] + (size_t)row * DM + col; x0 = *(const f32x4*)xp; x1 = *(const f32x4*)(xp + 4); }
;           else { const u32x4 xw = *(const u32x4*)(X1b + (size_t)row * DM + col); x0 = unpk4(u32x2{xw.x, xw.y}); x1 = unpk4(u32x2{xw.z, xw.w}); }
;           f32x4 v0 = acc[ai][bj][m][0], v1 = acc[ai][bj][m][1];
;           v0.x += ALPHA_F * x0.x; v0.y += ALPHA_F * x0.y; v0.z += ALPHA_F * x0.z; v0.w += ALPHA_F * x0.w;
;           v1.x += ALPHA_F * x1.x; v1.y += ALPHA_F * x1.y; v1.z += ALPHA_F * x1.z; v1.w += ALPHA_F * x1.w;
;           const u32x2 lo = pk4(v0), hi = pk4(v1);
;           *(u32x4*)((bf16_t*)(ws + (EPI == EPI_WO ? OFF_PRE1 : OFF_PRE2)) + (size_t)row * DM + col) = u32x4{lo.x, lo.y, hi.x, hi.y};
;         }
	v_fma_f32 v160, v160, s14, v50
	v_fma_f32 v161, v161, s14, v51
	v_fma_f32 v162, v162, s14, v52
	v_fma_f32 v163, v163, s14, v53
	v_cvt_pk_bf16_f32 v156, v156, v157
	v_cvt_pk_bf16_f32 v157, v158, v159
	v_cvt_pk_bf16_f32 v158, v160, v161
	v_cvt_pk_bf16_f32 v159, v162, v163
	global_store_dwordx4 v[164:165], v[156:159], off
	global_load_dwordx4 v[156:159], v[168:169], off offset:512
	s_nop 0
	global_load_dwordx4 v[160:163], v[168:169], off offset:528
	v_lshlrev_b64 v[168:169], 12, v[166:167]
	v_lshl_add_u64 v[168:169], s[52:53], 0, v[168:169]
	v_lshl_add_u64 v[168:169], v[168:169], 0, v[146:147]
	s_waitcnt vmcnt(1)
	v_fma_f32 v156, v156, s14, v30
	v_fma_f32 v157, v157, s14, v31
	v_fma_f32 v158, v158, s14, v32
	v_fma_f32 v159, v159, s14, v33
	s_waitcnt vmcnt(0)
	v_fma_f32 v160, v160, s14, v22
	v_fma_f32 v161, v161, s14, v23
	v_fma_f32 v162, v162, s14, v24
	v_fma_f32 v163, v163, s14, v25
	v_cvt_pk_bf16_f32 v156, v156, v157
	v_cvt_pk_bf16_f32 v157, v158, v159
	v_cvt_pk_bf16_f32 v158, v160, v161
	v_cvt_pk_bf16_f32 v159, v162, v163
	global_store_dwordx4 v[164:165], v[156:159], off offset:256
	global_load_dwordx4 v[156:159], v[168:169], off
	s_nop 0
	global_load_dwordx4 v[160:163], v[168:169], off offset:16
	v_lshlrev_b64 v[164:165], 11, v[166:167]
	v_lshl_add_u64 v[164:165], s[96:97], 0, v[164:165]
	v_lshl_add_u64 v[164:165], v[164:165], 0, v[144:145]
	v_lshlrev_b64 v[166:167], 12, v[142:143]
	v_lshl_add_u64 v[166:167], s[52:53], 0, v[166:167]
	v_lshl_add_u64 v[146:147], v[166:167], 0, v[146:147]
	v_lshlrev_b64 v[142:143], 11, v[142:143]
	v_lshl_add_u64 v[142:143], s[96:97], 0, v[142:143]
	s_waitcnt vmcnt(1)
	v_fma_f32 v156, v156, s14, v42
	v_fma_f32 v157, v157, s14, v43
	v_fma_f32 v158, v158, s14, v44
	v_fma_f32 v159, v159, s14, v45
	s_waitcnt vmcnt(0)
	v_fma_f32 v160, v160, s14, v34
	v_fma_f32 v161, v161, s14, v35
	v_fma_f32 v162, v162, s14, v36
	v_fma_f32 v163, v163, s14, v37
	v_cvt_pk_bf16_f32 v156, v156, v157
	v_cvt_pk_bf16_f32 v157, v158, v159
	v_cvt_pk_bf16_f32 v158, v160, v161
	v_cvt_pk_bf16_f32 v159, v162, v163
	global_store_dwordx4 v[164:165], v[156:159], off
	global_load_dwordx4 v[156:159], v[168:169], off offset:512
	s_nop 0
	global_load_dwordx4 v[160:163], v[168:169], off offset:528
	s_waitcnt vmcnt(1)
	v_fma_f32 v156, v156, s14, v14
	v_fma_f32 v157, v157, s14, v15
	v_fma_f32 v158, v158, s14, v16
	v_fma_f32 v159, v159, s14, v17
	s_waitcnt vmcnt(0)
	v_fma_f32 v160, v160, s14, v10
	v_fma_f32 v161, v161, s14, v11
	v_fma_f32 v162, v162, s14, v12
	v_fma_f32 v163, v163, s14, v13
	v_cvt_pk_bf16_f32 v156, v156, v157
	v_cvt_pk_bf16_f32 v157, v158, v159
	v_cvt_pk_bf16_f32 v158, v160, v161
	v_cvt_pk_bf16_f32 v159, v162, v163
	global_store_dwordx4 v[164:165], v[156:159], off offset:256
	global_load_dwordx4 v[156:159], v[146:147], off
	s_nop 0
	global_load_dwordx4 v[160:163], v[146:147], off offset:16
	v_lshl_add_u64 v[164:165], v[142:143], 0, v[144:145]
	s_waitcnt vmcnt(1)
	v_fma_f32 v142, v156, s14, v26
	v_fma_f32 v143, v157, s14, v27
	v_fma_f32 v144, v158, s14, v28
	v_fma_f32 v145, v159, s14, v29
	s_waitcnt vmcnt(0)
	v_fma_f32 v156, v160, s14, v18
	v_fma_f32 v157, v161, s14, v19
	v_fma_f32 v158, v162, s14, v20
	v_fma_f32 v159, v163, s14, v21
	v_cvt_pk_bf16_f32 v142, v142, v143
	v_cvt_pk_bf16_f32 v143, v144, v145
	v_cvt_pk_bf16_f32 v144, v156, v157
	v_cvt_pk_bf16_f32 v145, v158, v159
	global_store_dwordx4 v[164:165], v[142:145], off
	global_load_dwordx4 v[142:145], v[146:147], off offset:512
	s_nop 0
	global_load_dwordx4 v[156:159], v[146:147], off offset:528
	s_waitcnt vmcnt(1)
	v_fma_f32 v142, v142, s14, v6
	v_fma_f32 v143, v143, s14, v7
	v_fma_f32 v144, v144, s14, v8
	v_fma_f32 v145, v145, s14, v9
	s_waitcnt vmcnt(0)
	v_fma_f32 v146, v156, s14, v2
	v_fma_f32 v147, v157, s14, v3
	v_fma_f32 v156, v158, s14, v4
	v_fma_f32 v157, v159, s14, v5
	v_cvt_pk_bf16_f32 v142, v142, v143
	v_cvt_pk_bf16_f32 v143, v144, v145
	v_cvt_pk_bf16_f32 v144, v146, v147
	v_cvt_pk_bf16_f32 v145, v156, v157
	global_store_dwordx4 v[164:165], v[142:145], off offset:256
	s_cbranch_execz .LBB0_829

; __device__ __forceinline__ u32x2 pk4(f32x4 v) { u32x2 r; r.x = pk2(v.x, v.y); r.y = pk2(v.z, v.w); return r; }
; template <int EPI>
; __device__ __forceinline__ void epilogue(const Params& p, f32x4 (&acc)[2][2][4][2], const int pm, const int pn, const int wr, const int wc, const int fr, const int fq) {
;     ...
;           const int j0 = jb + bj * 4;
;           const f32x4 a0 = acc[ai][bj][m][0], g = acc[ai][bj][m][1];
;           f32x4 am1, am2;
;           if (prompt) {
;             f32x4 o1 = f32x4{0.f, 0.f, 0.f, 0.f}, o2 = o1;
;             if (m > 0) { o1 = ror1v(acc[ai][bj][m > 0 ? m - 1 : 0][0]); o2 = ror2v(acc[ai][bj][m > 0 ? m - 1 : 0][0]); }
;             am1 = shr1v(o1, a0); am2 = shr2v(o2, a0);
;             if (m == 0 && fr < 2 && (row & 2047) >= 2) defer = true;
;             if (m == 3 && fr >= 14) *(f32x4*)(HA1 + ((size_t)(rblk >> 6) * 2 + (fr - 14)) * DFF + j0) = a0;
;             const int pos = row & 2047;
;             if (pos >= 2046) *(f32x4*)(p.out + O_CP + ((size_t)(row >> 11) * 2 + (pos - 2046)) * DFF + j0) = a0;
;           } else {
;             const int sidx = row - MP, b = sidx >> 2, tt = sidx & 3;
;             const f32x4 st0 = *(const f32x4*)(p.in[6] + ((size_t)b * 2 + 0) * DFF + j0);
;             const f32x4 st1 = *(const f32x4*)(p.in[6] + ((size_t)b * 2 + 1) * DFF + j0);
;             const f32x4 s1 = ror1v(a0), s2 = ror2v(a0);
;             am1 = (tt >= 1) ? s1 : st1;
;             am2 = (tt >= 2) ? s2 : ((tt == 1) ? st1 : st0);
;             if (tt >= 2) *(f32x4*)(p.out + O_CS + ((size_t)b * 2 + (tt - 2)) * DFF + j0) = a0;
;           }
;           f32x4 h;
;           h.x = gelu_tanh(cb[bj].x + w0[bj].x * am2.x + w1[bj].x * am1.x + w2[bj].x * a0.x) * g.x;
;           h.y = gelu_tanh(cb[bj].y + w0[bj].y * am2.y + w1[bj].y * am1.y + w2[bj].y * a0.y) * g.y;
;           h.z = gelu_tanh(cb[bj].z + w0[bj].z * am2.z + w1[bj].z * am1.z + w2[bj].z * a0.z) * g.z;
;           h.w = gelu_tanh(cb[bj].w + w0[bj].w * am2.w + w1[bj].w * am1.w + w2[bj].w * a0.w) * g.w;
;           ho[bj] = pk4(h);
;           if (defer) {
;             *(f32x4*)(HA0 + ((size_t)(rblk >> 6) * 2 + fr) * DFF + j0) = a0;
;             *(f32x4*)(HG0 + ((size_t)(rblk >> 6) * 2 + fr) * DFF + j0) = g;
;           }
;         }
;         if (!defer) *(u32x4*)(H + (size_t)row * DFF + jb) = u32x4{ho[0].x, ho[0].y, ho[1].x, ho[1].y};
.LBB0_987:
	s_xor_b64 s[56:57], s[60:61], -1
	v_readlane_b32 s60, v244, 0
	v_readlane_b32 s62, v244, 2
	v_readlane_b32 s63, v244, 3
	v_readlane_b32 s61, v244, 1
	s_nop 0
	v_lshl_add_u64 v[178:179], v[214:215], 1, s[62:63]
	s_and_saveexec_b64 s[58:59], s[56:57]
	s_xor_b64 s[56:57], exec, s[58:59]
	s_cbranch_execz .LBB0_989
	s_waitcnt vmcnt(0)
	v_fma_f32 v162, v54, v162, v70
	v_fma_f32 v163, v55, v163, v71
	v_fma_f32 v164, v56, v164, v72
	v_fma_f32 v165, v57, v165, v73
	v_fma_f32 v162, v58, v166, v162
	v_fma_f32 v163, v59, v167, v163
	v_fma_f32 v164, v60, v168, v164
	v_fma_f32 v165, v61, v169, v165
	v_fma_f32 v162, v150, v66, v162
	v_fma_f32 v163, v151, v67, v163
	v_fma_f32 v164, v152, v68, v164
	v_fma_f32 v165, v153, v69, v165
	v_mul_f32_e32 v166, 0x3d372713, v162
	v_mul_f32_e32 v167, 0x3d372713, v163
	v_mul_f32_e32 v166, v162, v166
	v_mul_f32_e32 v167, v163, v167
	v_fma_f32 v166, v162, v166, v162
	v_fma_f32 v167, v163, v167, v163
	v_mul_f32_e32 v166, 0xbfcc422a, v166
	v_mul_f32_e32 v167, 0xbfcc422a, v167
	v_mul_f32_e32 v180, 0x3d372713, v164
	v_mul_f32_e32 v181, 0x3d372713, v165
	v_min_f32_e32 v166, 0x42a00000, v166
	v_min_f32_e32 v167, 0x42a00000, v167
	v_mul_f32_e32 v180, v164, v180
	v_mul_f32_e32 v181, v165, v181
	v_mul_f32_e32 v166, 0x3fb8aa3b, v166
	v_mul_f32_e32 v167, 0x3fb8aa3b, v167
	v_fma_f32 v180, v164, v180, v164
	v_fma_f32 v181, v165, v181, v165
	v_exp_f32_e32 v166, v166
	v_exp_f32_e32 v167, v167
	v_mul_f32_e32 v180, 0xbfcc422a, v180
	v_mul_f32_e32 v181, 0xbfcc422a, v181
	v_min_f32_e32 v180, 0x42a00000, v180
	v_min_f32_e32 v181, 0x42a00000, v181
	v_mul_f32_e32 v180, 0x3fb8aa3b, v180
	v_mul_f32_e32 v181, 0x3fb8aa3b, v181
	v_exp_f32_e32 v180, v180
	v_exp_f32_e32 v181, v181
	v_add_f32_e64 v166, v166, 1.0
	v_add_f32_e64 v167, v167, 1.0
	v_add_f32_e64 v180, v180, 1.0
	v_add_f32_e64 v181, v181, 1.0
	v_rcp_f32_e32 v168, v166
	v_rcp_f32_e32 v169, v167
	v_rcp_f32_e32 v220, v180
	v_rcp_f32_e32 v221, v181
	v_fma_f32 v166, -v166, v168, 1.0
	v_fma_f32 v167, -v167, v169, 1.0
	s_nop 0
	v_fma_f32 v166, v168, v166, v168
	v_fma_f32 v167, v169, v167, v169
	s_nop 0
	v_mul_f32_e64 v162, v162, v166
	v_mul_f32_e64 v163, v163, v167
	v_fma_f32 v166, v40, v172, v52
	v_fma_f32 v167, v41, v173, v53
	v_mul_f32_e64 v158, v158, v162
	v_mul_f32_e64 v159, v159, v163
	v_fma_f32 v162, -v180, v220, 1.0
	v_fma_f32 v163, -v181, v221, 1.0
	v_cvt_pk_bf16_f32 v158, v158, v159
	v_fma_f32 v162, v220, v162, v220
	v_fma_f32 v163, v221, v163, v221
	v_fma_f32 v166, v44, v176, v166
	v_fma_f32 v167, v45, v177, v167
	v_mul_f32_e64 v162, v164, v162
	v_mul_f32_e64 v163, v165, v163
	v_fma_f32 v166, v148, v48, v166
	v_fma_f32 v167, v149, v49, v167
	v_mul_f32_e64 v160, v160, v162
	v_mul_f32_e64 v161, v161, v163
	v_fma_f32 v162, v38, v170, v50
	v_fma_f32 v163, v39, v171, v51
	s_nop 0
	v_fma_f32 v162, v42, v174, v162
	v_fma_f32 v163, v43, v175, v163
	s_nop 0
	v_fma_f32 v162, v146, v46, v162
	v_fma_f32 v163, v147, v47, v163
	s_nop 0
	v_mul_f32_e32 v159, 0x3d372713, v162
	v_mul_f32_e32 v159, v162, v159
	v_fma_f32 v159, v162, v159, v162
	v_mul_f32_e32 v159, 0xbfcc422a, v159
	v_min_f32_e32 v159, 0x42a00000, v159
	v_mul_f32_e32 v159, 0x3fb8aa3b, v159
	v_exp_f32_e32 v164, v159
	v_mul_f32_e32 v159, 0x3d372713, v163
	v_mul_f32_e32 v159, v163, v159
	v_fma_f32 v159, v163, v159, v163
	v_mul_f32_e32 v159, 0xbfcc422a, v159
	v_min_f32_e32 v159, 0x42a00000, v159
	v_mul_f32_e32 v159, 0x3fb8aa3b, v159
	v_exp_f32_e32 v165, v159
	v_mul_f32_e32 v159, 0x3d372713, v166
	v_mul_f32_e32 v159, v166, v159
	v_fma_f32 v159, v166, v159, v166
	v_mul_f32_e32 v159, 0xbfcc422a, v159
	v_min_f32_e32 v159, 0x42a00000, v159
	v_mul_f32_e32 v159, 0x3fb8aa3b, v159
	v_exp_f32_e32 v170, v159
	v_mul_f32_e32 v159, 0x3d372713, v167
	v_mul_f32_e32 v159, v167, v159
	v_fma_f32 v159, v167, v159, v167
	v_mul_f32_e32 v159, 0xbfcc422a, v159
	v_min_f32_e32 v159, 0x42a00000, v159
	v_add_f32_e64 v164, v164, 1.0
	v_add_f32_e64 v165, v165, 1.0
	v_mul_f32_e32 v159, 0x3fb8aa3b, v159
	v_rcp_f32_e32 v168, v164
	v_rcp_f32_e32 v169, v165
	v_exp_f32_e32 v171, v159
	v_cvt_pk_bf16_f32 v159, v160, v161
	v_fma_f32 v160, -v164, v168, 1.0
	v_fma_f32 v161, -v165, v169, 1.0
	v_add_f32_e64 v164, v170, 1.0
	v_add_f32_e64 v165, v171, 1.0
	v_fma_f32 v160, v168, v160, v168
	v_fma_f32 v161, v169, v161, v169
	v_rcp_f32_e32 v168, v164
	v_rcp_f32_e32 v169, v165
	v_mul_f32_e64 v160, v162, v160
	v_mul_f32_e64 v161, v163, v161
	v_fma_f32 v162, -v164, v168, 1.0
	v_fma_f32 v163, -v165, v169, 1.0
	s_nop 0
	v_fma_f32 v162, v168, v162, v168
	v_fma_f32 v163, v169, v163, v169
	v_mul_f32_e64 v160, v154, v160
	v_mul_f32_e64 v161, v155, v161
	v_mul_f32_e64 v162, v166, v162
	v_mul_f32_e64 v163, v167, v163
	v_cvt_pk_bf16_f32 v160, v160, v161
	v_mul_f32_e64 v162, v156, v162
	v_mul_f32_e64 v163, v157, v163
	s_nop 0
	v_cvt_pk_bf16_f32 v161, v162, v163
	v_mad_i64_i32 v[162:163], s[58:59], v201, s79, v[178:179]
	global_store_dwordx4 v[162:163], v[158:161], off

; __device__ __forceinline__ u32x2 pk4(f32x4 v) { u32x2 r; r.x = pk2(v.x, v.y); r.y = pk2(v.z, v.w); return r; }
; template <int EPI>
; __device__ __forceinline__ void epilogue(const Params& p, f32x4 (&acc)[2][2][4][2], const int pm, const int pn, const int wr, const int wc, const int fr, const int fq) {
;     ...
;           const int j0 = jb + bj * 4;
;           const f32x4 a0 = acc[ai][bj][m][0], g = acc[ai][bj][m][1];
;           f32x4 am1, am2;
;           if (prompt) {
;             f32x4 o1 = f32x4{0.f, 0.f, 0.f, 0.f}, o2 = o1;
;             if (m > 0) { o1 = ror1v(acc[ai][bj][m > 0 ? m - 1 : 0][0]); o2 = ror2v(acc[ai][bj][m > 0 ? m - 1 : 0][0]); }
;             am1 = shr1v(o1, a0); am2 = shr2v(o2, a0);
;             if (m == 0 && fr < 2 && (row & 2047) >= 2) defer = true;
;             if (m == 3 && fr >= 14) *(f32x4*)(HA1 + ((size_t)(rblk >> 6) * 2 + (fr - 14)) * DFF + j0) = a0;
;             const int pos = row & 2047;
;             if (pos >= 2046) *(f32x4*)(p.out + O_CP + ((size_t)(row >> 11) * 2 + (pos - 2046)) * DFF + j0) = a0;
;           } else {
;             const int sidx = row - MP, b = sidx >> 2, tt = sidx & 3;
;             const f32x4 st0 = *(const f32x4*)(p.in[6] + ((size_t)b * 2 + 0) * DFF + j0);
;             const f32x4 st1 = *(const f32x4*)(p.in[6] + ((size_t)b * 2 + 1) * DFF + j0);
;             const f32x4 s1 = ror1v(a0), s2 = ror2v(a0);
;             am1 = (tt >= 1) ? s1 : st1;
;             am2 = (tt >= 2) ? s2 : ((tt == 1) ? st1 : st0);
;             if (tt >= 2) *(f32x4*)(p.out + O_CS + ((size_t)b * 2 + (tt - 2)) * DFF + j0) = a0;
;           }
;           f32x4 h;
;           h.x = gelu_tanh(cb[bj].x + w0[bj].x * am2.x + w1[bj].x * am1.x + w2[bj].x * a0.x) * g.x;
;           h.y = gelu_tanh(cb[bj].y + w0[bj].y * am2.y + w1[bj].y * am1.y + w2[bj].y * a0.y) * g.y;
;           h.z = gelu_tanh(cb[bj].z + w0[bj].z * am2.z + w1[bj].z * am1.z + w2[bj].z * a0.z) * g.z;
;           h.w = gelu_tanh(cb[bj].w + w0[bj].w * am2.w + w1[bj].w * am1.w + w2[bj].w * a0.w) * g.w;
;           ho[bj] = pk4(h);
;           if (defer) {
;             *(f32x4*)(HA0 + ((size_t)(rblk >> 6) * 2 + fr) * DFF + j0) = a0;
;             *(f32x4*)(HG0 + ((size_t)(rblk >> 6) * 2 + fr) * DFF + j0) = g;
;           }
;         }
;         if (!defer) *(u32x4*)(H + (size_t)row * DFF + jb) = u32x4{ho[0].x, ho[0].y, ho[1].x, ho[1].y};
.LBB0_1003:
	v_fma_f32 v146, v54, v154, v70
	v_fma_f32 v147, v55, v155, v71
	v_fma_f32 v154, v56, v156, v72
	v_fma_f32 v155, v57, v157, v73
	v_fma_f32 v146, v58, v158, v146
	v_fma_f32 v147, v59, v159, v147
	v_fma_f32 v154, v60, v160, v154
	v_fma_f32 v155, v61, v161, v155
	v_fma_f32 v146, v134, v66, v146
	v_fma_f32 v147, v135, v67, v147
	v_fma_f32 v154, v136, v68, v154
	v_fma_f32 v155, v137, v69, v155
	v_mul_f32_e32 v148, 0x3d372713, v146
	v_mul_f32_e32 v149, 0x3d372713, v147
	v_mul_f32_e32 v148, v146, v148
	v_mul_f32_e32 v149, v147, v149
	v_fma_f32 v148, v146, v148, v146
	v_fma_f32 v149, v147, v149, v147
	v_mul_f32_e32 v148, 0xbfcc422a, v148
	v_mul_f32_e32 v149, 0xbfcc422a, v149
	v_mul_f32_e32 v158, 0x3d372713, v154
	v_mul_f32_e32 v159, 0x3d372713, v155
	v_min_f32_e32 v148, 0x42a00000, v148
	v_min_f32_e32 v149, 0x42a00000, v149
	v_mul_f32_e32 v158, v154, v158
	v_mul_f32_e32 v159, v155, v159
	v_mul_f32_e32 v148, 0x3fb8aa3b, v148
	v_mul_f32_e32 v149, 0x3fb8aa3b, v149
	v_fma_f32 v158, v154, v158, v154
	v_fma_f32 v159, v155, v159, v155
	v_exp_f32_e32 v148, v148
	v_exp_f32_e32 v149, v149
	v_mul_f32_e32 v158, 0xbfcc422a, v158
	v_mul_f32_e32 v159, 0xbfcc422a, v159
	v_min_f32_e32 v158, 0x42a00000, v158
	v_min_f32_e32 v159, 0x42a00000, v159
	v_mul_f32_e32 v158, 0x3fb8aa3b, v158
	v_mul_f32_e32 v159, 0x3fb8aa3b, v159
	v_exp_f32_e32 v158, v158
	v_exp_f32_e32 v159, v159
	v_add_f32_e64 v148, v148, 1.0
	v_add_f32_e64 v149, v149, 1.0
	s_nop 1
	v_readlane_b32 s80, v244, 14
	v_rcp_f32_e32 v156, v148
	v_rcp_f32_e32 v157, v149
	v_add_f32_e64 v158, v158, 1.0
	v_add_f32_e64 v159, v159, 1.0
	s_nop 1
	v_readlane_b32 s92, v244, 26
	v_rcp_f32_e32 v160, v158
	v_rcp_f32_e32 v161, v159
	v_fma_f32 v148, -v148, v156, 1.0
	v_fma_f32 v149, -v149, v157, 1.0
	s_nop 1
	v_readlane_b32 s93, v244, 27
	v_fma_f32 v148, v156, v148, v156
	v_fma_f32 v149, v157, v149, v157
	v_or_b32_e32 v156, 16, v201
	v_mul_f32_e64 v146, v146, v148
	v_mul_f32_e64 v147, v147, v149
	s_and_b64 vcc, exec, s[18:19]
	v_mul_f32_e64 v142, v142, v146
	v_mul_f32_e64 v143, v143, v147
	v_fma_f32 v146, -v158, v160, 1.0
	v_fma_f32 v147, -v159, v161, 1.0
	v_cvt_pk_bf16_f32 v142, v142, v143
	v_fma_f32 v146, v160, v146, v160
	v_fma_f32 v147, v161, v147, v161
	s_nop 1
	v_readlane_b32 s81, v244, 15
	v_mul_f32_e64 v146, v154, v146
	v_mul_f32_e64 v147, v155, v147
	s_nop 1
	v_readlane_b32 s82, v244, 16
	v_mul_f32_e64 v144, v144, v146
	v_mul_f32_e64 v145, v145, v147
	v_fma_f32 v146, v38, v150, v50
	v_fma_f32 v147, v39, v151, v51
	v_fma_f32 v150, v40, v152, v52
	v_fma_f32 v151, v41, v153, v53
	v_fma_f32 v146, v42, v162, v146
	v_fma_f32 v147, v43, v163, v147
	v_fma_f32 v150, v44, v164, v150
	v_fma_f32 v151, v45, v165, v151
	v_fma_f32 v146, v130, v46, v146
	v_fma_f32 v147, v131, v47, v147
	v_fma_f32 v150, v132, v48, v150
	v_fma_f32 v151, v133, v49, v151
	v_mul_f32_e32 v143, 0x3d372713, v146
	v_mul_f32_e32 v143, v146, v143
	v_fma_f32 v143, v146, v143, v146
	v_mul_f32_e32 v143, 0xbfcc422a, v143
	v_min_f32_e32 v143, 0x42a00000, v143
	v_mul_f32_e32 v143, 0x3fb8aa3b, v143
	v_exp_f32_e32 v148, v143
	v_mul_f32_e32 v143, 0x3d372713, v147
	v_mul_f32_e32 v143, v147, v143
	v_fma_f32 v143, v147, v143, v147
	v_mul_f32_e32 v143, 0xbfcc422a, v143
	v_min_f32_e32 v143, 0x42a00000, v143
	v_mul_f32_e32 v143, 0x3fb8aa3b, v143
	v_exp_f32_e32 v149, v143
	v_mul_f32_e32 v143, 0x3d372713, v150
	v_mul_f32_e32 v143, v150, v143
	v_fma_f32 v143, v150, v143, v150
	v_mul_f32_e32 v143, 0xbfcc422a, v143
	v_min_f32_e32 v143, 0x42a00000, v143
	v_mul_f32_e32 v143, 0x3fb8aa3b, v143
	v_exp_f32_e32 v154, v143
	v_mul_f32_e32 v143, 0x3d372713, v151
	v_mul_f32_e32 v143, v151, v143
	v_fma_f32 v143, v151, v143, v151
	v_mul_f32_e32 v143, 0xbfcc422a, v143
	v_min_f32_e32 v143, 0x42a00000, v143
	v_add_f32_e64 v148, v148, 1.0
	v_add_f32_e64 v149, v149, 1.0
	v_mul_f32_e32 v143, 0x3fb8aa3b, v143
	v_rcp_f32_e32 v152, v148
	v_rcp_f32_e32 v153, v149
	v_exp_f32_e32 v155, v143
	v_cvt_pk_bf16_f32 v143, v144, v145
	v_readlane_b32 s83, v244, 17
	v_fma_f32 v144, -v148, v152, 1.0
	v_fma_f32 v145, -v149, v153, 1.0
	v_add_f32_e64 v148, v154, 1.0
	v_add_f32_e64 v149, v155, 1.0
	v_fma_f32 v144, v152, v144, v152
	v_fma_f32 v145, v153, v145, v153
	v_rcp_f32_e32 v154, v148
	v_rcp_f32_e32 v155, v149
	v_mul_f32_e64 v144, v146, v144
	v_mul_f32_e64 v145, v147, v145
	s_nop 1
	v_readlane_b32 s84, v244, 18
	v_mul_f32_e64 v138, v138, v144
	v_mul_f32_e64 v139, v139, v145
	s_nop 1
	v_fma_f32 v144, -v148, v154, 1.0
	v_fma_f32 v145, -v149, v155, 1.0
	s_nop 1
	v_readlane_b32 s85, v244, 19
	v_fma_f32 v144, v154, v144, v154
	v_fma_f32 v145, v155, v145, v155
	s_nop 1
	v_readlane_b32 s86, v244, 20
	v_mul_f32_e64 v144, v150, v144
	v_mul_f32_e64 v145, v151, v145
	s_nop 1
	v_readlane_b32 s87, v244, 21
	v_mul_f32_e64 v140, v140, v144
	v_mul_f32_e64 v141, v141, v145
	v_cvt_pk_bf16_f32 v144, v138, v139
	v_cvt_pk_bf16_f32 v145, v140, v141
	v_mad_i64_i32 v[138:139], s[56:57], v156, s79, v[178:179]
	global_store_dwordx4 v[138:139], v[142:145], off
	v_add_u32_e32 v138, 0xffffc020, v201
	v_ashrrev_i32_e32 v138, 2, v138
	v_ashrrev_i32_e32 v139, 31, v138
	v_mad_i64_i32 v[140:141], s[56:57], v138, s77, 0
	v_lshl_add_u64 v[138:139], v[138:139], 1, v[202:203]
	v_mad_u64_u32 v[154:155], s[56:57], v138, s78, 0
	v_lshl_add_u64 v[152:153], s[92:93], 0, v[140:141]
	v_mad_i32_i24 v155, v139, s78, v155
	s_mov_b64 s[56:57], -1
	v_lshl_add_u64 v[150:151], v[214:215], 2, v[152:153]
	v_readlane_b32 s88, v244, 22
	v_readlane_b32 s89, v244, 23
	v_readlane_b32 s90, v244, 24
	v_readlane_b32 s91, v244, 25
	v_readlane_b32 s94, v244, 28
	v_readlane_b32 s95, v244, 29
	s_cbranch_vccnz .LBB0_1007
	v_add_co_u32_e32 v142, vcc, 0x2000, v150
	v_mov_b32_e32 v156, 0
	s_nop 0
	v_addc_co_u32_e32 v143, vcc, 0, v151, vcc
	global_load_dwordx4 v[138:141], v[150:151], off
	s_nop 0
	global_load_dwordx4 v[142:145], v[142:143], off offset:3072
	v_mov_b32_e32 v157, 0
	v_mov_b32_e32 v158, 0
	v_mov_b32_e32 v159, 0
	v_mov_b32_e32 v146, 0
	v_mov_b32_e32 v147, 0
	v_mov_b32_e32 v148, 0
	v_mov_b32_e32 v149, 0
	v_mov_b32_dpp v156, v118 row_ror:1 row_mask:0xf bank_mask:0xf
	v_mov_b32_dpp v157, v119 row_ror:1 row_mask:0xf bank_mask:0xf
	v_mov_b32_dpp v158, v120 row_ror:1 row_mask:0xf bank_mask:0xf
	v_mov_b32_dpp v159, v121 row_ror:1 row_mask:0xf bank_mask:0xf
	v_mov_b32_dpp v146, v118 row_ror:2 row_mask:0xf bank_mask:0xf
	v_mov_b32_dpp v147, v119 row_ror:2 row_mask:0xf bank_mask:0xf
	v_mov_b32_dpp v148, v120 row_ror:2 row_mask:0xf bank_mask:0xf
	v_mov_b32_dpp v149, v121 row_ror:2 row_mask:0xf bank_mask:0xf
	s_waitcnt vmcnt(0)
	v_cndmask_b32_e64 v141, v141, v145, s[10:11]
	v_cndmask_b32_e64 v140, v140, v144, s[10:11]
	v_cndmask_b32_e64 v139, v139, v143, s[10:11]
	v_cndmask_b32_e64 v138, v138, v142, s[10:11]
	s_and_saveexec_b64 s[56:57], s[8:9]
	s_cbranch_execz .LBB0_1006
	v_lshl_add_u64 v[138:139], s[42:43], 0, v[154:155]
	v_lshl_add_u64 v[138:139], v[214:215], 2, v[138:139]
	global_store_dwordx4 v[138:139], v[118:121], off
	v_mov_b64_e32 v[138:139], v[146:147]
	v_mov_b64_e32 v[140:141], v[148:149]

; __device__ __forceinline__ u32x2 pk4(f32x4 v) { u32x2 r; r.x = pk2(v.x, v.y); r.y = pk2(v.z, v.w); return r; }
; template <int EPI>
; __device__ __forceinline__ void epilogue(const Params& p, f32x4 (&acc)[2][2][4][2], const int pm, const int pn, const int wr, const int wc, const int fr, const int fq) {
;     ...
;           const int j0 = jb + bj * 4;
;           const f32x4 a0 = acc[ai][bj][m][0], g = acc[ai][bj][m][1];
;           f32x4 am1, am2;
;           if (prompt) {
;             f32x4 o1 = f32x4{0.f, 0.f, 0.f, 0.f}, o2 = o1;
;             if (m > 0) { o1 = ror1v(acc[ai][bj][m > 0 ? m - 1 : 0][0]); o2 = ror2v(acc[ai][bj][m > 0 ? m - 1 : 0][0]); }
;             am1 = shr1v(o1, a0); am2 = shr2v(o2, a0);
;             if (m == 0 && fr < 2 && (row & 2047) >= 2) defer = true;
;             if (m == 3 && fr >= 14) *(f32x4*)(HA1 + ((size_t)(rblk >> 6) * 2 + (fr - 14)) * DFF + j0) = a0;
;             const int pos = row & 2047;
;             if (pos >= 2046) *(f32x4*)(p.out + O_CP + ((size_t)(row >> 11) * 2 + (pos - 2046)) * DFF + j0) = a0;
;           } else {
;             const int sidx = row - MP, b = sidx >> 2, tt = sidx & 3;
;             const f32x4 st0 = *(const f32x4*)(p.in[6] + ((size_t)b * 2 + 0) * DFF + j0);
;             const f32x4 st1 = *(const f32x4*)(p.in[6] + ((size_t)b * 2 + 1) * DFF + j0);
;             const f32x4 s1 = ror1v(a0), s2 = ror2v(a0);
;             am1 = (tt >= 1) ? s1 : st1;
;             am2 = (tt >= 2) ? s2 : ((tt == 1) ? st1 : st0);
;             if (tt >= 2) *(f32x4*)(p.out + O_CS + ((size_t)b * 2 + (tt - 2)) * DFF + j0) = a0;
;           }
;           f32x4 h;
;           h.x = gelu_tanh(cb[bj].x + w0[bj].x * am2.x + w1[bj].x * am1.x + w2[bj].x * a0.x) * g.x;
;           h.y = gelu_tanh(cb[bj].y + w0[bj].y * am2.y + w1[bj].y * am1.y + w2[bj].y * a0.y) * g.y;
;           h.z = gelu_tanh(cb[bj].z + w0[bj].z * am2.z + w1[bj].z * am1.z + w2[bj].z * a0.z) * g.z;
;           h.w = gelu_tanh(cb[bj].w + w0[bj].w * am2.w + w1[bj].w * am1.w + w2[bj].w * a0.w) * g.w;
;           ho[bj] = pk4(h);
;           if (defer) {
;             *(f32x4*)(HA0 + ((size_t)(rblk >> 6) * 2 + fr) * DFF + j0) = a0;
;             *(f32x4*)(HG0 + ((size_t)(rblk >> 6) * 2 + fr) * DFF + j0) = g;
;           }
;         }
;         if (!defer) *(u32x4*)(H + (size_t)row * DFF + jb) = u32x4{ho[0].x, ho[0].y, ho[1].x, ho[1].y};
.LBB0_1015:
	v_fma_f32 v130, v54, v138, v70
	v_fma_f32 v131, v55, v139, v71
	v_fma_f32 v138, v56, v140, v72
	v_fma_f32 v139, v57, v141, v73
	v_fma_f32 v130, v58, v142, v130
	v_fma_f32 v131, v59, v143, v131
	v_fma_f32 v138, v60, v144, v138
	v_fma_f32 v139, v61, v145, v139
	v_fma_f32 v130, v118, v66, v130
	v_fma_f32 v131, v119, v67, v131
	v_fma_f32 v138, v120, v68, v138
	v_fma_f32 v139, v121, v69, v139
	v_mul_f32_e32 v132, 0x3d372713, v130
	v_mul_f32_e32 v133, 0x3d372713, v131
	v_mul_f32_e32 v132, v130, v132
	v_mul_f32_e32 v133, v131, v133
	v_fma_f32 v132, v130, v132, v130
	v_fma_f32 v133, v131, v133, v131
	v_mul_f32_e32 v132, 0xbfcc422a, v132
	v_mul_f32_e32 v133, 0xbfcc422a, v133
	v_mul_f32_e32 v142, 0x3d372713, v138
	v_mul_f32_e32 v143, 0x3d372713, v139
	v_min_f32_e32 v132, 0x42a00000, v132
	v_min_f32_e32 v133, 0x42a00000, v133
	v_mul_f32_e32 v142, v138, v142
	v_mul_f32_e32 v143, v139, v143
	v_mul_f32_e32 v132, 0x3fb8aa3b, v132
	v_mul_f32_e32 v133, 0x3fb8aa3b, v133
	v_fma_f32 v142, v138, v142, v138
	v_fma_f32 v143, v139, v143, v139
	v_exp_f32_e32 v132, v132
	v_exp_f32_e32 v133, v133
	v_mul_f32_e32 v142, 0xbfcc422a, v142
	v_mul_f32_e32 v143, 0xbfcc422a, v143
	v_min_f32_e32 v142, 0x42a00000, v142
	v_min_f32_e32 v143, 0x42a00000, v143
	v_mul_f32_e32 v142, 0x3fb8aa3b, v142
	v_mul_f32_e32 v143, 0x3fb8aa3b, v143
	v_exp_f32_e32 v142, v142
	v_exp_f32_e32 v143, v143
	v_add_f32_e64 v132, v132, 1.0
	v_add_f32_e64 v133, v133, 1.0
	s_nop 1
	v_readlane_b32 s80, v244, 14
	v_rcp_f32_e32 v140, v132
	v_rcp_f32_e32 v141, v133
	v_add_f32_e64 v142, v142, 1.0
	v_add_f32_e64 v143, v143, 1.0
	s_nop 1
	v_readlane_b32 s92, v244, 26
	v_rcp_f32_e32 v144, v142
	v_rcp_f32_e32 v145, v143
	v_fma_f32 v132, -v132, v140, 1.0
	v_fma_f32 v133, -v133, v141, 1.0
	s_nop 1
	v_readlane_b32 s93, v244, 27
	v_fma_f32 v132, v140, v132, v140
	v_fma_f32 v133, v141, v133, v141
	v_or_b32_e32 v140, 32, v201
	v_mul_f32_e64 v130, v130, v132
	v_mul_f32_e64 v131, v131, v133
	s_and_b64 vcc, exec, s[18:19]
	v_mul_f32_e64 v126, v126, v130
	v_mul_f32_e64 v127, v127, v131
	v_fma_f32 v130, -v142, v144, 1.0
	v_fma_f32 v131, -v143, v145, 1.0
	v_cvt_pk_bf16_f32 v126, v126, v127
	v_fma_f32 v130, v144, v130, v144
	v_fma_f32 v131, v145, v131, v145
	v_bitop3_b32 v144, v201, s0, 48 bitop3:0xc8
	v_mul_f32_e64 v130, v138, v130
	v_mul_f32_e64 v131, v139, v131
	s_nop 1
	v_readlane_b32 s81, v244, 15
	v_mul_f32_e64 v128, v128, v130
	v_mul_f32_e64 v129, v129, v131
	v_fma_f32 v130, v38, v134, v50
	v_fma_f32 v131, v39, v135, v51
	v_fma_f32 v134, v40, v136, v52
	v_fma_f32 v135, v41, v137, v53
	v_fma_f32 v130, v42, v146, v130
	v_fma_f32 v131, v43, v147, v131
	v_fma_f32 v134, v44, v148, v134
	v_fma_f32 v135, v45, v149, v135
	v_fma_f32 v130, v114, v46, v130
	v_fma_f32 v131, v115, v47, v131
	v_fma_f32 v134, v116, v48, v134
	v_fma_f32 v135, v117, v49, v135
	v_mul_f32_e32 v127, 0x3d372713, v130
	v_mul_f32_e32 v127, v130, v127
	v_fma_f32 v127, v130, v127, v130
	v_mul_f32_e32 v127, 0xbfcc422a, v127
	v_min_f32_e32 v127, 0x42a00000, v127
	v_mul_f32_e32 v127, 0x3fb8aa3b, v127
	v_exp_f32_e32 v132, v127
	v_mul_f32_e32 v127, 0x3d372713, v131
	v_mul_f32_e32 v127, v131, v127
	v_fma_f32 v127, v131, v127, v131
	v_mul_f32_e32 v127, 0xbfcc422a, v127
	v_min_f32_e32 v127, 0x42a00000, v127
	v_mul_f32_e32 v127, 0x3fb8aa3b, v127
	v_exp_f32_e32 v133, v127
	v_mul_f32_e32 v127, 0x3d372713, v134
	v_mul_f32_e32 v127, v134, v127
	v_fma_f32 v127, v134, v127, v134
	v_mul_f32_e32 v127, 0xbfcc422a, v127
	v_min_f32_e32 v127, 0x42a00000, v127
	v_mul_f32_e32 v127, 0x3fb8aa3b, v127
	v_exp_f32_e32 v138, v127
	v_mul_f32_e32 v127, 0x3d372713, v135
	v_mul_f32_e32 v127, v135, v127
	v_fma_f32 v127, v135, v127, v135
	v_mul_f32_e32 v127, 0xbfcc422a, v127
	v_min_f32_e32 v127, 0x42a00000, v127
	v_add_f32_e64 v132, v132, 1.0
	v_add_f32_e64 v133, v133, 1.0
	v_mul_f32_e32 v127, 0x3fb8aa3b, v127
	v_rcp_f32_e32 v136, v132
	v_rcp_f32_e32 v137, v133
	v_exp_f32_e32 v139, v127
	v_cvt_pk_bf16_f32 v127, v128, v129
	v_readlane_b32 s82, v244, 16
	v_fma_f32 v128, -v132, v136, 1.0
	v_fma_f32 v129, -v133, v137, 1.0
	v_add_f32_e64 v132, v138, 1.0
	v_add_f32_e64 v133, v139, 1.0
	v_fma_f32 v128, v136, v128, v136
	v_fma_f32 v129, v137, v129, v137
	v_rcp_f32_e32 v138, v132
	v_rcp_f32_e32 v139, v133
	v_mul_f32_e64 v128, v130, v128
	v_mul_f32_e64 v129, v131, v129
	s_nop 1
	v_readlane_b32 s83, v244, 17
	v_mul_f32_e64 v122, v122, v128
	v_mul_f32_e64 v123, v123, v129
	s_nop 1
	v_fma_f32 v128, -v132, v138, 1.0
	v_fma_f32 v129, -v133, v139, 1.0
	s_nop 1
	v_readlane_b32 s84, v244, 18
	v_fma_f32 v128, v138, v128, v138
	v_fma_f32 v129, v139, v129, v139
	s_nop 1
	v_readlane_b32 s85, v244, 19
	v_mul_f32_e64 v128, v134, v128
	v_mul_f32_e64 v129, v135, v129
	s_nop 1
	v_readlane_b32 s86, v244, 20
	v_mul_f32_e64 v124, v124, v128
	v_mul_f32_e64 v125, v125, v129
	v_cvt_pk_bf16_f32 v128, v122, v123
	v_cvt_pk_bf16_f32 v129, v124, v125
	v_mad_i64_i32 v[122:123], s[56:57], v140, s79, v[178:179]
	global_store_dwordx4 v[122:123], v[126:129], off
	v_add_u32_e32 v122, 0xffffc030, v201
	v_ashrrev_i32_e32 v140, 2, v122
	v_mad_i64_i32 v[122:123], s[56:57], v140, s77, 0
	v_lshl_add_u64 v[136:137], s[92:93], 0, v[122:123]
	v_cmp_lt_u32_e64 s[56:57], s1, v144
	v_lshl_add_u64 v[134:135], v[214:215], 2, v[136:137]
	v_readlane_b32 s87, v244, 21
	v_readlane_b32 s88, v244, 22
	v_readlane_b32 s89, v244, 23
	v_readlane_b32 s90, v244, 24
	v_readlane_b32 s91, v244, 25
	v_readlane_b32 s94, v244, 28
	v_readlane_b32 s95, v244, 29
	s_cbranch_vccnz .LBB0_1019
	v_add_co_u32_e32 v126, vcc, 0x2000, v134
	v_mov_b32_e32 v138, 0
	s_nop 0
	v_addc_co_u32_e32 v127, vcc, 0, v135, vcc
	global_load_dwordx4 v[122:125], v[134:135], off
	s_nop 0
	global_load_dwordx4 v[126:129], v[126:127], off offset:3072
	v_mov_b32_e32 v139, 0
	v_mov_b32_e32 v141, 0
	v_mov_b32_e32 v142, 0
	v_mov_b32_e32 v130, 0
	v_mov_b32_e32 v131, 0
	v_mov_b32_e32 v132, 0
	v_mov_b32_e32 v133, 0
	s_mov_b64 s[60:61], 0
	v_mov_b32_dpp v138, v110 row_ror:1 row_mask:0xf bank_mask:0xf
	v_mov_b32_dpp v139, v111 row_ror:1 row_mask:0xf bank_mask:0xf
	v_mov_b32_dpp v141, v112 row_ror:1 row_mask:0xf bank_mask:0xf
	v_mov_b32_dpp v142, v113 row_ror:1 row_mask:0xf bank_mask:0xf
	v_mov_b32_dpp v130, v110 row_ror:2 row_mask:0xf bank_mask:0xf
	v_mov_b32_dpp v131, v111 row_ror:2 row_mask:0xf bank_mask:0xf
	v_mov_b32_dpp v132, v112 row_ror:2 row_mask:0xf bank_mask:0xf
	v_mov_b32_dpp v133, v113 row_ror:2 row_mask:0xf bank_mask:0xf
	s_mov_b64 s[58:59], 0
	s_waitcnt vmcnt(0)
	v_cndmask_b32_e64 v125, v125, v129, s[10:11]
	v_cndmask_b32_e64 v124, v124, v128, s[10:11]
	v_cndmask_b32_e64 v123, v123, v127, s[10:11]
	v_cndmask_b32_e64 v122, v122, v126, s[10:11]
	s_and_saveexec_b64 s[62:63], s[8:9]
	v_mov_b64_e32 v[122:123], v[130:131]
	s_mov_b64 s[58:59], exec
	v_mov_b64_e32 v[124:125], v[132:133]
	s_or_b64 exec, exec, s[62:63]
	v_cndmask_b32_e64 v129, v142, v129, s[6:7]
	v_cndmask_b32_e64 v128, v141, v128, s[6:7]
	v_cndmask_b32_e64 v127, v139, v127, s[6:7]
	v_cndmask_b32_e64 v126, v138, v126, s[6:7]
	s_branch .LBB0_1020

; __device__ __forceinline__ u32x2 pk4(f32x4 v) { u32x2 r; r.x = pk2(v.x, v.y); r.y = pk2(v.z, v.w); return r; }
; template <int EPI>
; __device__ __forceinline__ void epilogue(const Params& p, f32x4 (&acc)[2][2][4][2], const int pm, const int pn, const int wr, const int wc, const int fr, const int fq) {
;     ...
;           const int j0 = jb + bj * 4;
;           const f32x4 a0 = acc[ai][bj][m][0], g = acc[ai][bj][m][1];
;           f32x4 am1, am2;
;           if (prompt) {
;             f32x4 o1 = f32x4{0.f, 0.f, 0.f, 0.f}, o2 = o1;
;             if (m > 0) { o1 = ror1v(acc[ai][bj][m > 0 ? m - 1 : 0][0]); o2 = ror2v(acc[ai][bj][m > 0 ? m - 1 : 0][0]); }
;             am1 = shr1v(o1, a0); am2 = shr2v(o2, a0);
;             if (m == 0 && fr < 2 && (row & 2047) >= 2) defer = true;
;             if (m == 3 && fr >= 14) *(f32x4*)(HA1 + ((size_t)(rblk >> 6) * 2 + (fr - 14)) * DFF + j0) = a0;
;             const int pos = row & 2047;
;             if (pos >= 2046) *(f32x4*)(p.out + O_CP + ((size_t)(row >> 11) * 2 + (pos - 2046)) * DFF + j0) = a0;
;           } else {
;             const int sidx = row - MP, b = sidx >> 2, tt = sidx & 3;
;             const f32x4 st0 = *(const f32x4*)(p.in[6] + ((size_t)b * 2 + 0) * DFF + j0);
;             const f32x4 st1 = *(const f32x4*)(p.in[6] + ((size_t)b * 2 + 1) * DFF + j0);
;             const f32x4 s1 = ror1v(a0), s2 = ror2v(a0);
;             am1 = (tt >= 1) ? s1 : st1;
;             am2 = (tt >= 2) ? s2 : ((tt == 1) ? st1 : st0);
;             if (tt >= 2) *(f32x4*)(p.out + O_CS + ((size_t)b * 2 + (tt - 2)) * DFF + j0) = a0;
;           }
;           f32x4 h;
;           h.x = gelu_tanh(cb[bj].x + w0[bj].x * am2.x + w1[bj].x * am1.x + w2[bj].x * a0.x) * g.x;
;           h.y = gelu_tanh(cb[bj].y + w0[bj].y * am2.y + w1[bj].y * am1.y + w2[bj].y * a0.y) * g.y;
;           h.z = gelu_tanh(cb[bj].z + w0[bj].z * am2.z + w1[bj].z * am1.z + w2[bj].z * a0.z) * g.z;
;           h.w = gelu_tanh(cb[bj].w + w0[bj].w * am2.w + w1[bj].w * am1.w + w2[bj].w * a0.w) * g.w;
;           ho[bj] = pk4(h);
;           if (defer) {
;             *(f32x4*)(HA0 + ((size_t)(rblk >> 6) * 2 + fr) * DFF + j0) = a0;
;             *(f32x4*)(HG0 + ((size_t)(rblk >> 6) * 2 + fr) * DFF + j0) = g;
;           }
;         }
;         if (!defer) *(u32x4*)(H + (size_t)row * DFF + jb) = u32x4{ho[0].x, ho[0].y, ho[1].x, ho[1].y};
.LBB0_1036:
	v_fma_f32 v116, v54, v122, v70
	v_fma_f32 v117, v55, v123, v71
	v_fma_f32 v122, v56, v124, v72
	v_fma_f32 v123, v57, v125, v73
	v_fma_f32 v116, v58, v126, v116
	v_fma_f32 v117, v59, v127, v117
	v_fma_f32 v122, v60, v128, v122
	v_fma_f32 v123, v61, v129, v123
	v_fma_f32 v110, v110, v66, v116
	v_fma_f32 v111, v111, v67, v117
	v_fma_f32 v112, v112, v68, v122
	v_fma_f32 v113, v113, v69, v123
	v_mul_f32_e32 v115, 0x3d372713, v110
	v_mul_f32_e32 v115, v110, v115
	v_fma_f32 v115, v110, v115, v110
	v_mul_f32_e32 v115, 0xbfcc422a, v115
	v_min_f32_e32 v115, 0x42a00000, v115
	v_mul_f32_e32 v115, 0x3fb8aa3b, v115
	v_exp_f32_e32 v116, v115
	v_mul_f32_e32 v115, 0x3d372713, v111
	v_mul_f32_e32 v115, v111, v115
	v_fma_f32 v115, v111, v115, v111
	v_mul_f32_e32 v115, 0xbfcc422a, v115
	v_min_f32_e32 v115, 0x42a00000, v115
	v_mul_f32_e32 v115, 0x3fb8aa3b, v115
	v_exp_f32_e32 v117, v115
	v_mul_f32_e32 v115, 0x3d372713, v112
	v_mul_f32_e32 v115, v112, v115
	v_fma_f32 v115, v112, v115, v112
	v_mul_f32_e32 v115, 0xbfcc422a, v115
	v_min_f32_e32 v115, 0x42a00000, v115
	v_mul_f32_e32 v115, 0x3fb8aa3b, v115
	v_exp_f32_e32 v124, v115
	v_mul_f32_e32 v115, 0x3d372713, v113
	v_mul_f32_e32 v115, v113, v115
	v_fma_f32 v115, v113, v115, v113
	v_mul_f32_e32 v115, 0xbfcc422a, v115
	v_min_f32_e32 v115, 0x42a00000, v115
	v_mul_f32_e32 v115, 0x3fb8aa3b, v115
	v_exp_f32_e32 v125, v115
	v_add_f32_e64 v116, v116, 1.0
	v_add_f32_e64 v117, v117, 1.0
	v_or_b32_e32 v114, 48, v201
	v_rcp_f32_e32 v122, v116
	v_rcp_f32_e32 v123, v117
	v_add_f32_e64 v124, v124, 1.0
	v_add_f32_e64 v125, v125, 1.0
	s_addk_i32 s47, 0x80
	v_rcp_f32_e32 v126, v124
	v_rcp_f32_e32 v127, v125
	v_fma_f32 v116, -v116, v122, 1.0
	v_fma_f32 v117, -v117, v123, 1.0
	s_nop 1
	v_readlane_b32 s80, v244, 14
	v_fma_f32 v116, v122, v116, v122
	v_fma_f32 v117, v123, v117, v123
	s_and_b32 s49, s47, 0x7c0
	v_mul_f32_e64 v110, v110, v116
	v_mul_f32_e64 v111, v111, v117
	s_nop 1
	v_readlane_b32 s92, v244, 26
	v_mul_f32_e64 v106, v106, v110
	v_mul_f32_e64 v107, v107, v111
	v_fma_f32 v110, -v124, v126, 1.0
	v_fma_f32 v111, -v125, v127, 1.0
	v_or_b32_e32 v124, s47, v200
	v_fma_f32 v110, v126, v110, v126
	v_fma_f32 v111, v127, v111, v127
	s_nop 1
	v_readlane_b32 s93, v244, 27
	v_mul_f32_e64 v110, v112, v110
	v_mul_f32_e64 v111, v113, v111
	v_fma_f32 v112, v40, v120, v52
	v_fma_f32 v113, v41, v121, v53
	v_mul_f32_e64 v108, v108, v110
	v_mul_f32_e64 v109, v109, v111
	v_fma_f32 v110, v38, v118, v50
	v_fma_f32 v111, v39, v119, v51
	v_fma_f32 v112, v44, v132, v112
	v_fma_f32 v113, v45, v133, v113
	v_fma_f32 v110, v42, v130, v110
	v_fma_f32 v111, v43, v131, v111
	v_fma_f32 v104, v104, v48, v112
	v_fma_f32 v105, v105, v49, v113
	v_fma_f32 v110, v102, v46, v110
	v_fma_f32 v111, v103, v47, v111
	s_cmp_lg_u32 s49, 0
	v_mul_f32_e32 v102, 0x3d372713, v110
	v_mul_f32_e32 v103, 0x3d372713, v111
	v_mul_f32_e32 v102, v110, v102
	v_mul_f32_e32 v103, v111, v103
	v_fma_f32 v102, v110, v102, v110
	v_fma_f32 v103, v111, v103, v111
	v_mul_f32_e32 v102, 0xbfcc422a, v102
	v_mul_f32_e32 v103, 0xbfcc422a, v103
	v_min_f32_e32 v102, 0x42a00000, v102
	v_min_f32_e32 v103, 0x42a00000, v103
	v_mul_f32_e32 v102, 0x3fb8aa3b, v102
	v_mul_f32_e32 v103, 0x3fb8aa3b, v103
	v_exp_f32_e32 v102, v102
	v_exp_f32_e32 v103, v103
	s_mov_b64 s[58:59], -1
	v_readlane_b32 s81, v244, 15
	v_readlane_b32 s82, v244, 16
	v_add_f32_e64 v112, v102, 1.0
	v_add_f32_e64 v113, v103, 1.0
	v_mul_f32_e32 v102, 0x3d372713, v104
	v_mul_f32_e32 v102, v104, v102
	v_fma_f32 v102, v104, v102, v104
	v_mul_f32_e32 v102, 0xbfcc422a, v102
	v_min_f32_e32 v102, 0x42a00000, v102
	v_mul_f32_e32 v102, 0x3fb8aa3b, v102
	v_exp_f32_e32 v118, v102
	v_mul_f32_e32 v102, 0x3d372713, v105
	v_mul_f32_e32 v102, v105, v102
	v_fma_f32 v102, v105, v102, v105
	v_mul_f32_e32 v102, 0xbfcc422a, v102
	v_min_f32_e32 v102, 0x42a00000, v102
	v_mul_f32_e32 v102, 0x3fb8aa3b, v102
	v_exp_f32_e32 v119, v102
	v_rcp_f32_e32 v116, v112
	v_rcp_f32_e32 v117, v113
	v_cvt_pk_bf16_f32 v103, v108, v109
	v_add_f32_e64 v108, v118, 1.0
	v_add_f32_e64 v109, v119, 1.0
	v_cvt_pk_bf16_f32 v102, v106, v107
	v_fma_f32 v106, -v112, v116, 1.0
	v_fma_f32 v107, -v113, v117, 1.0
	v_rcp_f32_e32 v112, v108
	v_rcp_f32_e32 v113, v109
	v_fma_f32 v106, v116, v106, v116
	v_fma_f32 v107, v117, v107, v117
	s_nop 1
	v_readlane_b32 s83, v244, 17
	v_mul_f32_e64 v106, v110, v106
	v_mul_f32_e64 v107, v111, v107
	s_nop 1
	v_readlane_b32 s84, v244, 18
	v_mul_f32_e64 v98, v98, v106
	v_mul_f32_e64 v99, v99, v107
	s_nop 1
	v_fma_f32 v106, -v108, v112, 1.0
	v_fma_f32 v107, -v109, v113, 1.0
	s_nop 1
	v_readlane_b32 s85, v244, 19
	v_fma_f32 v106, v112, v106, v112
	v_fma_f32 v107, v113, v107, v113
	s_nop 1
	v_readlane_b32 s86, v244, 20
	v_mul_f32_e64 v104, v104, v106
	v_mul_f32_e64 v105, v105, v107
	s_nop 1
	v_readlane_b32 s87, v244, 21
	v_mul_f32_e64 v100, v100, v104
	v_mul_f32_e64 v101, v101, v105
	v_cvt_pk_bf16_f32 v104, v98, v99
	v_cvt_pk_bf16_f32 v105, v100, v101
	v_mad_i64_i32 v[98:99], s[54:55], v114, s79, v[178:179]
	global_store_dwordx4 v[98:99], v[102:105], off
	v_add_u32_e32 v98, 0xffffc000, v124
	v_ashrrev_i32_e32 v98, 2, v98
	v_ashrrev_i32_e32 v99, 31, v98
	v_mad_i64_i32 v[100:101], s[56:57], v98, s77, 0
	v_lshl_add_u64 v[98:99], v[98:99], 1, v[202:203]
	v_mad_u64_u32 v[118:119], s[56:57], v98, s78, 0
	v_lshl_add_u64 v[116:117], s[92:93], 0, v[100:101]
	s_cselect_b64 s[54:55], -1, 0
	v_mad_i32_i24 v119, v99, s78, v119
	s_and_b64 vcc, exec, s[18:19]
	v_lshl_add_u64 v[114:115], v[214:215], 2, v[116:117]
	v_readlane_b32 s88, v244, 22
	v_readlane_b32 s89, v244, 23
	v_readlane_b32 s90, v244, 24
	v_readlane_b32 s91, v244, 25
	v_readlane_b32 s94, v244, 28
	v_readlane_b32 s95, v244, 29
	s_cbranch_vccnz .LBB0_1040
; __device__ __forceinline__ f32x4 ror1v(f32x4 v) { return f32x4{dpp_ror1(v.x), dpp_ror1(v.y), dpp_ror1(v.z), dpp_ror1(v.w)}; }
; __device__ __forceinline__ f32x4 ror2v(f32x4 v) { return f32x4{dpp_ror2(v.x), dpp_ror2(v.y), dpp_ror2(v.z), dpp_ror2(v.w)}; }
; template <int EPI>
; __device__ __forceinline__ void epilogue(const Params& p, f32x4 (&acc)[2][2][4][2], const int pm, const int pn, const int wr, const int wc, const int fr, const int fq) {
;     ...
;             const int sidx = row - MP, b = sidx >> 2, tt = sidx & 3;
;             const f32x4 st0 = *(const f32x4*)(p.in[6] + ((size_t)b * 2 + 0) * DFF + j0);
;             const f32x4 st1 = *(const f32x4*)(p.in[6] + ((size_t)b * 2 + 1) * DFF + j0);
;             const f32x4 s1 = ror1v(a0), s2 = ror2v(a0);
;             am1 = (tt >= 1) ? s1 : st1;
;             am2 = (tt >= 2) ? s2 : ((tt == 1) ? st1 : st0);
;             if (tt >= 2) *(f32x4*)(p.out + O_CS + ((size_t)b * 2 + (tt - 2)) * DFF + j0) = a0;
	v_add_co_u32_e32 v102, vcc, 0x2000, v114
	v_mov_b32_e32 v110, 0
	s_nop 0
	v_addc_co_u32_e32 v103, vcc, 0, v115, vcc
	global_load_dwordx4 v[98:101], v[114:115], off
	s_nop 0
	global_load_dwordx4 v[102:105], v[102:103], off offset:3072
	v_mov_b32_e32 v111, 0
	v_mov_b32_e32 v112, 0
	v_mov_b32_e32 v113, 0
	v_mov_b32_e32 v106, 0
	v_mov_b32_e32 v107, 0
	v_mov_b32_e32 v108, 0
	v_mov_b32_e32 v109, 0
	v_mov_b32_dpp v110, v86 row_ror:1 row_mask:0xf bank_mask:0xf
	v_mov_b32_dpp v111, v87 row_ror:1 row_mask:0xf bank_mask:0xf
	v_mov_b32_dpp v112, v88 row_ror:1 row_mask:0xf bank_mask:0xf
	v_mov_b32_dpp v113, v89 row_ror:1 row_mask:0xf bank_mask:0xf
	v_mov_b32_dpp v106, v86 row_ror:2 row_mask:0xf bank_mask:0xf
	v_mov_b32_dpp v107, v87 row_ror:2 row_mask:0xf bank_mask:0xf
	v_mov_b32_dpp v108, v88 row_ror:2 row_mask:0xf bank_mask:0xf
	v_mov_b32_dpp v109, v89 row_ror:2 row_mask:0xf bank_mask:0xf
	s_waitcnt vmcnt(0)
	v_cndmask_b32_e64 v101, v101, v105, s[10:11]
	v_cndmask_b32_e64 v100, v100, v104, s[10:11]
	v_cndmask_b32_e64 v99, v99, v103, s[10:11]
	v_cndmask_b32_e64 v98, v98, v102, s[10:11]
	s_and_saveexec_b64 s[56:57], s[8:9]
	s_cbranch_execz .LBB0_1039
	v_lshl_add_u64 v[98:99], s[42:43], 0, v[118:119]
	v_lshl_add_u64 v[98:99], v[214:215], 2, v[98:99]
	global_store_dwordx4 v[98:99], v[86:89], off
	v_mov_b64_e32 v[98:99], v[106:107]
	v_mov_b64_e32 v[100:101], v[108:109]

; __device__ __forceinline__ u32x2 pk4(f32x4 v) { u32x2 r; r.x = pk2(v.x, v.y); r.y = pk2(v.z, v.w); return r; }
; template <int EPI>
; __device__ __forceinline__ void epilogue(const Params& p, f32x4 (&acc)[2][2][4][2], const int pm, const int pn, const int wr, const int wc, const int fr, const int fq) {
;     ...
;           const int j0 = jb + bj * 4;
;           const f32x4 a0 = acc[ai][bj][m][0], g = acc[ai][bj][m][1];
;           f32x4 am1, am2;
;           if (prompt) {
;             f32x4 o1 = f32x4{0.f, 0.f, 0.f, 0.f}, o2 = o1;
;             if (m > 0) { o1 = ror1v(acc[ai][bj][m > 0 ? m - 1 : 0][0]); o2 = ror2v(acc[ai][bj][m > 0 ? m - 1 : 0][0]); }
;             am1 = shr1v(o1, a0); am2 = shr2v(o2, a0);
;             if (m == 0 && fr < 2 && (row & 2047) >= 2) defer = true;
;             if (m == 3 && fr >= 14) *(f32x4*)(HA1 + ((size_t)(rblk >> 6) * 2 + (fr - 14)) * DFF + j0) = a0;
;             const int pos = row & 2047;
;             if (pos >= 2046) *(f32x4*)(p.out + O_CP + ((size_t)(row >> 11) * 2 + (pos - 2046)) * DFF + j0) = a0;
;           } else {
;             const int sidx = row - MP, b = sidx >> 2, tt = sidx & 3;
;             const f32x4 st0 = *(const f32x4*)(p.in[6] + ((size_t)b * 2 + 0) * DFF + j0);
;             const f32x4 st1 = *(const f32x4*)(p.in[6] + ((size_t)b * 2 + 1) * DFF + j0);
;             const f32x4 s1 = ror1v(a0), s2 = ror2v(a0);
;             am1 = (tt >= 1) ? s1 : st1;
;             am2 = (tt >= 2) ? s2 : ((tt == 1) ? st1 : st0);
;             if (tt >= 2) *(f32x4*)(p.out + O_CS + ((size_t)b * 2 + (tt - 2)) * DFF + j0) = a0;
;           }
;           f32x4 h;
;           h.x = gelu_tanh(cb[bj].x + w0[bj].x * am2.x + w1[bj].x * am1.x + w2[bj].x * a0.x) * g.x;
;           h.y = gelu_tanh(cb[bj].y + w0[bj].y * am2.y + w1[bj].y * am1.y + w2[bj].y * a0.y) * g.y;
;           h.z = gelu_tanh(cb[bj].z + w0[bj].z * am2.z + w1[bj].z * am1.z + w2[bj].z * a0.z) * g.z;
;           h.w = gelu_tanh(cb[bj].w + w0[bj].w * am2.w + w1[bj].w * am1.w + w2[bj].w * a0.w) * g.w;
;           ho[bj] = pk4(h);
;           if (defer) {
;             *(f32x4*)(HA0 + ((size_t)(rblk >> 6) * 2 + fr) * DFF + j0) = a0;
;             *(f32x4*)(HG0 + ((size_t)(rblk >> 6) * 2 + fr) * DFF + j0) = g;
;           }
;         }
;         if (!defer) *(u32x4*)(H + (size_t)row * DFF + jb) = u32x4{ho[0].x, ho[0].y, ho[1].x, ho[1].y};
.LBB0_1049:
	v_fma_f32 v98, v54, v98, v70
	v_fma_f32 v99, v55, v99, v71
	v_fma_f32 v100, v56, v100, v72
	v_fma_f32 v101, v57, v101, v73
	v_fma_f32 v98, v58, v102, v98
	v_fma_f32 v99, v59, v103, v99
	v_fma_f32 v100, v60, v104, v100
	v_fma_f32 v101, v61, v105, v101
	v_fma_f32 v98, v86, v66, v98
	v_fma_f32 v99, v87, v67, v99
	v_fma_f32 v100, v88, v68, v100
	v_fma_f32 v101, v89, v69, v101
	v_mul_f32_e32 v102, 0x3d372713, v98
	v_mul_f32_e32 v103, 0x3d372713, v99
	v_mul_f32_e32 v102, v98, v102
	v_mul_f32_e32 v103, v99, v103
	v_fma_f32 v102, v98, v102, v98
	v_fma_f32 v103, v99, v103, v99
	v_mul_f32_e32 v102, 0xbfcc422a, v102
	v_mul_f32_e32 v103, 0xbfcc422a, v103
	v_mul_f32_e32 v114, 0x3d372713, v100
	v_mul_f32_e32 v115, 0x3d372713, v101
	v_min_f32_e32 v102, 0x42a00000, v102
	v_min_f32_e32 v103, 0x42a00000, v103
	v_mul_f32_e32 v114, v100, v114
	v_mul_f32_e32 v115, v101, v115
	v_mul_f32_e32 v102, 0x3fb8aa3b, v102
	v_mul_f32_e32 v103, 0x3fb8aa3b, v103
	v_fma_f32 v114, v100, v114, v100
	v_fma_f32 v115, v101, v115, v101
	v_exp_f32_e32 v102, v102
	v_exp_f32_e32 v103, v103
	v_mul_f32_e32 v114, 0xbfcc422a, v114
	v_mul_f32_e32 v115, 0xbfcc422a, v115
	v_min_f32_e32 v114, 0x42a00000, v114
	v_min_f32_e32 v115, 0x42a00000, v115
	v_mul_f32_e32 v114, 0x3fb8aa3b, v114
	v_mul_f32_e32 v115, 0x3fb8aa3b, v115
	v_exp_f32_e32 v114, v114
	v_exp_f32_e32 v115, v115
	v_add_f32_e64 v102, v102, 1.0
	v_add_f32_e64 v103, v103, 1.0
	v_add_f32_e64 v114, v114, 1.0
	v_add_f32_e64 v115, v115, 1.0
	v_rcp_f32_e32 v104, v102
	v_rcp_f32_e32 v105, v103
	v_rcp_f32_e32 v116, v114
	v_rcp_f32_e32 v117, v115
	v_fma_f32 v102, -v102, v104, 1.0
	v_fma_f32 v103, -v103, v105, 1.0
	s_nop 0
	v_fma_f32 v102, v104, v102, v104
	v_fma_f32 v103, v105, v103, v105
	s_nop 0
	v_mul_f32_e64 v98, v98, v102
	v_mul_f32_e64 v99, v99, v103
	v_fma_f32 v102, v40, v108, v52
	v_fma_f32 v103, v41, v109, v53
	v_mul_f32_e64 v94, v94, v98
	v_mul_f32_e64 v95, v95, v99
	v_fma_f32 v98, -v114, v116, 1.0
	v_fma_f32 v99, -v115, v117, 1.0
	v_cvt_pk_bf16_f32 v94, v94, v95
	v_fma_f32 v98, v116, v98, v116
	v_fma_f32 v99, v117, v99, v117
	v_fma_f32 v102, v44, v112, v102
	v_fma_f32 v103, v45, v113, v103
	v_mul_f32_e64 v98, v100, v98
	v_mul_f32_e64 v99, v101, v99
	v_fma_f32 v102, v84, v48, v102
	v_fma_f32 v103, v85, v49, v103
	v_mul_f32_e64 v96, v96, v98
	v_mul_f32_e64 v97, v97, v99
	v_fma_f32 v98, v38, v106, v50
	v_fma_f32 v99, v39, v107, v51
	s_nop 0
	v_fma_f32 v98, v42, v110, v98
	v_fma_f32 v99, v43, v111, v99
	s_nop 0
	v_fma_f32 v98, v82, v46, v98
	v_fma_f32 v99, v83, v47, v99
	s_nop 0
	v_mul_f32_e32 v95, 0x3d372713, v98
	v_mul_f32_e32 v95, v98, v95
	v_fma_f32 v95, v98, v95, v98
	v_mul_f32_e32 v95, 0xbfcc422a, v95
	v_min_f32_e32 v95, 0x42a00000, v95
	v_mul_f32_e32 v95, 0x3fb8aa3b, v95
	v_exp_f32_e32 v100, v95
	v_mul_f32_e32 v95, 0x3d372713, v99
	v_mul_f32_e32 v95, v99, v95
	v_fma_f32 v95, v99, v95, v99
	v_mul_f32_e32 v95, 0xbfcc422a, v95
	v_min_f32_e32 v95, 0x42a00000, v95
	v_mul_f32_e32 v95, 0x3fb8aa3b, v95
	v_exp_f32_e32 v101, v95
	v_mul_f32_e32 v95, 0x3d372713, v102
	v_mul_f32_e32 v95, v102, v95
	v_fma_f32 v95, v102, v95, v102
	v_mul_f32_e32 v95, 0xbfcc422a, v95
	v_min_f32_e32 v95, 0x42a00000, v95
	v_mul_f32_e32 v95, 0x3fb8aa3b, v95
	v_exp_f32_e32 v106, v95
	v_mul_f32_e32 v95, 0x3d372713, v103
	v_mul_f32_e32 v95, v103, v95
	v_fma_f32 v95, v103, v95, v103
	v_mul_f32_e32 v95, 0xbfcc422a, v95
	v_min_f32_e32 v95, 0x42a00000, v95
	v_add_f32_e64 v100, v100, 1.0
	v_add_f32_e64 v101, v101, 1.0
	v_mul_f32_e32 v95, 0x3fb8aa3b, v95
	v_rcp_f32_e32 v104, v100
	v_rcp_f32_e32 v105, v101
	v_exp_f32_e32 v107, v95
	v_cvt_pk_bf16_f32 v95, v96, v97
	v_fma_f32 v96, -v100, v104, 1.0
	v_fma_f32 v97, -v101, v105, 1.0
	v_add_f32_e64 v100, v106, 1.0
	v_add_f32_e64 v101, v107, 1.0
	v_fma_f32 v96, v104, v96, v104
	v_fma_f32 v97, v105, v97, v105
	v_rcp_f32_e32 v104, v100
	v_rcp_f32_e32 v105, v101
	v_mul_f32_e64 v96, v98, v96
	v_mul_f32_e64 v97, v99, v97
	v_fma_f32 v98, -v100, v104, 1.0
	v_fma_f32 v99, -v101, v105, 1.0
	s_nop 0
	v_fma_f32 v98, v104, v98, v104
	v_fma_f32 v99, v105, v99, v105
	v_mul_f32_e64 v96, v90, v96
	v_mul_f32_e64 v97, v91, v97
	v_mul_f32_e64 v98, v102, v98
	v_mul_f32_e64 v99, v103, v99
	v_cvt_pk_bf16_f32 v96, v96, v97
	v_mul_f32_e64 v98, v92, v98
	v_mul_f32_e64 v99, v93, v99
	s_nop 0
	v_cvt_pk_bf16_f32 v97, v98, v99
	v_mad_i64_i32 v[98:99], s[58:59], v124, s79, v[178:179]
	global_store_dwordx4 v[98:99], v[94:97], off
	s_andn2_saveexec_b64 s[56:57], s[56:57]
	s_cbranch_execnz .LBB0_1053
	s_branch .LBB0_1054

; __device__ __forceinline__ u32x2 pk4(f32x4 v) { u32x2 r; r.x = pk2(v.x, v.y); r.y = pk2(v.z, v.w); return r; }
; template <int EPI>
; __device__ __forceinline__ void epilogue(const Params& p, f32x4 (&acc)[2][2][4][2], const int pm, const int pn, const int wr, const int wc, const int fr, const int fq) {
;     ...
;           const int j0 = jb + bj * 4;
;           const f32x4 a0 = acc[ai][bj][m][0], g = acc[ai][bj][m][1];
;           f32x4 am1, am2;
;           if (prompt) {
;             f32x4 o1 = f32x4{0.f, 0.f, 0.f, 0.f}, o2 = o1;
;             if (m > 0) { o1 = ror1v(acc[ai][bj][m > 0 ? m - 1 : 0][0]); o2 = ror2v(acc[ai][bj][m > 0 ? m - 1 : 0][0]); }
;             am1 = shr1v(o1, a0); am2 = shr2v(o2, a0);
;             if (m == 0 && fr < 2 && (row & 2047) >= 2) defer = true;
;             if (m == 3 && fr >= 14) *(f32x4*)(HA1 + ((size_t)(rblk >> 6) * 2 + (fr - 14)) * DFF + j0) = a0;
;             const int pos = row & 2047;
;             if (pos >= 2046) *(f32x4*)(p.out + O_CP + ((size_t)(row >> 11) * 2 + (pos - 2046)) * DFF + j0) = a0;
;           } else {
;             const int sidx = row - MP, b = sidx >> 2, tt = sidx & 3;
;             const f32x4 st0 = *(const f32x4*)(p.in[6] + ((size_t)b * 2 + 0) * DFF + j0);
;             const f32x4 st1 = *(const f32x4*)(p.in[6] + ((size_t)b * 2 + 1) * DFF + j0);
;             const f32x4 s1 = ror1v(a0), s2 = ror2v(a0);
;             am1 = (tt >= 1) ? s1 : st1;
;             am2 = (tt >= 2) ? s2 : ((tt == 1) ? st1 : st0);
;             if (tt >= 2) *(f32x4*)(p.out + O_CS + ((size_t)b * 2 + (tt - 2)) * DFF + j0) = a0;
;           }
;           f32x4 h;
;           h.x = gelu_tanh(cb[bj].x + w0[bj].x * am2.x + w1[bj].x * am1.x + w2[bj].x * a0.x) * g.x;
;           h.y = gelu_tanh(cb[bj].y + w0[bj].y * am2.y + w1[bj].y * am1.y + w2[bj].y * a0.y) * g.y;
;           h.z = gelu_tanh(cb[bj].z + w0[bj].z * am2.z + w1[bj].z * am1.z + w2[bj].z * a0.z) * g.z;
;           h.w = gelu_tanh(cb[bj].w + w0[bj].w * am2.w + w1[bj].w * am1.w + w2[bj].w * a0.w) * g.w;
;           ho[bj] = pk4(h);
;           if (defer) {
;             *(f32x4*)(HA0 + ((size_t)(rblk >> 6) * 2 + fr) * DFF + j0) = a0;
;             *(f32x4*)(HG0 + ((size_t)(rblk >> 6) * 2 + fr) * DFF + j0) = g;
;           }
;         }
;         if (!defer) *(u32x4*)(H + (size_t)row * DFF + jb) = u32x4{ho[0].x, ho[0].y, ho[1].x, ho[1].y};
.LBB0_1066:
	v_fma_f32 v82, v54, v90, v70
	v_fma_f32 v83, v55, v91, v71
	v_fma_f32 v90, v56, v92, v72
	v_fma_f32 v91, v57, v93, v73
	v_fma_f32 v82, v58, v94, v82
	v_fma_f32 v83, v59, v95, v83
	v_fma_f32 v90, v60, v96, v90
	v_fma_f32 v91, v61, v97, v91
	v_fma_f32 v82, v62, v66, v82
	v_fma_f32 v83, v63, v67, v83
	v_fma_f32 v90, v64, v68, v90
	v_fma_f32 v91, v65, v69, v91
	v_mul_f32_e32 v84, 0x3d372713, v82
	v_mul_f32_e32 v85, 0x3d372713, v83
	v_mul_f32_e32 v84, v82, v84
	v_mul_f32_e32 v85, v83, v85
	v_fma_f32 v84, v82, v84, v82
	v_fma_f32 v85, v83, v85, v83
	v_mul_f32_e32 v84, 0xbfcc422a, v84
	v_mul_f32_e32 v85, 0xbfcc422a, v85
	v_mul_f32_e32 v94, 0x3d372713, v90
	v_mul_f32_e32 v95, 0x3d372713, v91
	v_min_f32_e32 v84, 0x42a00000, v84
	v_min_f32_e32 v85, 0x42a00000, v85
	v_mul_f32_e32 v94, v90, v94
	v_mul_f32_e32 v95, v91, v95
	v_mul_f32_e32 v84, 0x3fb8aa3b, v84
	v_mul_f32_e32 v85, 0x3fb8aa3b, v85
	v_fma_f32 v94, v90, v94, v90
	v_fma_f32 v95, v91, v95, v91
	v_exp_f32_e32 v84, v84
	v_exp_f32_e32 v85, v85
	v_mul_f32_e32 v94, 0xbfcc422a, v94
	v_mul_f32_e32 v95, 0xbfcc422a, v95
	v_min_f32_e32 v94, 0x42a00000, v94
	v_min_f32_e32 v95, 0x42a00000, v95
	v_mul_f32_e32 v94, 0x3fb8aa3b, v94
	v_mul_f32_e32 v95, 0x3fb8aa3b, v95
	v_exp_f32_e32 v94, v94
	v_exp_f32_e32 v95, v95
	v_add_f32_e64 v84, v84, 1.0
	v_add_f32_e64 v85, v85, 1.0
	s_nop 1
	v_readlane_b32 s80, v244, 14
	v_rcp_f32_e32 v92, v84
	v_rcp_f32_e32 v93, v85
	v_add_f32_e64 v94, v94, 1.0
	v_add_f32_e64 v95, v95, 1.0
	s_nop 1
	v_readlane_b32 s92, v244, 26
	v_rcp_f32_e32 v96, v94
	v_rcp_f32_e32 v97, v95
	v_fma_f32 v84, -v84, v92, 1.0
	v_fma_f32 v85, -v85, v93, 1.0
	s_nop 1
	v_readlane_b32 s93, v244, 27
	v_fma_f32 v84, v92, v84, v92
	v_fma_f32 v85, v93, v85, v93
	v_or_b32_e32 v92, 16, v124
	v_mul_f32_e64 v82, v82, v84
	v_mul_f32_e64 v83, v83, v85
	s_and_b64 vcc, exec, s[18:19]
	v_mul_f32_e64 v78, v78, v82
	v_mul_f32_e64 v79, v79, v83
	v_fma_f32 v82, -v94, v96, 1.0
	v_fma_f32 v83, -v95, v97, 1.0
	v_cvt_pk_bf16_f32 v78, v78, v79
	v_fma_f32 v82, v96, v82, v96
	v_fma_f32 v83, v97, v83, v97
	s_nop 1
	v_readlane_b32 s81, v244, 15
	v_mul_f32_e64 v82, v90, v82
	v_mul_f32_e64 v83, v91, v83
	s_nop 1
	v_readlane_b32 s82, v244, 16
	v_mul_f32_e64 v80, v80, v82
	v_mul_f32_e64 v81, v81, v83
	v_fma_f32 v82, v38, v86, v50
	v_fma_f32 v83, v39, v87, v51
	v_fma_f32 v86, v40, v88, v52
	v_fma_f32 v87, v41, v89, v53
	v_fma_f32 v82, v42, v98, v82
	v_fma_f32 v83, v43, v99, v83
	v_fma_f32 v86, v44, v100, v86
	v_fma_f32 v87, v45, v101, v87
	v_fma_f32 v82, v34, v46, v82
	v_fma_f32 v83, v35, v47, v83
	v_fma_f32 v86, v36, v48, v86
	v_fma_f32 v87, v37, v49, v87
	v_mul_f32_e32 v79, 0x3d372713, v82
	v_mul_f32_e32 v79, v82, v79
	v_fma_f32 v79, v82, v79, v82
	v_mul_f32_e32 v79, 0xbfcc422a, v79
	v_min_f32_e32 v79, 0x42a00000, v79
	v_mul_f32_e32 v79, 0x3fb8aa3b, v79
	v_exp_f32_e32 v84, v79
	v_mul_f32_e32 v79, 0x3d372713, v83
	v_mul_f32_e32 v79, v83, v79
	v_fma_f32 v79, v83, v79, v83
	v_mul_f32_e32 v79, 0xbfcc422a, v79
	v_min_f32_e32 v79, 0x42a00000, v79
	v_mul_f32_e32 v79, 0x3fb8aa3b, v79
	v_exp_f32_e32 v85, v79
	v_mul_f32_e32 v79, 0x3d372713, v86
	v_mul_f32_e32 v79, v86, v79
	v_fma_f32 v79, v86, v79, v86
	v_mul_f32_e32 v79, 0xbfcc422a, v79
	v_min_f32_e32 v79, 0x42a00000, v79
	v_mul_f32_e32 v79, 0x3fb8aa3b, v79
	v_exp_f32_e32 v90, v79
	v_mul_f32_e32 v79, 0x3d372713, v87
	v_mul_f32_e32 v79, v87, v79
	v_fma_f32 v79, v87, v79, v87
	v_mul_f32_e32 v79, 0xbfcc422a, v79
	v_min_f32_e32 v79, 0x42a00000, v79
	v_add_f32_e64 v84, v84, 1.0
	v_add_f32_e64 v85, v85, 1.0
	v_mul_f32_e32 v79, 0x3fb8aa3b, v79
	v_rcp_f32_e32 v88, v84
	v_rcp_f32_e32 v89, v85
	v_exp_f32_e32 v91, v79
	v_cvt_pk_bf16_f32 v79, v80, v81
	v_readlane_b32 s83, v244, 17
	v_fma_f32 v80, -v84, v88, 1.0
	v_fma_f32 v81, -v85, v89, 1.0
	v_add_f32_e64 v84, v90, 1.0
	v_add_f32_e64 v85, v91, 1.0
	v_fma_f32 v80, v88, v80, v88
	v_fma_f32 v81, v89, v81, v89
	v_rcp_f32_e32 v90, v84
	v_rcp_f32_e32 v91, v85
	v_mul_f32_e64 v80, v82, v80
	v_mul_f32_e64 v81, v83, v81
	s_nop 1
	v_readlane_b32 s84, v244, 18
	v_mul_f32_e64 v74, v74, v80
	v_mul_f32_e64 v75, v75, v81
	s_nop 1
	v_fma_f32 v80, -v84, v90, 1.0
	v_fma_f32 v81, -v85, v91, 1.0
	s_nop 1
	v_readlane_b32 s85, v244, 19
	v_fma_f32 v80, v90, v80, v90
	v_fma_f32 v81, v91, v81, v91
	s_nop 1
	v_readlane_b32 s86, v244, 20
	v_mul_f32_e64 v80, v86, v80
	v_mul_f32_e64 v81, v87, v81
	s_nop 1
	v_readlane_b32 s87, v244, 21
	v_mul_f32_e64 v76, v76, v80
	v_mul_f32_e64 v77, v77, v81
	v_cvt_pk_bf16_f32 v80, v74, v75
	v_cvt_pk_bf16_f32 v81, v76, v77
	v_mad_i64_i32 v[74:75], s[56:57], v92, s79, v[178:179]
	global_store_dwordx4 v[74:75], v[78:81], off
	v_add_u32_e32 v74, 0xffffc020, v124
	v_ashrrev_i32_e32 v74, 2, v74
	v_ashrrev_i32_e32 v75, 31, v74
	v_mad_i64_i32 v[76:77], s[56:57], v74, s77, 0
	v_lshl_add_u64 v[74:75], v[74:75], 1, v[202:203]
	v_mad_u64_u32 v[90:91], s[56:57], v74, s78, 0
	v_lshl_add_u64 v[88:89], s[92:93], 0, v[76:77]
	v_mad_i32_i24 v91, v75, s78, v91
	s_mov_b64 s[56:57], -1
	v_lshl_add_u64 v[86:87], v[214:215], 2, v[88:89]
	v_readlane_b32 s88, v244, 22
	v_readlane_b32 s89, v244, 23
	v_readlane_b32 s90, v244, 24
	v_readlane_b32 s91, v244, 25
	v_readlane_b32 s94, v244, 28
	v_readlane_b32 s95, v244, 29
	s_cbranch_vccnz .LBB0_1070
	v_add_co_u32_e32 v78, vcc, 0x2000, v86
	v_mov_b32_e32 v92, 0
	s_nop 0
	v_addc_co_u32_e32 v79, vcc, 0, v87, vcc
	global_load_dwordx4 v[74:77], v[86:87], off
	s_nop 0
	global_load_dwordx4 v[78:81], v[78:79], off offset:3072
	v_mov_b32_e32 v93, 0
	v_mov_b32_e32 v94, 0
	v_mov_b32_e32 v95, 0
	v_mov_b32_e32 v82, 0
	v_mov_b32_e32 v83, 0
	v_mov_b32_e32 v84, 0
	v_mov_b32_e32 v85, 0
	v_mov_b32_dpp v92, v22 row_ror:1 row_mask:0xf bank_mask:0xf
	v_mov_b32_dpp v93, v23 row_ror:1 row_mask:0xf bank_mask:0xf
	v_mov_b32_dpp v94, v24 row_ror:1 row_mask:0xf bank_mask:0xf
	v_mov_b32_dpp v95, v25 row_ror:1 row_mask:0xf bank_mask:0xf
	v_mov_b32_dpp v82, v22 row_ror:2 row_mask:0xf bank_mask:0xf
	v_mov_b32_dpp v83, v23 row_ror:2 row_mask:0xf bank_mask:0xf
	v_mov_b32_dpp v84, v24 row_ror:2 row_mask:0xf bank_mask:0xf
	v_mov_b32_dpp v85, v25 row_ror:2 row_mask:0xf bank_mask:0xf
	s_waitcnt vmcnt(0)
	v_cndmask_b32_e64 v77, v77, v81, s[10:11]
	v_cndmask_b32_e64 v76, v76, v80, s[10:11]
	v_cndmask_b32_e64 v75, v75, v79, s[10:11]
	v_cndmask_b32_e64 v74, v74, v78, s[10:11]
	s_and_saveexec_b64 s[56:57], s[8:9]
	s_cbranch_execz .LBB0_1069
	v_lshl_add_u64 v[74:75], s[42:43], 0, v[90:91]
	v_lshl_add_u64 v[74:75], v[214:215], 2, v[74:75]
	global_store_dwordx4 v[74:75], v[22:25], off
	v_mov_b64_e32 v[74:75], v[82:83]
	v_mov_b64_e32 v[76:77], v[84:85]

; __device__ __forceinline__ u32x2 pk4(f32x4 v) { u32x2 r; r.x = pk2(v.x, v.y); r.y = pk2(v.z, v.w); return r; }
; template <int EPI>
; __device__ __forceinline__ void epilogue(const Params& p, f32x4 (&acc)[2][2][4][2], const int pm, const int pn, const int wr, const int wc, const int fr, const int fq) {
;     ...
;           const int j0 = jb + bj * 4;
;           const f32x4 a0 = acc[ai][bj][m][0], g = acc[ai][bj][m][1];
;           f32x4 am1, am2;
;           if (prompt) {
;             f32x4 o1 = f32x4{0.f, 0.f, 0.f, 0.f}, o2 = o1;
;             if (m > 0) { o1 = ror1v(acc[ai][bj][m > 0 ? m - 1 : 0][0]); o2 = ror2v(acc[ai][bj][m > 0 ? m - 1 : 0][0]); }
;             am1 = shr1v(o1, a0); am2 = shr2v(o2, a0);
;             if (m == 0 && fr < 2 && (row & 2047) >= 2) defer = true;
;             if (m == 3 && fr >= 14) *(f32x4*)(HA1 + ((size_t)(rblk >> 6) * 2 + (fr - 14)) * DFF + j0) = a0;
;             const int pos = row & 2047;
;             if (pos >= 2046) *(f32x4*)(p.out + O_CP + ((size_t)(row >> 11) * 2 + (pos - 2046)) * DFF + j0) = a0;
;           } else {
;             const int sidx = row - MP, b = sidx >> 2, tt = sidx & 3;
;             const f32x4 st0 = *(const f32x4*)(p.in[6] + ((size_t)b * 2 + 0) * DFF + j0);
;             const f32x4 st1 = *(const f32x4*)(p.in[6] + ((size_t)b * 2 + 1) * DFF + j0);
;             const f32x4 s1 = ror1v(a0), s2 = ror2v(a0);
;             am1 = (tt >= 1) ? s1 : st1;
;             am2 = (tt >= 2) ? s2 : ((tt == 1) ? st1 : st0);
;             if (tt >= 2) *(f32x4*)(p.out + O_CS + ((size_t)b * 2 + (tt - 2)) * DFF + j0) = a0;
;           }
;           f32x4 h;
;           h.x = gelu_tanh(cb[bj].x + w0[bj].x * am2.x + w1[bj].x * am1.x + w2[bj].x * a0.x) * g.x;
;           h.y = gelu_tanh(cb[bj].y + w0[bj].y * am2.y + w1[bj].y * am1.y + w2[bj].y * a0.y) * g.y;
;           h.z = gelu_tanh(cb[bj].z + w0[bj].z * am2.z + w1[bj].z * am1.z + w2[bj].z * a0.z) * g.z;
;           h.w = gelu_tanh(cb[bj].w + w0[bj].w * am2.w + w1[bj].w * am1.w + w2[bj].w * a0.w) * g.w;
;           ho[bj] = pk4(h);
;           if (defer) {
;             *(f32x4*)(HA0 + ((size_t)(rblk >> 6) * 2 + fr) * DFF + j0) = a0;
;             *(f32x4*)(HG0 + ((size_t)(rblk >> 6) * 2 + fr) * DFF + j0) = g;
;           }
;         }
;         if (!defer) *(u32x4*)(H + (size_t)row * DFF + jb) = u32x4{ho[0].x, ho[0].y, ho[1].x, ho[1].y};
.LBB0_1078:
	v_fma_f32 v34, v54, v74, v70
	v_fma_f32 v35, v55, v75, v71
	v_fma_f32 v74, v56, v76, v72
	v_fma_f32 v75, v57, v77, v73
	v_fma_f32 v34, v58, v78, v34
	v_fma_f32 v35, v59, v79, v35
	v_fma_f32 v74, v60, v80, v74
	v_fma_f32 v75, v61, v81, v75
	v_fma_f32 v34, v22, v66, v34
	v_fma_f32 v35, v23, v67, v35
	v_fma_f32 v74, v24, v68, v74
	v_fma_f32 v75, v25, v69, v75
	v_mul_f32_e32 v36, 0x3d372713, v34
	v_mul_f32_e32 v37, 0x3d372713, v35
	v_mul_f32_e32 v36, v34, v36
	v_mul_f32_e32 v37, v35, v37
	v_fma_f32 v36, v34, v36, v34
	v_fma_f32 v37, v35, v37, v35
	v_mul_f32_e32 v36, 0xbfcc422a, v36
	v_mul_f32_e32 v37, 0xbfcc422a, v37
	v_mul_f32_e32 v78, 0x3d372713, v74
	v_mul_f32_e32 v79, 0x3d372713, v75
	v_min_f32_e32 v36, 0x42a00000, v36
	v_min_f32_e32 v37, 0x42a00000, v37
	v_mul_f32_e32 v78, v74, v78
	v_mul_f32_e32 v79, v75, v79
	v_mul_f32_e32 v36, 0x3fb8aa3b, v36
	v_mul_f32_e32 v37, 0x3fb8aa3b, v37
	v_fma_f32 v78, v74, v78, v74
	v_fma_f32 v79, v75, v79, v75
	v_exp_f32_e32 v36, v36
	v_exp_f32_e32 v37, v37
	v_mul_f32_e32 v78, 0xbfcc422a, v78
	v_mul_f32_e32 v79, 0xbfcc422a, v79
	v_min_f32_e32 v78, 0x42a00000, v78
	v_min_f32_e32 v79, 0x42a00000, v79
	v_mul_f32_e32 v78, 0x3fb8aa3b, v78
	v_mul_f32_e32 v79, 0x3fb8aa3b, v79
	v_exp_f32_e32 v78, v78
	v_exp_f32_e32 v79, v79
	v_add_f32_e64 v36, v36, 1.0
	v_add_f32_e64 v37, v37, 1.0
	s_nop 1
	v_readlane_b32 s80, v244, 14
	v_rcp_f32_e32 v76, v36
	v_rcp_f32_e32 v77, v37
	v_add_f32_e64 v78, v78, 1.0
	v_add_f32_e64 v79, v79, 1.0
	s_nop 1
	v_readlane_b32 s92, v244, 26
	v_rcp_f32_e32 v80, v78
	v_rcp_f32_e32 v81, v79
	v_fma_f32 v36, -v36, v76, 1.0
	v_fma_f32 v37, -v37, v77, 1.0
	s_nop 1
	v_readlane_b32 s93, v244, 27
	v_fma_f32 v36, v76, v36, v76
	v_fma_f32 v37, v77, v37, v77
	v_or_b32_e32 v76, 32, v124
	v_mul_f32_e64 v34, v34, v36
	v_mul_f32_e64 v35, v35, v37
	s_and_b64 vcc, exec, s[18:19]
	v_mul_f32_e64 v30, v30, v34
	v_mul_f32_e64 v31, v31, v35
	v_fma_f32 v34, -v78, v80, 1.0
	v_fma_f32 v35, -v79, v81, 1.0
	v_cvt_pk_bf16_f32 v30, v30, v31
	v_fma_f32 v34, v80, v34, v80
	v_fma_f32 v35, v81, v35, v81
	v_bitop3_b32 v80, v124, s0, 48 bitop3:0xc8
	v_mul_f32_e64 v34, v74, v34
	v_mul_f32_e64 v35, v75, v35
	s_nop 1
	v_readlane_b32 s81, v244, 15
	v_mul_f32_e64 v32, v32, v34
	v_mul_f32_e64 v33, v33, v35
	v_fma_f32 v34, v38, v62, v50
	v_fma_f32 v35, v39, v63, v51
	v_fma_f32 v62, v40, v64, v52
	v_fma_f32 v63, v41, v65, v53
	v_fma_f32 v34, v42, v82, v34
	v_fma_f32 v35, v43, v83, v35
	v_fma_f32 v62, v44, v84, v62
	v_fma_f32 v63, v45, v85, v63
	v_fma_f32 v34, v18, v46, v34
	v_fma_f32 v35, v19, v47, v35
	v_fma_f32 v62, v20, v48, v62
	v_fma_f32 v63, v21, v49, v63
	v_mul_f32_e32 v31, 0x3d372713, v34
	v_mul_f32_e32 v31, v34, v31
	v_fma_f32 v31, v34, v31, v34
	v_mul_f32_e32 v31, 0xbfcc422a, v31
	v_min_f32_e32 v31, 0x42a00000, v31
	v_mul_f32_e32 v31, 0x3fb8aa3b, v31
	v_exp_f32_e32 v36, v31
	v_mul_f32_e32 v31, 0x3d372713, v35
	v_mul_f32_e32 v31, v35, v31
	v_fma_f32 v31, v35, v31, v35
	v_mul_f32_e32 v31, 0xbfcc422a, v31
	v_min_f32_e32 v31, 0x42a00000, v31
	v_mul_f32_e32 v31, 0x3fb8aa3b, v31
	v_exp_f32_e32 v37, v31
	v_mul_f32_e32 v31, 0x3d372713, v62
	v_mul_f32_e32 v31, v62, v31
	v_fma_f32 v31, v62, v31, v62
	v_mul_f32_e32 v31, 0xbfcc422a, v31
	v_min_f32_e32 v31, 0x42a00000, v31
	v_mul_f32_e32 v31, 0x3fb8aa3b, v31
	v_exp_f32_e32 v74, v31
	v_mul_f32_e32 v31, 0x3d372713, v63
	v_mul_f32_e32 v31, v63, v31
	v_fma_f32 v31, v63, v31, v63
	v_mul_f32_e32 v31, 0xbfcc422a, v31
	v_min_f32_e32 v31, 0x42a00000, v31
	v_add_f32_e64 v36, v36, 1.0
	v_add_f32_e64 v37, v37, 1.0
	v_mul_f32_e32 v31, 0x3fb8aa3b, v31
	v_rcp_f32_e32 v64, v36
	v_rcp_f32_e32 v65, v37
	v_exp_f32_e32 v75, v31
	v_cvt_pk_bf16_f32 v31, v32, v33
	v_readlane_b32 s82, v244, 16
	v_fma_f32 v32, -v36, v64, 1.0
	v_fma_f32 v33, -v37, v65, 1.0
	v_add_f32_e64 v36, v74, 1.0
	v_add_f32_e64 v37, v75, 1.0
	v_fma_f32 v32, v64, v32, v64
	v_fma_f32 v33, v65, v33, v65
	v_rcp_f32_e32 v74, v36
	v_rcp_f32_e32 v75, v37
	v_mul_f32_e64 v32, v34, v32
	v_mul_f32_e64 v33, v35, v33
	s_nop 1
	v_readlane_b32 s83, v244, 17
	v_mul_f32_e64 v26, v26, v32
	v_mul_f32_e64 v27, v27, v33
	s_nop 1
	v_fma_f32 v32, -v36, v74, 1.0
	v_fma_f32 v33, -v37, v75, 1.0
	s_nop 1
	v_readlane_b32 s84, v244, 18
	v_fma_f32 v32, v74, v32, v74
	v_fma_f32 v33, v75, v33, v75
	s_nop 1
	v_readlane_b32 s85, v244, 19
	v_mul_f32_e64 v32, v62, v32
	v_mul_f32_e64 v33, v63, v33
	s_nop 1
	v_readlane_b32 s86, v244, 20
	v_mul_f32_e64 v28, v28, v32
	v_mul_f32_e64 v29, v29, v33
	v_cvt_pk_bf16_f32 v32, v26, v27
	v_cvt_pk_bf16_f32 v33, v28, v29
	v_mad_i64_i32 v[26:27], s[56:57], v76, s79, v[178:179]
	global_store_dwordx4 v[26:27], v[30:33], off
	v_add_u32_e32 v26, 0xffffc030, v124
	v_ashrrev_i32_e32 v76, 2, v26
	v_mad_i64_i32 v[26:27], s[56:57], v76, s77, 0
	v_lshl_add_u64 v[64:65], s[92:93], 0, v[26:27]
	v_cmp_lt_u32_e64 s[56:57], s1, v80
	v_lshl_add_u64 v[62:63], v[214:215], 2, v[64:65]
	v_readlane_b32 s87, v244, 21
	v_readlane_b32 s88, v244, 22
	v_readlane_b32 s89, v244, 23
	v_readlane_b32 s90, v244, 24
	v_readlane_b32 s91, v244, 25
	v_readlane_b32 s94, v244, 28
	v_readlane_b32 s95, v244, 29
	s_cbranch_vccnz .LBB0_1082
	v_add_co_u32_e32 v30, vcc, 0x2000, v62
	v_mov_b32_e32 v74, 0
	s_nop 0
	v_addc_co_u32_e32 v31, vcc, 0, v63, vcc
	global_load_dwordx4 v[26:29], v[62:63], off
	s_nop 0
	global_load_dwordx4 v[30:33], v[30:31], off offset:3072
	v_mov_b32_e32 v75, 0
	v_mov_b32_e32 v77, 0
	v_mov_b32_e32 v78, 0
	v_mov_b32_e32 v34, 0
	v_mov_b32_e32 v35, 0
	v_mov_b32_e32 v36, 0
	v_mov_b32_e32 v37, 0
	s_mov_b64 s[60:61], 0
	v_mov_b32_dpp v74, v14 row_ror:1 row_mask:0xf bank_mask:0xf
	v_mov_b32_dpp v75, v15 row_ror:1 row_mask:0xf bank_mask:0xf
	v_mov_b32_dpp v77, v16 row_ror:1 row_mask:0xf bank_mask:0xf
	v_mov_b32_dpp v78, v17 row_ror:1 row_mask:0xf bank_mask:0xf
	v_mov_b32_dpp v34, v14 row_ror:2 row_mask:0xf bank_mask:0xf
	v_mov_b32_dpp v35, v15 row_ror:2 row_mask:0xf bank_mask:0xf
	v_mov_b32_dpp v36, v16 row_ror:2 row_mask:0xf bank_mask:0xf
	v_mov_b32_dpp v37, v17 row_ror:2 row_mask:0xf bank_mask:0xf
	s_mov_b64 s[58:59], 0
	s_waitcnt vmcnt(0)
	v_cndmask_b32_e64 v29, v29, v33, s[10:11]
	v_cndmask_b32_e64 v28, v28, v32, s[10:11]
	v_cndmask_b32_e64 v27, v27, v31, s[10:11]
	v_cndmask_b32_e64 v26, v26, v30, s[10:11]
	s_and_saveexec_b64 s[62:63], s[8:9]
	v_mov_b64_e32 v[26:27], v[34:35]
	s_mov_b64 s[58:59], exec
	v_mov_b64_e32 v[28:29], v[36:37]
	s_or_b64 exec, exec, s[62:63]
	v_cndmask_b32_e64 v33, v78, v33, s[6:7]
	v_cndmask_b32_e64 v32, v77, v32, s[6:7]
	v_cndmask_b32_e64 v31, v75, v31, s[6:7]
	v_cndmask_b32_e64 v30, v74, v30, s[6:7]
	s_branch .LBB0_1083

; __device__ __forceinline__ u32x2 pk4(f32x4 v) { u32x2 r; r.x = pk2(v.x, v.y); r.y = pk2(v.z, v.w); return r; }
; template <int EPI>
; __device__ __forceinline__ void epilogue(const Params& p, f32x4 (&acc)[2][2][4][2], const int pm, const int pn, const int wr, const int wc, const int fr, const int fq) {
;     ...
;           const int j0 = jb + bj * 4;
;           const f32x4 a0 = acc[ai][bj][m][0], g = acc[ai][bj][m][1];
;           f32x4 am1, am2;
;           if (prompt) {
;             f32x4 o1 = f32x4{0.f, 0.f, 0.f, 0.f}, o2 = o1;
;             if (m > 0) { o1 = ror1v(acc[ai][bj][m > 0 ? m - 1 : 0][0]); o2 = ror2v(acc[ai][bj][m > 0 ? m - 1 : 0][0]); }
;             am1 = shr1v(o1, a0); am2 = shr2v(o2, a0);
;             if (m == 0 && fr < 2 && (row & 2047) >= 2) defer = true;
;             if (m == 3 && fr >= 14) *(f32x4*)(HA1 + ((size_t)(rblk >> 6) * 2 + (fr - 14)) * DFF + j0) = a0;
;             const int pos = row & 2047;
;             if (pos >= 2046) *(f32x4*)(p.out + O_CP + ((size_t)(row >> 11) * 2 + (pos - 2046)) * DFF + j0) = a0;
;           } else {
;             const int sidx = row - MP, b = sidx >> 2, tt = sidx & 3;
;             const f32x4 st0 = *(const f32x4*)(p.in[6] + ((size_t)b * 2 + 0) * DFF + j0);
;             const f32x4 st1 = *(const f32x4*)(p.in[6] + ((size_t)b * 2 + 1) * DFF + j0);
;             const f32x4 s1 = ror1v(a0), s2 = ror2v(a0);
;             am1 = (tt >= 1) ? s1 : st1;
;             am2 = (tt >= 2) ? s2 : ((tt == 1) ? st1 : st0);
;             if (tt >= 2) *(f32x4*)(p.out + O_CS + ((size_t)b * 2 + (tt - 2)) * DFF + j0) = a0;
;           }
;           f32x4 h;
;           h.x = gelu_tanh(cb[bj].x + w0[bj].x * am2.x + w1[bj].x * am1.x + w2[bj].x * a0.x) * g.x;
;           h.y = gelu_tanh(cb[bj].y + w0[bj].y * am2.y + w1[bj].y * am1.y + w2[bj].y * a0.y) * g.y;
;           h.z = gelu_tanh(cb[bj].z + w0[bj].z * am2.z + w1[bj].z * am1.z + w2[bj].z * a0.z) * g.z;
;           h.w = gelu_tanh(cb[bj].w + w0[bj].w * am2.w + w1[bj].w * am1.w + w2[bj].w * a0.w) * g.w;
;           ho[bj] = pk4(h);
;           if (defer) {
;             *(f32x4*)(HA0 + ((size_t)(rblk >> 6) * 2 + fr) * DFF + j0) = a0;
;             *(f32x4*)(HG0 + ((size_t)(rblk >> 6) * 2 + fr) * DFF + j0) = g;
;           }
;         }
;         if (!defer) *(u32x4*)(H + (size_t)row * DFF + jb) = u32x4{ho[0].x, ho[0].y, ho[1].x, ho[1].y};
.LBB0_1099:
	v_fma_f32 v20, v54, v26, v70
	v_fma_f32 v21, v55, v27, v71
	v_fma_f32 v26, v56, v28, v72
	v_fma_f32 v27, v57, v29, v73
	v_fma_f32 v20, v58, v30, v20
	v_fma_f32 v21, v59, v31, v21
	v_fma_f32 v26, v60, v32, v26
	v_fma_f32 v27, v61, v33, v27
	v_fma_f32 v14, v14, v66, v20
	v_fma_f32 v15, v15, v67, v21
	v_fma_f32 v16, v16, v68, v26
	v_fma_f32 v17, v17, v69, v27
	v_mul_f32_e32 v19, 0x3d372713, v14
	v_mul_f32_e32 v19, v14, v19
	v_fma_f32 v19, v14, v19, v14
	v_mul_f32_e32 v19, 0xbfcc422a, v19
	v_min_f32_e32 v19, 0x42a00000, v19
	v_mul_f32_e32 v19, 0x3fb8aa3b, v19
	v_exp_f32_e32 v20, v19
	v_mul_f32_e32 v19, 0x3d372713, v15
	v_mul_f32_e32 v19, v15, v19
	v_fma_f32 v19, v15, v19, v15
	v_mul_f32_e32 v19, 0xbfcc422a, v19
	v_min_f32_e32 v19, 0x42a00000, v19
	v_mul_f32_e32 v19, 0x3fb8aa3b, v19
	v_exp_f32_e32 v21, v19
	v_mul_f32_e32 v19, 0x3d372713, v16
	v_mul_f32_e32 v19, v16, v19
	v_fma_f32 v19, v16, v19, v16
	v_mul_f32_e32 v19, 0xbfcc422a, v19
	v_min_f32_e32 v19, 0x42a00000, v19
	v_mul_f32_e32 v19, 0x3fb8aa3b, v19
	v_exp_f32_e32 v28, v19
	v_mul_f32_e32 v19, 0x3d372713, v17
	v_mul_f32_e32 v19, v17, v19
	v_fma_f32 v19, v17, v19, v17
	v_mul_f32_e32 v19, 0xbfcc422a, v19
	v_add_f32_e64 v20, v20, 1.0
	v_add_f32_e64 v21, v21, 1.0
	v_min_f32_e32 v19, 0x42a00000, v19
	v_rcp_f32_e32 v26, v20
	v_rcp_f32_e32 v27, v21
	v_mul_f32_e32 v19, 0x3fb8aa3b, v19
	v_exp_f32_e32 v29, v19
	v_or_b32_e32 v18, 48, v124
	v_fma_f32 v20, -v20, v26, 1.0
	v_fma_f32 v21, -v21, v27, 1.0
	s_andn2_b64 vcc, exec, s[16:17]
	v_fma_f32 v20, v26, v20, v26
	v_fma_f32 v21, v27, v21, v27
	v_add_f32_e64 v26, v28, 1.0
	v_add_f32_e64 v27, v29, 1.0
	v_mul_f32_e64 v14, v14, v20
	v_mul_f32_e64 v15, v15, v21
	v_rcp_f32_e32 v28, v26
	v_rcp_f32_e32 v29, v27
	v_mul_f32_e64 v10, v10, v14
	v_mul_f32_e64 v11, v11, v15
	v_fma_f32 v20, v40, v24, v52
	v_fma_f32 v21, v41, v25, v53
	v_cvt_pk_bf16_f32 v10, v10, v11
	v_fma_f32 v14, -v26, v28, 1.0
	v_fma_f32 v15, -v27, v29, 1.0
	v_fma_f32 v20, v44, v36, v20
	v_fma_f32 v21, v45, v37, v21
	v_fma_f32 v14, v28, v14, v28
	v_fma_f32 v15, v29, v15, v29
	v_fma_f32 v8, v8, v48, v20
	v_fma_f32 v9, v9, v49, v21
	v_mul_f32_e64 v14, v16, v14
	v_mul_f32_e64 v15, v17, v15
	v_fma_f32 v16, v38, v22, v50
	v_fma_f32 v17, v39, v23, v51
	v_mul_f32_e64 v12, v12, v14
	v_mul_f32_e64 v13, v13, v15
	v_fma_f32 v16, v42, v34, v16
	v_fma_f32 v17, v43, v35, v17
	s_mov_b64 s[16:17], -1
	v_fma_f32 v6, v6, v46, v16
	v_fma_f32 v7, v7, v47, v17
	s_nop 0
	v_mul_f32_e32 v11, 0x3d372713, v6
	v_mul_f32_e32 v11, v6, v11
	v_fma_f32 v11, v6, v11, v6
	v_mul_f32_e32 v11, 0xbfcc422a, v11
	v_min_f32_e32 v11, 0x42a00000, v11
	v_mul_f32_e32 v11, 0x3fb8aa3b, v11
	v_exp_f32_e32 v16, v11
	v_mul_f32_e32 v11, 0x3d372713, v7
	v_mul_f32_e32 v11, v7, v11
	v_fma_f32 v11, v7, v11, v7
	v_mul_f32_e32 v11, 0xbfcc422a, v11
	v_min_f32_e32 v11, 0x42a00000, v11
	v_mul_f32_e32 v11, 0x3fb8aa3b, v11
	v_exp_f32_e32 v17, v11
	v_mul_f32_e32 v11, 0x3d372713, v8
	v_mul_f32_e32 v11, v8, v11
	v_fma_f32 v11, v8, v11, v8
	v_mul_f32_e32 v11, 0xbfcc422a, v11
	v_min_f32_e32 v11, 0x42a00000, v11
	v_mul_f32_e32 v11, 0x3fb8aa3b, v11
	v_exp_f32_e32 v22, v11
	v_mul_f32_e32 v11, 0x3d372713, v9
	v_mul_f32_e32 v11, v9, v11
	v_fma_f32 v11, v9, v11, v9
	v_mul_f32_e32 v11, 0xbfcc422a, v11
	v_min_f32_e32 v11, 0x42a00000, v11
	v_mul_f32_e32 v11, 0x3fb8aa3b, v11
	v_add_f32_e64 v16, v16, 1.0
	v_add_f32_e64 v17, v17, 1.0
	v_exp_f32_e32 v23, v11
	v_rcp_f32_e32 v20, v16
	v_rcp_f32_e32 v21, v17
	v_cvt_pk_bf16_f32 v11, v12, v13
	v_add_f32_e64 v14, v22, 1.0
	v_add_f32_e64 v15, v23, 1.0
	v_fma_f32 v12, -v16, v20, 1.0
	v_fma_f32 v13, -v17, v21, 1.0
	v_rcp_f32_e32 v16, v14
	v_rcp_f32_e32 v17, v15
	v_fma_f32 v12, v20, v12, v20
	v_fma_f32 v13, v21, v13, v21
	s_nop 0
	v_mul_f32_e64 v6, v6, v12
	v_mul_f32_e64 v7, v7, v13
	s_nop 0
	v_mul_f32_e64 v2, v2, v6
	v_mul_f32_e64 v3, v3, v7
	v_fma_f32 v6, -v14, v16, 1.0
	v_fma_f32 v7, -v15, v17, 1.0
	v_cvt_pk_bf16_f32 v12, v2, v3
	v_fma_f32 v6, v16, v6, v16
	v_fma_f32 v7, v17, v7, v17
	v_mad_i64_i32 v[2:3], s[18:19], v18, s79, v[178:179]
	v_mul_f32_e64 v6, v8, v6
	v_mul_f32_e64 v7, v9, v7
	s_nop 0
	v_mul_f32_e64 v4, v4, v6
	v_mul_f32_e64 v5, v5, v7
	s_nop 0
	v_cvt_pk_bf16_f32 v13, v4, v5
	global_store_dwordx4 v[2:3], v[10:13], off
	s_cbranch_vccnz .LBB0_962
	s_andn2_b64 vcc, exec, s[24:25]
	s_cbranch_vccnz .LBB0_961
	s_barrier
	s_branch .LBB0_961

; __device__ __forceinline__ float gelu_tanh(float x) { float z = 1.5957691216057308f * (x + 0.044715f * x * x * x); return x * rcp_nr(1.f + __expf(fminf(-z, 80.f))); }
; __device__ __forceinline__ u32x2 pk4(f32x4 v) { u32x2 r; r.x = pk2(v.x, v.y); r.y = pk2(v.z, v.w); return r; }
; __device__ __forceinline__ void fixup_phase(const Params& p) {
;     ...
;     const f32x4 a0 = *(const f32x4*)(HA0 + ((size_t)rb * 2 + rl) * DFF + j0);
;     const f32x4 g = *(const f32x4*)(HG0 + ((size_t)rb * 2 + rl) * DFF + j0);
;     const f32x4 pm1 = *(const f32x4*)(HA1 + ((size_t)(rb - 1) * 2 + 1) * DFF + j0);
;     const f32x4 pm2 = *(const f32x4*)(HA1 + ((size_t)(rb - 1) * 2 + 0) * DFF + j0);
;     f32x4 am1, am2;
;     if (rl == 0) { am1 = pm1; am2 = pm2; }
;     else { am1 = *(const f32x4*)(HA0 + ((size_t)rb * 2 + 0) * DFF + j0); am2 = pm1; }
;     const f32x4 w0 = *(const f32x4*)(p.in[23] + j0), w1 = *(const f32x4*)(p.in[23] + DFF + j0), w2 = *(const f32x4*)(p.in[23] + 2 * DFF + j0);
;     const f32x4 cb = *(const f32x4*)(p.in[24] + j0);
;     f32x4 h;
;     h.x = gelu_tanh(cb.x + w0.x * am2.x + w1.x * am1.x + w2.x * a0.x) * g.x;
;     h.y = gelu_tanh(cb.y + w0.y * am2.y + w1.y * am1.y + w2.y * a0.y) * g.y;
;     h.z = gelu_tanh(cb.z + w0.z * am2.z + w1.z * am1.z + w2.z * a0.z) * g.z;
;     h.w = gelu_tanh(cb.w + w0.w * am2.w + w1.w * am1.w + w2.w * a0.w) * g.w;
;     *(u32x2*)(H + ((size_t)rb * 64 + rl) * DFF + j0) = pk4(h);
.LBB0_1157:
	s_or_b64 exec, exec, s[26:27]
	v_readlane_b32 s36, v244, 35
	v_readlane_b32 s37, v244, 36
	v_readlane_b32 s38, v244, 37
	v_readlane_b32 s39, v244, 38
	v_readlane_b32 s40, v244, 39
	v_readlane_b32 s41, v244, 40
	v_readlane_b32 s42, v244, 41
	v_readlane_b32 s43, v244, 42
	v_readlane_b32 s36, v244, 4
	v_readlane_b32 s50, v244, 49
	v_readlane_b32 s51, v244, 50
	v_readlane_b32 s37, v244, 5
	v_readlane_b32 s38, v244, 6
	v_lshl_add_u64 v[18:19], s[50:51], 0, v[24:25]
	v_lshl_add_u64 v[26:27], s[36:37], 0, v[24:25]
	global_load_dwordx4 v[18:21], v[18:19], off
	v_readlane_b32 s39, v244, 7
	global_load_dwordx4 v[30:33], v[26:27], off
	v_lshl_add_u64 v[26:27], s[14:15], 0, v[24:25]
	global_load_dwordx4 v[34:37], v[26:27], off
	v_lshl_add_u64 v[24:25], s[16:17], 0, v[24:25]
	global_load_dwordx4 v[24:27], v[24:25], off
	v_readlane_b32 s36, v244, 0
	v_readlane_b32 s38, v244, 2
	v_readlane_b32 s39, v244, 3
	v_readlane_b32 s44, v244, 43
	v_readlane_b32 s45, v244, 44
	v_readlane_b32 s46, v244, 45
	v_readlane_b32 s47, v244, 46
	v_readlane_b32 s48, v244, 47
	v_readlane_b32 s49, v244, 48
	v_readlane_b32 s40, v244, 8
	v_readlane_b32 s41, v244, 9
	v_readlane_b32 s42, v244, 10
	v_readlane_b32 s43, v244, 11
	v_readlane_b32 s37, v244, 1
	s_waitcnt vmcnt(2)
	v_fma_f32 v16, v16, v20, v32
	v_fma_f32 v17, v17, v21, v33
	v_fma_f32 v14, v14, v18, v30
	v_fma_f32 v15, v15, v19, v31
	s_waitcnt vmcnt(1)
	v_fma_f32 v12, v12, v36, v16
	v_fma_f32 v13, v13, v37, v17
	v_fma_f32 v10, v10, v34, v14
	v_fma_f32 v11, v11, v35, v15
	s_waitcnt vmcnt(0)
	v_fma_f32 v8, v8, v26, v12
	v_fma_f32 v9, v9, v27, v13
	v_fma_f32 v6, v6, v24, v10
	v_fma_f32 v7, v7, v25, v11
	v_mul_f32_e32 v12, 0x3d372713, v8
	v_mul_f32_e32 v10, 0x3d372713, v6
	v_mul_f32_e32 v11, 0x3d372713, v7
	v_mul_f32_e32 v13, 0x3d372713, v9
	v_mul_f32_e32 v10, v6, v10
	v_mul_f32_e32 v11, v7, v11
	v_mul_f32_e32 v12, v8, v12
	v_mul_f32_e32 v13, v9, v13
	v_fma_f32 v10, v6, v10, v6
	v_fma_f32 v11, v7, v11, v7
	v_fma_f32 v12, v8, v12, v8
	v_fma_f32 v13, v9, v13, v9
	v_mul_f32_e32 v10, 0xbfcc422a, v10
	v_mul_f32_e32 v11, 0xbfcc422a, v11
	v_mul_f32_e32 v12, 0xbfcc422a, v12
	v_mul_f32_e32 v13, 0xbfcc422a, v13
	v_min_f32_e32 v10, 0x42a00000, v10
	v_min_f32_e32 v11, 0x42a00000, v11
	v_min_f32_e32 v12, 0x42a00000, v12
	v_min_f32_e32 v13, 0x42a00000, v13
	v_mul_f32_e32 v10, 0x3fb8aa3b, v10
	v_mul_f32_e32 v11, 0x3fb8aa3b, v11
	v_mul_f32_e32 v12, 0x3fb8aa3b, v12
	v_mul_f32_e32 v13, 0x3fb8aa3b, v13
	v_exp_f32_e32 v10, v10
	v_exp_f32_e32 v11, v11
	v_exp_f32_e32 v12, v12
	v_exp_f32_e32 v13, v13
	v_lshl_or_b32 v20, v28, 6, v29
	v_add_f32_e64 v10, v10, 1.0
	v_add_f32_e64 v11, v11, 1.0
	v_mov_b64_e32 v[14:15], s[38:39]
	v_add_f32_e64 v12, v12, 1.0
	v_add_f32_e64 v13, v13, 1.0
	v_rcp_f32_e32 v16, v10
	v_rcp_f32_e32 v17, v11
	v_rcp_f32_e32 v18, v12
	v_rcp_f32_e32 v19, v13
	v_mad_i64_i32 v[14:15], s[26:27], v20, s29, v[14:15]
	v_fma_f32 v10, -v10, v16, 1.0
	v_fma_f32 v11, -v11, v17, 1.0
	v_fma_f32 v12, -v12, v18, 1.0
	v_fma_f32 v13, -v13, v19, 1.0
	v_fma_f32 v10, v16, v10, v16
	v_fma_f32 v11, v17, v11, v17
	v_fma_f32 v12, v18, v12, v18
	v_fma_f32 v13, v19, v13, v19
	v_mul_f32_e64 v6, v6, v10
	v_mul_f32_e64 v7, v7, v11
	v_mul_f32_e64 v8, v8, v12
	v_mul_f32_e64 v9, v9, v13
	v_mul_f32_e64 v2, v2, v6
	v_mul_f32_e64 v3, v3, v7
	v_mul_f32_e64 v4, v4, v8
	v_mul_f32_e64 v5, v5, v9
	v_cvt_pk_bf16_f32 v2, v2, v3
	v_cvt_pk_bf16_f32 v3, v4, v5
	v_lshl_add_u64 v[4:5], v[22:23], 1, v[14:15]
	global_store_dwordx2 v[4:5], v[2:3], off

; __device__ __forceinline__ u32x2 pk4(f32x4 v) { u32x2 r; r.x = pk2(v.x, v.y); r.y = pk2(v.z, v.w); return r; }
; __device__ __forceinline__ f32x4 unpk4(u32x2 w) { f32x4 r; r.x = bflo(w.x); r.y = bfhi(w.x); r.z = bflo(w.y); r.w = bfhi(w.y); return r; }
; template <int EPI>
; __device__ __forceinline__ void epilogue(const Params& p, f32x4 (&acc)[2][2][4][2], const int pm, const int pn, const int wr, const int wc, const int fr, const int fq) {
;     ...
;     const bf16_t* X1b = (const bf16_t*)(ws + OFF_X1B);
; #pragma unroll
;     for (int ai = 0; ai < 2; ++ai)
; #pragma unroll
;       for (int m = 0; m < 4; ++m) {
;         const int row = pm * 256 + ai * 128 + wr * 64 + m * 16 + fr;
; #pragma unroll
;         for (int bj = 0; bj < 2; ++bj) {
;           const int col = pn * 256 + bj * 128 + wc * 32 + fq * 8;
;           f32x4 x0, x1;
;           if constexpr (EPI == EPI_WO) { const float* xp = p.in[0] + (size_t)row * DM + col; x0 = *(const f32x4*)xp; x1 = *(const f32x4*)(xp + 4); }
;           else { const u32x4 xw = *(const u32x4*)(X1b + (size_t)row * DM + col); x0 = unpk4(u32x2{xw.x, xw.y}); x1 = unpk4(u32x2{xw.z, xw.w}); }
;           f32x4 v0 = acc[ai][bj][m][0], v1 = acc[ai][bj][m][1];
;           v0.x += ALPHA_F * x0.x; v0.y += ALPHA_F * x0.y; v0.z += ALPHA_F * x0.z; v0.w += ALPHA_F * x0.w;
;           v1.x += ALPHA_F * x1.x; v1.y += ALPHA_F * x1.y; v1.z += ALPHA_F * x1.z; v1.w += ALPHA_F * x1.w;
;           const u32x2 lo = pk4(v0), hi = pk4(v1);
;           *(u32x4*)((bf16_t*)(ws + (EPI == EPI_WO ? OFF_PRE1 : OFF_PRE2)) + (size_t)row * DM + col) = u32x4{lo.x, lo.y, hi.x, hi.y};
;         }
.LBB0_1252:
	v_lshl_add_u32 v150, s35, 8, v152
	v_lshl_or_b32 v128, s36, 8, v155
	v_ashrrev_i32_e32 v151, 31, v150
	v_or_b32_e32 v160, 16, v150
	v_ashrrev_i32_e32 v129, 31, v128
	v_lshlrev_b64 v[172:173], 11, v[150:151]
	v_ashrrev_i32_e32 v161, 31, v160
	v_lshl_add_u64 v[130:131], s[20:21], 0, v[172:173]
	v_lshlrev_b64 v[148:149], 1, v[128:129]
	v_lshlrev_b64 v[174:175], 11, v[160:161]
	v_lshl_add_u64 v[132:133], v[130:131], 0, v[148:149]
	v_lshl_add_u64 v[160:161], s[20:21], 0, v[174:175]
	global_load_dwordx4 v[128:131], v[132:133], off
	s_nop 0
	global_load_dwordx4 v[132:135], v[132:133], off offset:256
	v_lshl_add_u64 v[164:165], v[160:161], 0, v[148:149]
	global_load_dwordx4 v[160:163], v[164:165], off
	s_nop 0
	global_load_dwordx4 v[164:167], v[164:165], off offset:256
	v_or_b32_e32 v168, 32, v150
	v_ashrrev_i32_e32 v169, 31, v168
	v_lshlrev_b64 v[180:181], 11, v[168:169]
	v_lshl_add_u64 v[168:169], s[20:21], 0, v[180:181]
	v_lshl_add_u64 v[178:179], v[168:169], 0, v[148:149]
	v_or_b32_e32 v176, 48, v150
	global_load_dwordx4 v[168:171], v[178:179], off
	v_ashrrev_i32_e32 v177, 31, v176
	v_lshl_add_u64 v[172:173], s[22:23], 0, v[172:173]
	v_lshlrev_b64 v[186:187], 11, v[176:177]
	v_lshl_add_u64 v[198:199], v[172:173], 0, v[148:149]
	v_lshl_add_u64 v[172:173], s[22:23], 0, v[174:175]
	v_lshl_add_u64 v[174:175], s[20:21], 0, v[186:187]
	v_lshl_add_u64 v[194:195], v[174:175], 0, v[148:149]
	v_lshl_add_u64 v[200:201], v[172:173], 0, v[148:149]
	global_load_dwordx4 v[172:175], v[178:179], off offset:256
	s_nop 0
	global_load_dwordx4 v[176:179], v[194:195], off
	s_nop 0
	global_load_dwordx4 v[194:197], v[194:195], off offset:256
	s_waitcnt vmcnt(0)
	v_lshlrev_b32_e32 v202, 16, v128
	v_and_b32_e32 v203, 0xffff0000, v128
	v_lshlrev_b32_e32 v128, 16, v129
	v_and_b32_e32 v129, 0xffff0000, v129
	v_lshlrev_b32_e32 v204, 16, v130
	v_and_b32_e32 v205, 0xffff0000, v130
	v_lshlrev_b32_e32 v130, 16, v131
	v_and_b32_e32 v131, 0xffff0000, v131
	v_lshlrev_b32_e32 v206, 16, v132
	v_and_b32_e32 v207, 0xffff0000, v132
	v_lshlrev_b32_e32 v132, 16, v133
	v_and_b32_e32 v133, 0xffff0000, v133
	v_lshlrev_b32_e32 v208, 16, v134
	v_and_b32_e32 v209, 0xffff0000, v134
	v_lshlrev_b32_e32 v134, 16, v135
	v_and_b32_e32 v135, 0xffff0000, v135
	v_fma_f32 v202, v202, s14, v124
	v_fma_f32 v203, v203, s14, v125
	v_fma_f32 v210, v128, s14, v126
	v_fma_f32 v211, v129, s14, v127
	v_fma_f32 v204, v204, s14, v120
	v_fma_f32 v205, v205, s14, v121
	v_fma_f32 v212, v130, s14, v122
	v_fma_f32 v213, v131, s14, v123
	v_lshlrev_b32_e32 v218, 16, v160
	v_and_b32_e32 v219, 0xffff0000, v160
	v_lshlrev_b32_e32 v160, 16, v161
	v_and_b32_e32 v161, 0xffff0000, v161
	v_lshlrev_b32_e32 v220, 16, v162
	v_and_b32_e32 v221, 0xffff0000, v162
	v_lshlrev_b32_e32 v162, 16, v163
	v_and_b32_e32 v163, 0xffff0000, v163
	v_fma_f32 v206, v206, s14, v108
	v_fma_f32 v207, v207, s14, v109
	v_fma_f32 v214, v132, s14, v110
	v_fma_f32 v215, v133, s14, v111
	v_fma_f32 v208, v208, s14, v100
	v_fma_f32 v209, v209, s14, v101
	v_fma_f32 v216, v134, s14, v102
	v_fma_f32 v217, v135, s14, v103
	v_cvt_pk_bf16_f32 v128, v202, v203
	v_cvt_pk_bf16_f32 v129, v210, v211
	v_cvt_pk_bf16_f32 v130, v204, v205
	v_cvt_pk_bf16_f32 v131, v212, v213
	v_fma_f32 v202, v218, s14, v116
	v_fma_f32 v203, v219, s14, v117
	v_fma_f32 v160, v160, s14, v118
	v_fma_f32 v161, v161, s14, v119
	v_fma_f32 v204, v220, s14, v112
	v_fma_f32 v205, v221, s14, v113
	v_fma_f32 v162, v162, s14, v114
	v_fma_f32 v163, v163, s14, v115
	v_cvt_pk_bf16_f32 v132, v206, v207
	v_cvt_pk_bf16_f32 v133, v214, v215
	v_cvt_pk_bf16_f32 v134, v208, v209
	v_cvt_pk_bf16_f32 v135, v216, v217
	global_store_dwordx4 v[198:199], v[128:131], off
	global_store_dwordx4 v[198:199], v[132:135], off offset:256
	v_lshlrev_b32_e32 v222, 16, v164
	v_cvt_pk_bf16_f32 v128, v202, v203
	v_cvt_pk_bf16_f32 v129, v160, v161
	v_cvt_pk_bf16_f32 v130, v204, v205
	v_cvt_pk_bf16_f32 v131, v162, v163
	global_store_dwordx4 v[200:201], v[128:131], off
	v_and_b32_e32 v223, 0xffff0000, v164
	v_lshlrev_b32_e32 v164, 16, v165
	v_lshlrev_b32_e32 v128, 16, v166
	v_and_b32_e32 v129, 0xffff0000, v166
	v_and_b32_e32 v165, 0xffff0000, v165
	v_fma_f32 v132, v128, s14, v84
	v_fma_f32 v133, v129, s14, v85
	v_lshlrev_b32_e32 v128, 16, v167
	v_and_b32_e32 v129, 0xffff0000, v167
	v_fma_f32 v206, v222, s14, v92
	v_fma_f32 v207, v223, s14, v93
	v_fma_f32 v130, v164, s14, v94
	v_fma_f32 v131, v165, s14, v95
	v_fma_f32 v134, v128, s14, v86
	v_fma_f32 v135, v129, s14, v87
	v_cvt_pk_bf16_f32 v128, v206, v207
	v_cvt_pk_bf16_f32 v129, v130, v131
	v_cvt_pk_bf16_f32 v130, v132, v133
	v_cvt_pk_bf16_f32 v131, v134, v135
	global_store_dwordx4 v[200:201], v[128:131], off offset:256
	v_lshlrev_b32_e32 v134, 16, v170
	v_and_b32_e32 v135, 0xffff0000, v170
	v_lshlrev_b32_e32 v128, 16, v168
	v_and_b32_e32 v129, 0xffff0000, v168
	v_lshlrev_b32_e32 v130, 16, v169
	v_and_b32_e32 v131, 0xffff0000, v169
	v_lshlrev_b32_e32 v160, 16, v171
	v_and_b32_e32 v161, 0xffff0000, v171
	v_lshl_add_u64 v[132:133], s[22:23], 0, v[180:181]
	v_fma_f32 v128, v128, s14, v104
	v_fma_f32 v129, v129, s14, v105
	v_fma_f32 v130, v130, s14, v106
	v_fma_f32 v131, v131, s14, v107
	v_fma_f32 v134, v134, s14, v96
	v_fma_f32 v135, v135, s14, v97
	v_fma_f32 v160, v160, s14, v98
	v_fma_f32 v161, v161, s14, v99
	v_cvt_pk_bf16_f32 v128, v128, v129
	v_cvt_pk_bf16_f32 v129, v130, v131
	v_cvt_pk_bf16_f32 v130, v134, v135
	v_cvt_pk_bf16_f32 v131, v160, v161
	v_lshl_add_u64 v[132:133], v[132:133], 0, v[148:149]
	global_store_dwordx4 v[132:133], v[128:131], off
	v_lshlrev_b32_e32 v134, 16, v174
	v_and_b32_e32 v135, 0xffff0000, v174
	v_lshlrev_b32_e32 v128, 16, v172
; __device__ __forceinline__ u32x2 pk4(f32x4 v) { u32x2 r; r.x = pk2(v.x, v.y); r.y = pk2(v.z, v.w); return r; }
; __device__ __forceinline__ f32x4 unpk4(u32x2 w) { f32x4 r; r.x = bflo(w.x); r.y = bfhi(w.x); r.z = bflo(w.y); r.w = bfhi(w.y); return r; }
; template <int EPI>
; __device__ __forceinline__ void epilogue(const Params& p, f32x4 (&acc)[2][2][4][2], const int pm, const int pn, const int wr, const int wc, const int fr, const int fq) {
;     ...
;     const bf16_t* X1b = (const bf16_t*)(ws + OFF_X1B);
; #pragma unroll
;     for (int ai = 0; ai < 2; ++ai)
; #pragma unroll
;       for (int m = 0; m < 4; ++m) {
;         const int row = pm * 256 + ai * 128 + wr * 64 + m * 16 + fr;
; #pragma unroll
;         for (int bj = 0; bj < 2; ++bj) {
;           const int col = pn * 256 + bj * 128 + wc * 32 + fq * 8;
;           f32x4 x0, x1;
;           if constexpr (EPI == EPI_WO) { const float* xp = p.in[0] + (size_t)row * DM + col; x0 = *(const f32x4*)xp; x1 = *(const f32x4*)(xp + 4); }
;           else { const u32x4 xw = *(const u32x4*)(X1b + (size_t)row * DM + col); x0 = unpk4(u32x2{xw.x, xw.y}); x1 = unpk4(u32x2{xw.z, xw.w}); }
;           f32x4 v0 = acc[ai][bj][m][0], v1 = acc[ai][bj][m][1];
;           v0.x += ALPHA_F * x0.x; v0.y += ALPHA_F * x0.y; v0.z += ALPHA_F * x0.z; v0.w += ALPHA_F * x0.w;
;           v1.x += ALPHA_F * x1.x; v1.y += ALPHA_F * x1.y; v1.z += ALPHA_F * x1.z; v1.w += ALPHA_F * x1.w;
;           const u32x2 lo = pk4(v0), hi = pk4(v1);
;           *(u32x4*)((bf16_t*)(ws + (EPI == EPI_WO ? OFF_PRE1 : OFF_PRE2)) + (size_t)row * DM + col) = u32x4{lo.x, lo.y, hi.x, hi.y};
;         }
	v_and_b32_e32 v129, 0xffff0000, v172
	v_lshlrev_b32_e32 v130, 16, v173
	v_and_b32_e32 v131, 0xffff0000, v173
	v_lshlrev_b32_e32 v160, 16, v175
	v_and_b32_e32 v161, 0xffff0000, v175
	v_fma_f32 v128, v128, s14, v76
	v_fma_f32 v129, v129, s14, v77
	v_fma_f32 v130, v130, s14, v78
	v_fma_f32 v131, v131, s14, v79
	v_fma_f32 v134, v134, s14, v72
	v_fma_f32 v135, v135, s14, v73
	v_fma_f32 v160, v160, s14, v74
	v_fma_f32 v161, v161, s14, v75
	v_cvt_pk_bf16_f32 v128, v128, v129
	v_cvt_pk_bf16_f32 v129, v130, v131
	v_cvt_pk_bf16_f32 v130, v134, v135
	v_cvt_pk_bf16_f32 v131, v160, v161
	global_store_dwordx4 v[132:133], v[128:131], off offset:256
	v_lshlrev_b32_e32 v134, 16, v178
	v_and_b32_e32 v135, 0xffff0000, v178
	v_lshlrev_b32_e32 v128, 16, v176
	v_and_b32_e32 v129, 0xffff0000, v176
	v_lshlrev_b32_e32 v130, 16, v177
	v_and_b32_e32 v131, 0xffff0000, v177
	v_lshlrev_b32_e32 v160, 16, v179
	v_and_b32_e32 v161, 0xffff0000, v179
	v_lshl_add_u64 v[132:133], s[22:23], 0, v[186:187]
	v_fma_f32 v128, v128, s14, v88
	v_fma_f32 v129, v129, s14, v89
	v_fma_f32 v130, v130, s14, v90
	v_fma_f32 v131, v131, s14, v91
	v_fma_f32 v134, v134, s14, v80
	v_fma_f32 v135, v135, s14, v81
	v_fma_f32 v160, v160, s14, v82
	v_fma_f32 v161, v161, s14, v83
	v_cvt_pk_bf16_f32 v128, v128, v129
	v_cvt_pk_bf16_f32 v129, v130, v131
	v_cvt_pk_bf16_f32 v130, v134, v135
	v_cvt_pk_bf16_f32 v131, v160, v161
	v_lshl_add_u64 v[160:161], v[132:133], 0, v[148:149]
	global_store_dwordx4 v[160:161], v[128:131], off
	v_lshlrev_b32_e32 v132, 16, v194
	v_and_b32_e32 v133, 0xffff0000, v194
	v_add_u32_e32 v128, 0x80, v150
	v_ashrrev_i32_e32 v129, 31, v128
	v_lshlrev_b64 v[162:163], 11, v[128:129]
	v_lshl_add_u64 v[128:129], s[20:21], 0, v[162:163]
	v_lshl_add_u64 v[164:165], v[128:129], 0, v[148:149]
	global_load_dwordx4 v[128:131], v[164:165], off
	v_lshlrev_b32_e32 v134, 16, v195
	v_and_b32_e32 v135, 0xffff0000, v195
	v_lshlrev_b32_e32 v166, 16, v196
	v_and_b32_e32 v167, 0xffff0000, v196
	v_lshlrev_b32_e32 v168, 16, v197
	v_and_b32_e32 v169, 0xffff0000, v197
	v_fma_f32 v132, v132, s14, v68
	v_fma_f32 v133, v133, s14, v69
	v_fma_f32 v134, v134, s14, v70
	v_fma_f32 v135, v135, s14, v71
	v_fma_f32 v166, v166, s14, v64
	v_fma_f32 v167, v167, s14, v65
	v_fma_f32 v168, v168, s14, v66
	v_fma_f32 v169, v169, s14, v67
	v_cvt_pk_bf16_f32 v132, v132, v133
	v_cvt_pk_bf16_f32 v133, v134, v135
	v_cvt_pk_bf16_f32 v134, v166, v167
	v_cvt_pk_bf16_f32 v135, v168, v169
	global_store_dwordx4 v[160:161], v[132:135], off offset:256
	global_load_dwordx4 v[132:135], v[164:165], off offset:256
	v_lshl_add_u64 v[160:161], s[22:23], 0, v[162:163]
	v_lshl_add_u64 v[160:161], v[160:161], 0, v[148:149]
	s_waitcnt vmcnt(2)
	v_lshlrev_b32_e32 v162, 16, v128
	v_and_b32_e32 v163, 0xffff0000, v128
	v_lshlrev_b32_e32 v128, 16, v129
	v_and_b32_e32 v129, 0xffff0000, v129
	v_fma_f32 v164, v128, s14, v62
	v_fma_f32 v165, v129, s14, v63
	v_lshlrev_b32_e32 v128, 16, v130
	v_and_b32_e32 v129, 0xffff0000, v130
	v_fma_f32 v166, v128, s14, v56
	v_fma_f32 v167, v129, s14, v57
	v_lshlrev_b32_e32 v128, 16, v131
	v_and_b32_e32 v129, 0xffff0000, v131
	v_fma_f32 v162, v162, s14, v60
	v_fma_f32 v163, v163, s14, v61
	v_fma_f32 v168, v128, s14, v58
	v_fma_f32 v169, v129, s14, v59
	v_cvt_pk_bf16_f32 v128, v162, v163
	v_cvt_pk_bf16_f32 v129, v164, v165
	v_cvt_pk_bf16_f32 v130, v166, v167
	v_cvt_pk_bf16_f32 v131, v168, v169
	global_store_dwordx4 v[160:161], v[128:131], off
	s_waitcnt vmcnt(1)
	s_nop 0
	v_lshlrev_b32_e32 v128, 16, v132
	v_and_b32_e32 v129, 0xffff0000, v132
	v_fma_f32 v162, v128, s14, v44
	v_fma_f32 v163, v129, s14, v45
	v_lshlrev_b32_e32 v128, 16, v133
	v_and_b32_e32 v129, 0xffff0000, v133
	v_fma_f32 v164, v128, s14, v46
	v_fma_f32 v165, v129, s14, v47
	v_lshlrev_b32_e32 v128, 16, v134
	v_and_b32_e32 v129, 0xffff0000, v134
	v_fma_f32 v166, v128, s14, v36
	v_fma_f32 v167, v129, s14, v37
	v_add_u32_e32 v128, 0x90, v150
	v_ashrrev_i32_e32 v129, 31, v128
	v_lshlrev_b32_e32 v132, 16, v135
	v_lshlrev_b64 v[168:169], 11, v[128:129]
	v_and_b32_e32 v133, 0xffff0000, v135
	v_lshl_add_u64 v[128:129], s[20:21], 0, v[168:169]
	v_fma_f32 v172, v132, s14, v38
	v_fma_f32 v173, v133, s14, v39
	v_lshl_add_u64 v[170:171], v[128:129], 0, v[148:149]
	v_cvt_pk_bf16_f32 v132, v162, v163
	v_cvt_pk_bf16_f32 v133, v164, v165
	v_cvt_pk_bf16_f32 v134, v166, v167
	v_cvt_pk_bf16_f32 v135, v172, v173
	global_load_dwordx4 v[128:131], v[170:171], off
	v_lshl_add_u64 v[162:163], s[22:23], 0, v[168:169]
	global_store_dwordx4 v[160:161], v[132:135], off offset:256
	global_load_dwordx4 v[132:135], v[170:171], off offset:256
	v_add_u32_e32 v160, 0xa0, v150
	v_ashrrev_i32_e32 v161, 31, v160
	v_lshlrev_b64 v[160:161], 11, v[160:161]
	v_lshl_add_u64 v[164:165], s[20:21], 0, v[160:161]
	v_lshl_add_u64 v[162:163], v[162:163], 0, v[148:149]
	v_lshl_add_u64 v[164:165], v[164:165], 0, v[148:149]
	v_add_u32_e32 v150, 0xb0, v150
	v_ashrrev_i32_e32 v151, 31, v150
	v_lshlrev_b64 v[150:151], 11, v[150:151]
	v_lshl_add_u64 v[160:161], s[22:23], 0, v[160:161]
	v_lshl_add_u64 v[160:161], v[160:161], 0, v[148:149]
	s_waitcnt vmcnt(2)
; __device__ __forceinline__ u32x2 pk4(f32x4 v) { u32x2 r; r.x = pk2(v.x, v.y); r.y = pk2(v.z, v.w); return r; }
; __device__ __forceinline__ f32x4 unpk4(u32x2 w) { f32x4 r; r.x = bflo(w.x); r.y = bfhi(w.x); r.z = bflo(w.y); r.w = bfhi(w.y); return r; }
; template <int EPI>
; __device__ __forceinline__ void epilogue(const Params& p, f32x4 (&acc)[2][2][4][2], const int pm, const int pn, const int wr, const int wc, const int fr, const int fq) {
;     ...
;     const bf16_t* X1b = (const bf16_t*)(ws + OFF_X1B);
; #pragma unroll
;     for (int ai = 0; ai < 2; ++ai)
; #pragma unroll
;       for (int m = 0; m < 4; ++m) {
;         const int row = pm * 256 + ai * 128 + wr * 64 + m * 16 + fr;
; #pragma unroll
;         for (int bj = 0; bj < 2; ++bj) {
;           const int col = pn * 256 + bj * 128 + wc * 32 + fq * 8;
;           f32x4 x0, x1;
;           if constexpr (EPI == EPI_WO) { const float* xp = p.in[0] + (size_t)row * DM + col; x0 = *(const f32x4*)xp; x1 = *(const f32x4*)(xp + 4); }
;           else { const u32x4 xw = *(const u32x4*)(X1b + (size_t)row * DM + col); x0 = unpk4(u32x2{xw.x, xw.y}); x1 = unpk4(u32x2{xw.z, xw.w}); }
;           f32x4 v0 = acc[ai][bj][m][0], v1 = acc[ai][bj][m][1];
;           v0.x += ALPHA_F * x0.x; v0.y += ALPHA_F * x0.y; v0.z += ALPHA_F * x0.z; v0.w += ALPHA_F * x0.w;
;           v1.x += ALPHA_F * x1.x; v1.y += ALPHA_F * x1.y; v1.z += ALPHA_F * x1.z; v1.w += ALPHA_F * x1.w;
;           const u32x2 lo = pk4(v0), hi = pk4(v1);
;           *(u32x4*)((bf16_t*)(ws + (EPI == EPI_WO ? OFF_PRE1 : OFF_PRE2)) + (size_t)row * DM + col) = u32x4{lo.x, lo.y, hi.x, hi.y};
;         }
	v_lshlrev_b32_e32 v166, 16, v128
	v_and_b32_e32 v167, 0xffff0000, v128
	v_lshlrev_b32_e32 v128, 16, v129
	v_and_b32_e32 v129, 0xffff0000, v129
	v_lshlrev_b32_e32 v168, 16, v130
	v_and_b32_e32 v169, 0xffff0000, v130
	v_lshlrev_b32_e32 v130, 16, v131
	v_and_b32_e32 v131, 0xffff0000, v131
	s_waitcnt vmcnt(0)
	v_lshlrev_b32_e32 v170, 16, v132
	v_and_b32_e32 v171, 0xffff0000, v132
	v_lshlrev_b32_e32 v132, 16, v133
	v_and_b32_e32 v133, 0xffff0000, v133
	v_lshlrev_b32_e32 v172, 16, v134
	v_and_b32_e32 v173, 0xffff0000, v134
	v_lshlrev_b32_e32 v134, 16, v135
	v_fma_f32 v166, v166, s14, v52
	v_fma_f32 v167, v167, s14, v53
	v_fma_f32 v174, v128, s14, v54
	v_fma_f32 v175, v129, s14, v55
	v_fma_f32 v168, v168, s14, v48
	v_fma_f32 v169, v169, s14, v49
	v_fma_f32 v176, v130, s14, v50
	v_fma_f32 v177, v131, s14, v51
	v_and_b32_e32 v135, 0xffff0000, v135
	v_fma_f32 v170, v170, s14, v28
	v_fma_f32 v171, v171, s14, v29
	v_fma_f32 v178, v132, s14, v30
	v_fma_f32 v179, v133, s14, v31
	v_fma_f32 v172, v172, s14, v20
	v_fma_f32 v173, v173, s14, v21
	v_cvt_pk_bf16_f32 v128, v166, v167
	v_cvt_pk_bf16_f32 v129, v174, v175
	v_cvt_pk_bf16_f32 v130, v168, v169
	v_cvt_pk_bf16_f32 v131, v176, v177
	v_fma_f32 v166, v134, s14, v22
	v_fma_f32 v167, v135, s14, v23
	global_store_dwordx4 v[162:163], v[128:131], off
	v_cvt_pk_bf16_f32 v132, v170, v171
	v_cvt_pk_bf16_f32 v133, v178, v179
	v_cvt_pk_bf16_f32 v134, v172, v173
	v_cvt_pk_bf16_f32 v135, v166, v167
	global_load_dwordx4 v[128:131], v[164:165], off
	s_nop 0
	global_store_dwordx4 v[162:163], v[132:135], off offset:256
	global_load_dwordx4 v[132:135], v[164:165], off offset:256
	v_lshl_add_u64 v[162:163], s[20:21], 0, v[150:151]
	v_lshl_add_u64 v[162:163], v[162:163], 0, v[148:149]
	v_lshl_add_u64 v[150:151], s[22:23], 0, v[150:151]
	v_lshl_add_u64 v[148:149], v[150:151], 0, v[148:149]
	s_waitcnt vmcnt(2)
	v_lshlrev_b32_e32 v164, 16, v128
	v_and_b32_e32 v165, 0xffff0000, v128
	v_lshlrev_b32_e32 v128, 16, v129
	v_and_b32_e32 v129, 0xffff0000, v129
	v_lshlrev_b32_e32 v166, 16, v130
	v_and_b32_e32 v167, 0xffff0000, v130
	v_lshlrev_b32_e32 v130, 16, v131
	v_and_b32_e32 v131, 0xffff0000, v131
	s_waitcnt vmcnt(0)
	v_lshlrev_b32_e32 v168, 16, v132
	v_and_b32_e32 v169, 0xffff0000, v132
	v_lshlrev_b32_e32 v132, 16, v133
	v_and_b32_e32 v133, 0xffff0000, v133
	v_lshlrev_b32_e32 v170, 16, v134
	v_and_b32_e32 v171, 0xffff0000, v134
	v_lshlrev_b32_e32 v134, 16, v135
	v_and_b32_e32 v135, 0xffff0000, v135
	v_fma_f32 v164, v164, s14, v40
	v_fma_f32 v165, v165, s14, v41
	v_fma_f32 v172, v128, s14, v42
	v_fma_f32 v173, v129, s14, v43
	v_fma_f32 v166, v166, s14, v32
	v_fma_f32 v167, v167, s14, v33
	v_fma_f32 v174, v130, s14, v34
	v_fma_f32 v175, v131, s14, v35
	v_fma_f32 v168, v168, s14, v12
	v_fma_f32 v169, v169, s14, v13
	v_fma_f32 v176, v132, s14, v14
	v_fma_f32 v177, v133, s14, v15
	v_cvt_pk_bf16_f32 v128, v164, v165
	v_cvt_pk_bf16_f32 v129, v172, v173
	v_cvt_pk_bf16_f32 v130, v166, v167
	v_cvt_pk_bf16_f32 v131, v174, v175
	v_fma_f32 v164, v170, s14, v8
	v_fma_f32 v165, v171, s14, v9
	v_fma_f32 v166, v134, s14, v10
	v_fma_f32 v167, v135, s14, v11
	global_store_dwordx4 v[160:161], v[128:131], off
	v_cvt_pk_bf16_f32 v132, v168, v169
	v_cvt_pk_bf16_f32 v133, v176, v177
	v_cvt_pk_bf16_f32 v134, v164, v165
	v_cvt_pk_bf16_f32 v135, v166, v167
	global_load_dwordx4 v[128:131], v[162:163], off
	s_nop 0
	global_store_dwordx4 v[160:161], v[132:135], off offset:256
	global_load_dwordx4 v[132:135], v[162:163], off offset:256
	s_waitcnt vmcnt(2)
	v_lshlrev_b32_e32 v150, 16, v128
	v_and_b32_e32 v151, 0xffff0000, v128
	v_lshlrev_b32_e32 v128, 16, v129
	v_and_b32_e32 v129, 0xffff0000, v129
	v_lshlrev_b32_e32 v160, 16, v130
	v_and_b32_e32 v161, 0xffff0000, v130
	v_lshlrev_b32_e32 v130, 16, v131
	v_and_b32_e32 v131, 0xffff0000, v131
	s_waitcnt vmcnt(0)
	v_lshlrev_b32_e32 v162, 16, v132
	v_and_b32_e32 v163, 0xffff0000, v132
	v_lshlrev_b32_e32 v132, 16, v133
	v_and_b32_e32 v133, 0xffff0000, v133
	v_lshlrev_b32_e32 v164, 16, v134
	v_and_b32_e32 v165, 0xffff0000, v134
	v_lshlrev_b32_e32 v134, 16, v135
	v_and_b32_e32 v135, 0xffff0000, v135
	v_fma_f32 v150, v150, s14, v24
	v_fma_f32 v151, v151, s14, v25
	v_fma_f32 v166, v128, s14, v26
	v_fma_f32 v167, v129, s14, v27
	v_fma_f32 v160, v160, s14, v16
	v_fma_f32 v161, v161, s14, v17
	v_fma_f32 v168, v130, s14, v18
	v_fma_f32 v169, v131, s14, v19
	v_fma_f32 v162, v162, s14, v4
	v_fma_f32 v163, v163, s14, v5
	v_fma_f32 v170, v132, s14, v6
	v_fma_f32 v171, v133, s14, v7
	v_fma_f32 v164, v164, s14, v0
	v_fma_f32 v165, v165, s14, v1
	v_fma_f32 v172, v134, s14, v2
	v_fma_f32 v173, v135, s14, v3
	v_cvt_pk_bf16_f32 v128, v150, v151
	v_cvt_pk_bf16_f32 v129, v166, v167
	v_cvt_pk_bf16_f32 v130, v160, v161
	v_cvt_pk_bf16_f32 v131, v168, v169
	v_cvt_pk_bf16_f32 v132, v162, v163
	v_cvt_pk_bf16_f32 v133, v170, v171
	v_cvt_pk_bf16_f32 v134, v164, v165
	v_cvt_pk_bf16_f32 v135, v172, v173
	global_store_dwordx4 v[148:149], v[128:131], off
	global_store_dwordx4 v[148:149], v[132:135], off offset:256
	s_cbranch_execz .LBB0_1250
